# MLA prompt loop: per-tile barrier and DMA issue moved from the middle of the QK MFMAs to just before the PV MFMAs
# baseline (speedup 1.0000x reference)
.Lmy_A_entry:
	s_mov_b32 s30, 0x20000
	s_mov_b32 s31, 0
	s_mov_b32 s12, 0x1000
	s_mov_b32 s13, 0
	s_lshr_b32 s71, s24, 1
	s_lshr_b32 s79, s25, 2
	s_add_i32 s79, s79, -1
	s_barrier
	s_mov_b32 s0, 0x60000
	s_mov_b32 s1, 0
	v_lshl_add_u64 v[24:25], v[16:17], 0, s[0:1]
	s_add_u32 m0, s40, 0x9000
	s_mov_b32 s0, 0x3000
	global_load_lds_dwordx4 v[24:25], off
	v_lshl_add_u64 v[30:31], v[222:223], 0, s[0:1]
	s_add_u32 m0, s43, 0x9000
	s_nop 0
	global_load_lds_dwordx4 v[30:31], off
	s_mov_b32 s0, 0x80000
	s_mov_b32 s1, 0
	v_lshl_add_u64 v[24:25], v[16:17], 0, s[0:1]
	s_mov_b32 s0, 0x60000
	v_lshl_add_u64 v[28:29], v[224:225], 0, s[0:1]
	s_mov_b32 s0, 0x4000
	v_lshl_add_u64 v[30:31], v[222:223], 0, s[0:1]
	s_waitcnt lgkmcnt(0)
	v_mfma_f32_32x32x16_bf16 v[82:97], v[218:221], v[4:7], v[66:81]
	v_mfma_f32_32x32x16_bf16 v[98:113], v[214:217], v[4:7], v[66:81]
	v_mfma_f32_32x32x16_bf16 v[82:97], v[210:213], v[8:11], v[82:97]
	v_mfma_f32_32x32x16_bf16 v[98:113], v[206:209], v[8:11], v[98:113]
	v_mfma_f32_32x32x16_bf16 v[82:97], v[202:205], v[12:15], v[82:97]
	v_mfma_f32_32x32x16_bf16 v[98:113], v[198:201], v[12:15], v[98:113]
	v_mfma_f32_32x32x16_bf16 v[82:97], v[194:197], v[130:133], v[82:97]
	v_mfma_f32_32x32x16_bf16 v[98:113], v[190:193], v[130:133], v[98:113]
	v_mfma_f32_32x32x16_bf16 v[82:97], v[186:189], v[134:137], v[82:97]
	v_mfma_f32_32x32x16_bf16 v[98:113], v[182:185], v[134:137], v[98:113]
	v_mfma_f32_32x32x16_bf16 v[82:97], v[178:181], v[138:141], v[82:97]
	v_mfma_f32_32x32x16_bf16 v[98:113], v[174:177], v[138:141], v[98:113]
	v_add_u32_e32 v2, 0x3000, v238
	ds_read_b128 v[218:221], v2
	ds_read_b128 v[214:217], v2 offset:512
	ds_read_b128 v[210:213], v2 offset:2048
	ds_read_b128 v[206:209], v2 offset:2560
	ds_read_b128 v[202:205], v2 offset:4096
	ds_read_b128 v[198:201], v2 offset:4608
	ds_read_b128 v[194:197], v2 offset:6144
	ds_read_b128 v[190:193], v2 offset:6656
	ds_read_b128 v[186:189], v2 offset:8192
	ds_read_b128 v[182:185], v2 offset:8704
	ds_read_b128 v[178:181], v2 offset:10240
	ds_read_b128 v[174:177], v2 offset:10752
	s_nop 7
	v_max3_f32 v19, v82, v83, v84
	v_max3_f32 v26, v85, v86, v87
	v_max3_f32 v19, v19, v88, v89
	v_max3_f32 v26, v26, v90, v91
	v_max3_f32 v19, v19, v92, v93
	v_max3_f32 v26, v26, v94, v95
	v_max3_f32 v19, v19, v96, v97
	v_max3_f32 v26, v26, v98, v99
	v_max3_f32 v19, v19, v100, v101
	v_max3_f32 v26, v26, v102, v103
	v_max3_f32 v19, v19, v104, v105
	v_max3_f32 v26, v26, v106, v107
	v_max3_f32 v19, v19, v108, v109
	v_max3_f32 v26, v26, v110, v111
	v_max3_f32 v19, v19, v112, v113
	v_max_f32_e32 v19, v19, v26
	v_mov_b32_e32 v26, v19
	s_nop 1
	v_permlane32_swap_b32_e32 v19, v26
	v_max_f32_e32 v19, v19, v26
	v_max_f32_e32 v19, v19, v19
	v_mov_b32_e32 v239, v19
	v_xor_b32_e32 v66, 0x80000000, v19
	v_mov_b32_e32 v67, v66
	v_mov_b32_e32 v68, v66
	v_mov_b32_e32 v69, v66
	v_mov_b32_e32 v70, v66
	v_mov_b32_e32 v71, v66
	v_mov_b32_e32 v72, v66
	v_mov_b32_e32 v73, v66
	v_mov_b32_e32 v74, v66
	v_mov_b32_e32 v75, v66
	v_mov_b32_e32 v76, v66
	v_mov_b32_e32 v77, v66
	v_mov_b32_e32 v78, v66
	v_mov_b32_e32 v79, v66
	v_mov_b32_e32 v80, v66
	v_mov_b32_e32 v81, v66
	v_sub_f32_e32 v82, v82, v19
	v_sub_f32_e32 v83, v83, v19
	v_sub_f32_e32 v84, v84, v19
	v_sub_f32_e32 v85, v85, v19
	v_sub_f32_e32 v86, v86, v19
	v_sub_f32_e32 v87, v87, v19
	v_sub_f32_e32 v88, v88, v19
	v_sub_f32_e32 v89, v89, v19
	v_sub_f32_e32 v90, v90, v19
	v_sub_f32_e32 v91, v91, v19
	v_sub_f32_e32 v92, v92, v19
	v_sub_f32_e32 v93, v93, v19
	v_sub_f32_e32 v94, v94, v19
	v_sub_f32_e32 v95, v95, v19
	v_sub_f32_e32 v96, v96, v19
	v_sub_f32_e32 v97, v97, v19
	v_sub_f32_e32 v98, v98, v19
	v_sub_f32_e32 v99, v99, v19
	v_sub_f32_e32 v100, v100, v19
	v_sub_f32_e32 v101, v101, v19
	v_sub_f32_e32 v102, v102, v19
	v_sub_f32_e32 v103, v103, v19
	v_sub_f32_e32 v104, v104, v19
	v_sub_f32_e32 v105, v105, v19
	v_sub_f32_e32 v106, v106, v19
	v_sub_f32_e32 v107, v107, v19
	v_sub_f32_e32 v108, v108, v19
	v_sub_f32_e32 v109, v109, v19
	v_sub_f32_e32 v110, v110, v19
	v_sub_f32_e32 v111, v111, v19
	v_sub_f32_e32 v112, v112, v19
	v_sub_f32_e32 v113, v113, v19
	s_cmp_lt_i32 s79, 1
	s_cbranch_scc1 .Lmy_A_tail
	s_waitcnt lgkmcnt(0)
	v_mov_b32_e32 v2, v237
	v_mfma_f32_32x32x16_bf16 v[142:157], v[218:221], v[4:7], v[66:81]
	v_exp_f32_e32 v82, v82
	v_exp_f32_e32 v83, v83
	v_exp_f32_e32 v84, v84
	v_add_f32_e32 v27, v82, v83
	v_exp_f32_e32 v85, v85
	ds_read_b64_tr_b16 v[114:115], v2 offset:49152
	ds_read_b64_tr_b16 v[116:117], v2 offset:49664
	ds_read_b64_tr_b16 v[118:119], v2 offset:50176
	ds_read_b64_tr_b16 v[120:121], v2 offset:50688
	v_mfma_f32_32x32x16_bf16 v[158:173], v[214:217], v[4:7], v[66:81]
	v_exp_f32_e32 v86, v86
	v_add_f32_e32 v27, v27, v84
	v_exp_f32_e32 v87, v87
	v_add_f32_e32 v27, v27, v85
	v_exp_f32_e32 v88, v88
	ds_read_b64_tr_b16 v[122:123], v2 offset:51200
	ds_read_b64_tr_b16 v[124:125], v2 offset:51712
	ds_read_b64_tr_b16 v[126:127], v2 offset:52224
	ds_read_b64_tr_b16 v[128:129], v2 offset:52736
	v_mfma_f32_32x32x16_bf16 v[142:157], v[210:213], v[8:11], v[142:157]
	v_add_f32_e32 v27, v27, v86
	v_exp_f32_e32 v89, v89
	v_add_f32_e32 v27, v27, v87
	v_add_f32_e32 v27, v27, v88
	v_add_f32_e32 v27, v27, v89
	ds_read_b64_tr_b16 v[240:241], v2 offset:53248
	ds_read_b64_tr_b16 v[242:243], v2 offset:53760
	ds_read_b64_tr_b16 v[244:245], v2 offset:54272
	ds_read_b64_tr_b16 v[246:247], v2 offset:54784
	v_mfma_f32_32x32x16_bf16 v[158:173], v[206:209], v[8:11], v[158:173]
	v_cvt_pk_bf16_f32 v82, v82, v83
	v_cvt_pk_bf16_f32 v83, v84, v85
	v_cvt_pk_bf16_f32 v84, v86, v87
	v_cvt_pk_bf16_f32 v85, v88, v89
	ds_read_b64_tr_b16 v[248:249], v2 offset:55296
	ds_read_b64_tr_b16 v[250:251], v2 offset:55808
	ds_read_b64_tr_b16 v[20:21], v2 offset:56320
	ds_read_b64_tr_b16 v[22:23], v2 offset:56832
	v_mfma_f32_32x32x16_bf16 v[142:157], v[202:205], v[12:15], v[142:157]
	v_exp_f32_e32 v90, v90
	v_exp_f32_e32 v91, v91
	v_exp_f32_e32 v92, v92
	v_add_f32_e32 v27, v27, v90
	v_exp_f32_e32 v93, v93
	v_mfma_f32_32x32x16_bf16 v[158:173], v[198:201], v[12:15], v[158:173]
	v_add_f32_e32 v27, v27, v91
	v_exp_f32_e32 v94, v94
	v_add_f32_e32 v27, v27, v92
	v_exp_f32_e32 v95, v95
	v_add_f32_e32 v27, v27, v93
	v_mfma_f32_32x32x16_bf16 v[142:157], v[194:197], v[130:133], v[142:157]
	v_exp_f32_e32 v96, v96
	v_add_f32_e32 v27, v27, v94
	v_exp_f32_e32 v97, v97
	v_add_f32_e32 v27, v27, v95
	v_add_f32_e32 v27, v27, v96
	v_mfma_f32_32x32x16_bf16 v[158:173], v[190:193], v[130:133], v[158:173]
	v_add_f32_e32 v27, v27, v97
	v_cvt_pk_bf16_f32 v90, v90, v91
	v_cvt_pk_bf16_f32 v91, v92, v93
	v_cvt_pk_bf16_f32 v92, v94, v95
	v_cvt_pk_bf16_f32 v93, v96, v97
	v_mfma_f32_32x32x16_bf16 v[142:157], v[186:189], v[134:137], v[142:157]
	v_exp_f32_e32 v98, v98
	v_exp_f32_e32 v99, v99
	v_exp_f32_e32 v100, v100
	v_add_f32_e32 v27, v27, v98
	v_exp_f32_e32 v101, v101
	v_mfma_f32_32x32x16_bf16 v[158:173], v[182:185], v[134:137], v[158:173]
	v_add_f32_e32 v27, v27, v99
	v_exp_f32_e32 v102, v102
	v_add_f32_e32 v27, v27, v100
	v_exp_f32_e32 v103, v103
	v_add_f32_e32 v27, v27, v101
	v_mfma_f32_32x32x16_bf16 v[142:157], v[178:181], v[138:141], v[142:157]
	v_exp_f32_e32 v104, v104
	v_add_f32_e32 v27, v27, v102
	v_exp_f32_e32 v105, v105
	v_add_f32_e32 v27, v27, v103
	v_add_f32_e32 v27, v27, v104
	v_mfma_f32_32x32x16_bf16 v[158:173], v[174:177], v[138:141], v[158:173]
	v_add_f32_e32 v27, v27, v105
	v_cvt_pk_bf16_f32 v98, v98, v99
	v_cvt_pk_bf16_f32 v99, v100, v101
	v_cvt_pk_bf16_f32 v100, v102, v103
	v_cvt_pk_bf16_f32 v101, v104, v105
	s_waitcnt vmcnt(3)
	s_barrier
	s_waitcnt lgkmcnt(0)
	v_add_u32_e32 v2, 0x6000, v238
	v_mfma_f32_32x32x16_bf16 v[34:49], v[82:85], v[114:117], v[34:49]
	s_add_u32 m0, s57, 0x6000
	v_exp_f32_e32 v106, v106
	v_exp_f32_e32 v107, v107
	global_load_lds_dwordx4 v[28:29], off
	v_lshl_add_u64 v[28:29], v[28:29], 0, s[30:31]
	v_exp_f32_e32 v108, v108
	v_add_f32_e32 v27, v27, v106
	v_exp_f32_e32 v109, v109
	ds_read_b128 v[218:221], v2
	ds_read_b128 v[214:217], v2 offset:512
	ds_read_b128 v[210:213], v2 offset:2048
	v_mfma_f32_32x32x16_bf16 v[50:65], v[82:85], v[240:243], v[50:65]
	s_add_u32 m0, s40, 0x0
	v_add_f32_e32 v27, v27, v107
	v_exp_f32_e32 v110, v110
	global_load_lds_dwordx4 v[24:25], off
	v_lshl_add_u64 v[24:25], v[24:25], 0, s[30:31]
	v_add_f32_e32 v27, v27, v108
	v_exp_f32_e32 v111, v111
	v_add_f32_e32 v27, v27, v109
	ds_read_b128 v[206:209], v2 offset:2560
	ds_read_b128 v[202:205], v2 offset:4096
	ds_read_b128 v[198:201], v2 offset:4608
	v_mfma_f32_32x32x16_bf16 v[34:49], v[90:93], v[118:121], v[34:49]
	s_add_u32 m0, s43, 0x0
	v_exp_f32_e32 v112, v112
	v_add_f32_e32 v27, v27, v110
	global_load_lds_dwordx4 v[30:31], off
	v_lshl_add_u64 v[30:31], v[30:31], 0, s[12:13]
	v_exp_f32_e32 v113, v113
	v_add_f32_e32 v27, v27, v111
	v_add_f32_e32 v27, v27, v112
	ds_read_b128 v[194:197], v2 offset:6144
	ds_read_b128 v[190:193], v2 offset:6656
	ds_read_b128 v[186:189], v2 offset:8192
	v_mfma_f32_32x32x16_bf16 v[50:65], v[90:93], v[244:247], v[50:65]
	s_add_u32 m0, s40, 0x3000
	v_add_f32_e32 v27, v27, v113
	v_cvt_pk_bf16_f32 v106, v106, v107
	global_load_lds_dwordx4 v[24:25], off
	v_lshl_add_u64 v[24:25], v[24:25], 0, s[30:31]
	v_cvt_pk_bf16_f32 v107, v108, v109
	v_cvt_pk_bf16_f32 v108, v110, v111
	v_cvt_pk_bf16_f32 v109, v112, v113
	v_add_f32_e32 v236, v236, v27
	ds_read_b128 v[182:185], v2 offset:8704
	ds_read_b128 v[178:181], v2 offset:10240
	ds_read_b128 v[174:177], v2 offset:10752
	v_mfma_f32_32x32x16_bf16 v[34:49], v[98:101], v[122:125], v[34:49]
	s_add_u32 m0, s43, 0x3000
	v_max3_f32 v19, v142, v143, v144
	v_max3_f32 v26, v145, v146, v147
	global_load_lds_dwordx4 v[30:31], off
	v_lshl_add_u64 v[30:31], v[30:31], 0, s[12:13]
	v_max3_f32 v19, v19, v148, v149
	v_max3_f32 v26, v26, v150, v151
	v_mfma_f32_32x32x16_bf16 v[50:65], v[98:101], v[248:251], v[50:65]
	v_max3_f32 v19, v19, v152, v153
	v_max3_f32 v26, v26, v154, v155
	v_max3_f32 v19, v19, v156, v157
	v_max3_f32 v26, v26, v158, v159
	v_mfma_f32_32x32x16_bf16 v[34:49], v[106:109], v[126:129], v[34:49]
	v_max3_f32 v19, v19, v160, v161
	v_max3_f32 v26, v26, v162, v163
	v_max3_f32 v19, v19, v164, v165
	v_max3_f32 v26, v26, v166, v167
	v_mfma_f32_32x32x16_bf16 v[50:65], v[106:109], v[20:23], v[50:65]
	v_max3_f32 v19, v19, v168, v169
	v_max3_f32 v26, v26, v170, v171
	v_max3_f32 v19, v19, v172, v173
	v_max_f32_e32 v19, v19, v26
	v_cmp_lt_f32_e32 vcc, s41, v19
	s_cbranch_vccz .Lmy_nors_1
	s_nop 15
	s_nop 15
	v_mov_b32_e32 v26, v19
	s_nop 1
	v_permlane32_swap_b32_e32 v19, v26
	v_max_f32_e32 v19, v19, v26
	v_max_f32_e32 v19, v19, v19
	v_max_f32_e32 v90, 0, v19
	v_exp_f32_e64 v91, -v90
	v_add_f32_e32 v239, v239, v90
	v_xor_b32_e32 v66, 0x80000000, v239
	v_mov_b32_e32 v67, v66
	v_mov_b32_e32 v68, v66
	v_mov_b32_e32 v69, v66
	v_mov_b32_e32 v70, v66
	v_mov_b32_e32 v71, v66
	v_mov_b32_e32 v72, v66
	v_mov_b32_e32 v73, v66
	v_mov_b32_e32 v74, v66
	v_mov_b32_e32 v75, v66
	v_mov_b32_e32 v76, v66
	v_mov_b32_e32 v77, v66
	v_mov_b32_e32 v78, v66
	v_mov_b32_e32 v79, v66
	v_mov_b32_e32 v80, v66
	v_mov_b32_e32 v81, v66
	v_sub_f32_e32 v142, v142, v90
	v_sub_f32_e32 v143, v143, v90
	v_sub_f32_e32 v144, v144, v90
	v_sub_f32_e32 v145, v145, v90
	v_sub_f32_e32 v146, v146, v90
	v_sub_f32_e32 v147, v147, v90
	v_sub_f32_e32 v148, v148, v90
	v_sub_f32_e32 v149, v149, v90
	v_sub_f32_e32 v150, v150, v90
	v_sub_f32_e32 v151, v151, v90
	v_sub_f32_e32 v152, v152, v90
	v_sub_f32_e32 v153, v153, v90
	v_sub_f32_e32 v154, v154, v90
	v_sub_f32_e32 v155, v155, v90
	v_sub_f32_e32 v156, v156, v90
	v_sub_f32_e32 v157, v157, v90
	v_sub_f32_e32 v158, v158, v90
	v_sub_f32_e32 v159, v159, v90
	v_sub_f32_e32 v160, v160, v90
	v_sub_f32_e32 v161, v161, v90
	v_sub_f32_e32 v162, v162, v90
	v_sub_f32_e32 v163, v163, v90
	v_sub_f32_e32 v164, v164, v90
	v_sub_f32_e32 v165, v165, v90
	v_sub_f32_e32 v166, v166, v90
	v_sub_f32_e32 v167, v167, v90
	v_sub_f32_e32 v168, v168, v90
	v_sub_f32_e32 v169, v169, v90
	v_sub_f32_e32 v170, v170, v90
	v_sub_f32_e32 v171, v171, v90
	v_sub_f32_e32 v172, v172, v90
	v_sub_f32_e32 v173, v173, v90
	v_mul_f32_e32 v236, v236, v91
	s_mov_b64 s[96:97], exec
	s_and_b64 exec, exec, s[8:9]
	ds_write_b32 v235, v91
	s_mov_b64 exec, s[96:97]
	v_lshl_add_u32 v2, v228, 4, s47
	ds_read_b128 v[94:97], v2 offset:0
	s_waitcnt lgkmcnt(0)
	v_mul_f32_e32 v34, v34, v94
	v_mul_f32_e32 v50, v50, v94
	v_mul_f32_e32 v35, v35, v95
	v_mul_f32_e32 v51, v51, v95
	v_mul_f32_e32 v36, v36, v96
	v_mul_f32_e32 v52, v52, v96
	v_mul_f32_e32 v37, v37, v97
	v_mul_f32_e32 v53, v53, v97
	ds_read_b128 v[94:97], v2 offset:32
	s_waitcnt lgkmcnt(0)
	v_mul_f32_e32 v38, v38, v94
	v_mul_f32_e32 v54, v54, v94
	v_mul_f32_e32 v39, v39, v95
	v_mul_f32_e32 v55, v55, v95
	v_mul_f32_e32 v40, v40, v96
	v_mul_f32_e32 v56, v56, v96
	v_mul_f32_e32 v41, v41, v97
	v_mul_f32_e32 v57, v57, v97
	ds_read_b128 v[94:97], v2 offset:64
	s_waitcnt lgkmcnt(0)
	v_mul_f32_e32 v42, v42, v94
	v_mul_f32_e32 v58, v58, v94
	v_mul_f32_e32 v43, v43, v95
	v_mul_f32_e32 v59, v59, v95
	v_mul_f32_e32 v44, v44, v96
	v_mul_f32_e32 v60, v60, v96
	v_mul_f32_e32 v45, v45, v97
	v_mul_f32_e32 v61, v61, v97
	ds_read_b128 v[94:97], v2 offset:96
	s_waitcnt lgkmcnt(0)
	v_mul_f32_e32 v46, v46, v94
	v_mul_f32_e32 v62, v62, v94
	v_mul_f32_e32 v47, v47, v95
	v_mul_f32_e32 v63, v63, v95
	v_mul_f32_e32 v48, v48, v96
	v_mul_f32_e32 v64, v64, v96
	v_mul_f32_e32 v49, v49, v97
	v_mul_f32_e32 v65, v65, v97
.Lmy_nors_1:
	s_waitcnt lgkmcnt(0)
	v_add_u32_e32 v2, 0x2000, v237
	v_mfma_f32_32x32x16_bf16 v[82:97], v[218:221], v[4:7], v[66:81]
	v_exp_f32_e32 v142, v142
	v_exp_f32_e32 v143, v143
	v_exp_f32_e32 v144, v144
	v_add_f32_e32 v27, v142, v143
	v_exp_f32_e32 v145, v145
	ds_read_b64_tr_b16 v[114:115], v2 offset:49152
	ds_read_b64_tr_b16 v[116:117], v2 offset:49664
	ds_read_b64_tr_b16 v[118:119], v2 offset:50176
	ds_read_b64_tr_b16 v[120:121], v2 offset:50688
	v_mfma_f32_32x32x16_bf16 v[98:113], v[214:217], v[4:7], v[66:81]
	v_exp_f32_e32 v146, v146
	v_add_f32_e32 v27, v27, v144
	v_exp_f32_e32 v147, v147
	v_add_f32_e32 v27, v27, v145
	v_exp_f32_e32 v148, v148
	ds_read_b64_tr_b16 v[122:123], v2 offset:51200
	ds_read_b64_tr_b16 v[124:125], v2 offset:51712
	ds_read_b64_tr_b16 v[126:127], v2 offset:52224
	ds_read_b64_tr_b16 v[128:129], v2 offset:52736
	v_mfma_f32_32x32x16_bf16 v[82:97], v[210:213], v[8:11], v[82:97]
	v_add_f32_e32 v27, v27, v146
	v_exp_f32_e32 v149, v149
	v_add_f32_e32 v27, v27, v147
	v_add_f32_e32 v27, v27, v148
	v_add_f32_e32 v27, v27, v149
	ds_read_b64_tr_b16 v[240:241], v2 offset:53248
	ds_read_b64_tr_b16 v[242:243], v2 offset:53760
	ds_read_b64_tr_b16 v[244:245], v2 offset:54272
	ds_read_b64_tr_b16 v[246:247], v2 offset:54784
	v_mfma_f32_32x32x16_bf16 v[98:113], v[206:209], v[8:11], v[98:113]
	v_cvt_pk_bf16_f32 v142, v142, v143
	v_cvt_pk_bf16_f32 v143, v144, v145
	v_cvt_pk_bf16_f32 v144, v146, v147
	v_cvt_pk_bf16_f32 v145, v148, v149
	ds_read_b64_tr_b16 v[248:249], v2 offset:55296
	ds_read_b64_tr_b16 v[250:251], v2 offset:55808
	ds_read_b64_tr_b16 v[20:21], v2 offset:56320
	ds_read_b64_tr_b16 v[22:23], v2 offset:56832
	v_mfma_f32_32x32x16_bf16 v[82:97], v[202:205], v[12:15], v[82:97]
	v_exp_f32_e32 v150, v150
	v_exp_f32_e32 v151, v151
	v_exp_f32_e32 v152, v152
	v_add_f32_e32 v27, v27, v150
	v_exp_f32_e32 v153, v153
	v_mfma_f32_32x32x16_bf16 v[98:113], v[198:201], v[12:15], v[98:113]
	v_add_f32_e32 v27, v27, v151
	v_exp_f32_e32 v154, v154
	v_add_f32_e32 v27, v27, v152
	v_exp_f32_e32 v155, v155
	v_add_f32_e32 v27, v27, v153
	v_mfma_f32_32x32x16_bf16 v[82:97], v[194:197], v[130:133], v[82:97]
	v_exp_f32_e32 v156, v156
	v_add_f32_e32 v27, v27, v154
	v_exp_f32_e32 v157, v157
	v_add_f32_e32 v27, v27, v155
	v_add_f32_e32 v27, v27, v156
	v_mfma_f32_32x32x16_bf16 v[98:113], v[190:193], v[130:133], v[98:113]
	v_add_f32_e32 v27, v27, v157
	v_cvt_pk_bf16_f32 v150, v150, v151
	v_cvt_pk_bf16_f32 v151, v152, v153
	v_cvt_pk_bf16_f32 v152, v154, v155
	v_cvt_pk_bf16_f32 v153, v156, v157
	v_mfma_f32_32x32x16_bf16 v[82:97], v[186:189], v[134:137], v[82:97]
	v_exp_f32_e32 v158, v158
	v_exp_f32_e32 v159, v159
	v_exp_f32_e32 v160, v160
	v_add_f32_e32 v27, v27, v158
	v_exp_f32_e32 v161, v161
	v_mfma_f32_32x32x16_bf16 v[98:113], v[182:185], v[134:137], v[98:113]
	v_add_f32_e32 v27, v27, v159
	v_exp_f32_e32 v162, v162
	v_add_f32_e32 v27, v27, v160
	v_exp_f32_e32 v163, v163
	v_add_f32_e32 v27, v27, v161
	v_mfma_f32_32x32x16_bf16 v[82:97], v[178:181], v[138:141], v[82:97]
	v_exp_f32_e32 v164, v164
	v_add_f32_e32 v27, v27, v162
	v_exp_f32_e32 v165, v165
	v_add_f32_e32 v27, v27, v163
	v_add_f32_e32 v27, v27, v164
	v_mfma_f32_32x32x16_bf16 v[98:113], v[174:177], v[138:141], v[98:113]
	v_add_f32_e32 v27, v27, v165
	v_cvt_pk_bf16_f32 v158, v158, v159
	v_cvt_pk_bf16_f32 v159, v160, v161
	v_cvt_pk_bf16_f32 v160, v162, v163
	v_cvt_pk_bf16_f32 v161, v164, v165
	s_waitcnt vmcnt(5)
	s_barrier
	s_waitcnt lgkmcnt(0)
	v_add_u32_e32 v2, 0x9000, v238
	v_mfma_f32_32x32x16_bf16 v[34:49], v[142:145], v[114:117], v[34:49]
	s_add_u32 m0, s57, 0x0
	v_exp_f32_e32 v166, v166
	v_exp_f32_e32 v167, v167
	global_load_lds_dwordx4 v[28:29], off
	v_lshl_add_u64 v[28:29], v[28:29], 0, s[30:31]
	v_exp_f32_e32 v168, v168
	v_add_f32_e32 v27, v27, v166
	v_exp_f32_e32 v169, v169
	ds_read_b128 v[218:221], v2
	ds_read_b128 v[214:217], v2 offset:512
	ds_read_b128 v[210:213], v2 offset:2048
	v_mfma_f32_32x32x16_bf16 v[50:65], v[142:145], v[240:243], v[50:65]
	s_add_u32 m0, s40, 0x6000
	v_add_f32_e32 v27, v27, v167
	v_exp_f32_e32 v170, v170
	global_load_lds_dwordx4 v[24:25], off
	v_lshl_add_u64 v[24:25], v[24:25], 0, s[30:31]
	v_add_f32_e32 v27, v27, v168
	v_exp_f32_e32 v171, v171
	v_add_f32_e32 v27, v27, v169
	ds_read_b128 v[206:209], v2 offset:2560
	ds_read_b128 v[202:205], v2 offset:4096
	ds_read_b128 v[198:201], v2 offset:4608
	v_mfma_f32_32x32x16_bf16 v[34:49], v[150:153], v[118:121], v[34:49]
	s_add_u32 m0, s43, 0x6000
	v_exp_f32_e32 v172, v172
	v_add_f32_e32 v27, v27, v170
	global_load_lds_dwordx4 v[30:31], off
	v_lshl_add_u64 v[30:31], v[30:31], 0, s[12:13]
	v_exp_f32_e32 v173, v173
	v_add_f32_e32 v27, v27, v171
	v_add_f32_e32 v27, v27, v172
	ds_read_b128 v[194:197], v2 offset:6144
	ds_read_b128 v[190:193], v2 offset:6656
	ds_read_b128 v[186:189], v2 offset:8192
	v_mfma_f32_32x32x16_bf16 v[50:65], v[150:153], v[244:247], v[50:65]
	v_add_f32_e32 v27, v27, v173
	v_cvt_pk_bf16_f32 v166, v166, v167
	v_cvt_pk_bf16_f32 v167, v168, v169
	v_cvt_pk_bf16_f32 v168, v170, v171
	v_cvt_pk_bf16_f32 v169, v172, v173
	v_add_f32_e32 v236, v236, v27
	ds_read_b128 v[182:185], v2 offset:8704
	ds_read_b128 v[178:181], v2 offset:10240
	ds_read_b128 v[174:177], v2 offset:10752
	v_mfma_f32_32x32x16_bf16 v[34:49], v[158:161], v[122:125], v[34:49]
	v_max3_f32 v19, v82, v83, v84
	v_max3_f32 v26, v85, v86, v87
	v_max3_f32 v19, v19, v88, v89
	v_max3_f32 v26, v26, v90, v91
	v_mfma_f32_32x32x16_bf16 v[50:65], v[158:161], v[248:251], v[50:65]
	v_max3_f32 v19, v19, v92, v93
	v_max3_f32 v26, v26, v94, v95
	v_max3_f32 v19, v19, v96, v97
	v_max3_f32 v26, v26, v98, v99
	v_mfma_f32_32x32x16_bf16 v[34:49], v[166:169], v[126:129], v[34:49]
	v_max3_f32 v19, v19, v100, v101
	v_max3_f32 v26, v26, v102, v103
	v_max3_f32 v19, v19, v104, v105
	v_max3_f32 v26, v26, v106, v107
	v_mfma_f32_32x32x16_bf16 v[50:65], v[166:169], v[20:23], v[50:65]
	v_max3_f32 v19, v19, v108, v109
	v_max3_f32 v26, v26, v110, v111
	v_max3_f32 v19, v19, v112, v113
	v_max_f32_e32 v19, v19, v26
	v_cmp_lt_f32_e32 vcc, s41, v19
	s_cbranch_vccz .Lmy_nors_2
	s_nop 15
	s_nop 15
	v_mov_b32_e32 v26, v19
	s_nop 1
	v_permlane32_swap_b32_e32 v19, v26
	v_max_f32_e32 v19, v19, v26
	v_max_f32_e32 v19, v19, v19
	v_max_f32_e32 v150, 0, v19
	v_exp_f32_e64 v151, -v150
	v_add_f32_e32 v239, v239, v150
	v_xor_b32_e32 v66, 0x80000000, v239
	v_mov_b32_e32 v67, v66
	v_mov_b32_e32 v68, v66
	v_mov_b32_e32 v69, v66
	v_mov_b32_e32 v70, v66
	v_mov_b32_e32 v71, v66
	v_mov_b32_e32 v72, v66
	v_mov_b32_e32 v73, v66
	v_mov_b32_e32 v74, v66
	v_mov_b32_e32 v75, v66
	v_mov_b32_e32 v76, v66
	v_mov_b32_e32 v77, v66
	v_mov_b32_e32 v78, v66
	v_mov_b32_e32 v79, v66
	v_mov_b32_e32 v80, v66
	v_mov_b32_e32 v81, v66
	v_sub_f32_e32 v82, v82, v150
	v_sub_f32_e32 v83, v83, v150
	v_sub_f32_e32 v84, v84, v150
	v_sub_f32_e32 v85, v85, v150
	v_sub_f32_e32 v86, v86, v150
	v_sub_f32_e32 v87, v87, v150
	v_sub_f32_e32 v88, v88, v150
	v_sub_f32_e32 v89, v89, v150
	v_sub_f32_e32 v90, v90, v150
	v_sub_f32_e32 v91, v91, v150
	v_sub_f32_e32 v92, v92, v150
	v_sub_f32_e32 v93, v93, v150
	v_sub_f32_e32 v94, v94, v150
	v_sub_f32_e32 v95, v95, v150
	v_sub_f32_e32 v96, v96, v150
	v_sub_f32_e32 v97, v97, v150
	v_sub_f32_e32 v98, v98, v150
	v_sub_f32_e32 v99, v99, v150
	v_sub_f32_e32 v100, v100, v150
	v_sub_f32_e32 v101, v101, v150
	v_sub_f32_e32 v102, v102, v150
	v_sub_f32_e32 v103, v103, v150
	v_sub_f32_e32 v104, v104, v150
	v_sub_f32_e32 v105, v105, v150
	v_sub_f32_e32 v106, v106, v150
	v_sub_f32_e32 v107, v107, v150
	v_sub_f32_e32 v108, v108, v150
	v_sub_f32_e32 v109, v109, v150
	v_sub_f32_e32 v110, v110, v150
	v_sub_f32_e32 v111, v111, v150
	v_sub_f32_e32 v112, v112, v150
	v_sub_f32_e32 v113, v113, v150
	v_mul_f32_e32 v236, v236, v151
	s_mov_b64 s[96:97], exec
	s_and_b64 exec, exec, s[8:9]
	ds_write_b32 v235, v151
	s_mov_b64 exec, s[96:97]
	v_lshl_add_u32 v2, v228, 4, s47
	ds_read_b128 v[154:157], v2 offset:0
	s_waitcnt lgkmcnt(0)
	v_mul_f32_e32 v34, v34, v154
	v_mul_f32_e32 v50, v50, v154
	v_mul_f32_e32 v35, v35, v155
	v_mul_f32_e32 v51, v51, v155
	v_mul_f32_e32 v36, v36, v156
	v_mul_f32_e32 v52, v52, v156
	v_mul_f32_e32 v37, v37, v157
	v_mul_f32_e32 v53, v53, v157
	ds_read_b128 v[154:157], v2 offset:32
	s_waitcnt lgkmcnt(0)
	v_mul_f32_e32 v38, v38, v154
	v_mul_f32_e32 v54, v54, v154
	v_mul_f32_e32 v39, v39, v155
	v_mul_f32_e32 v55, v55, v155
	v_mul_f32_e32 v40, v40, v156
	v_mul_f32_e32 v56, v56, v156
	v_mul_f32_e32 v41, v41, v157
	v_mul_f32_e32 v57, v57, v157
	ds_read_b128 v[154:157], v2 offset:64
	s_waitcnt lgkmcnt(0)
	v_mul_f32_e32 v42, v42, v154
	v_mul_f32_e32 v58, v58, v154
	v_mul_f32_e32 v43, v43, v155
	v_mul_f32_e32 v59, v59, v155
	v_mul_f32_e32 v44, v44, v156
	v_mul_f32_e32 v60, v60, v156
	v_mul_f32_e32 v45, v45, v157
	v_mul_f32_e32 v61, v61, v157
	ds_read_b128 v[154:157], v2 offset:96
	s_waitcnt lgkmcnt(0)
	v_mul_f32_e32 v46, v46, v154
	v_mul_f32_e32 v62, v62, v154
	v_mul_f32_e32 v47, v47, v155
	v_mul_f32_e32 v63, v63, v155
	v_mul_f32_e32 v48, v48, v156
	v_mul_f32_e32 v64, v64, v156
	v_mul_f32_e32 v49, v49, v157
	v_mul_f32_e32 v65, v65, v157
.Lmy_nors_2:
	s_waitcnt lgkmcnt(0)
	v_add_u32_e32 v2, 0x4000, v237
	v_mfma_f32_32x32x16_bf16 v[142:157], v[218:221], v[4:7], v[66:81]
	v_exp_f32_e32 v82, v82
	v_exp_f32_e32 v83, v83
	v_exp_f32_e32 v84, v84
	v_add_f32_e32 v27, v82, v83
	v_exp_f32_e32 v85, v85
	ds_read_b64_tr_b16 v[114:115], v2 offset:49152
	ds_read_b64_tr_b16 v[116:117], v2 offset:49664
	ds_read_b64_tr_b16 v[118:119], v2 offset:50176
	ds_read_b64_tr_b16 v[120:121], v2 offset:50688
	v_mfma_f32_32x32x16_bf16 v[158:173], v[214:217], v[4:7], v[66:81]
	v_exp_f32_e32 v86, v86
	v_add_f32_e32 v27, v27, v84
	v_exp_f32_e32 v87, v87
	v_add_f32_e32 v27, v27, v85
	v_exp_f32_e32 v88, v88
	ds_read_b64_tr_b16 v[122:123], v2 offset:51200
	ds_read_b64_tr_b16 v[124:125], v2 offset:51712
	ds_read_b64_tr_b16 v[126:127], v2 offset:52224
	ds_read_b64_tr_b16 v[128:129], v2 offset:52736
	v_mfma_f32_32x32x16_bf16 v[142:157], v[210:213], v[8:11], v[142:157]
	v_add_f32_e32 v27, v27, v86
	v_exp_f32_e32 v89, v89
	v_add_f32_e32 v27, v27, v87
	v_add_f32_e32 v27, v27, v88
	v_add_f32_e32 v27, v27, v89
	ds_read_b64_tr_b16 v[240:241], v2 offset:53248
	ds_read_b64_tr_b16 v[242:243], v2 offset:53760
	ds_read_b64_tr_b16 v[244:245], v2 offset:54272
	ds_read_b64_tr_b16 v[246:247], v2 offset:54784
	v_mfma_f32_32x32x16_bf16 v[158:173], v[206:209], v[8:11], v[158:173]
	v_cvt_pk_bf16_f32 v82, v82, v83
	v_cvt_pk_bf16_f32 v83, v84, v85
	v_cvt_pk_bf16_f32 v84, v86, v87
	v_cvt_pk_bf16_f32 v85, v88, v89
	ds_read_b64_tr_b16 v[248:249], v2 offset:55296
	ds_read_b64_tr_b16 v[250:251], v2 offset:55808
	ds_read_b64_tr_b16 v[20:21], v2 offset:56320
	ds_read_b64_tr_b16 v[22:23], v2 offset:56832
	v_mfma_f32_32x32x16_bf16 v[142:157], v[202:205], v[12:15], v[142:157]
	v_exp_f32_e32 v90, v90
	v_exp_f32_e32 v91, v91
	v_exp_f32_e32 v92, v92
	v_add_f32_e32 v27, v27, v90
	v_exp_f32_e32 v93, v93
	v_mfma_f32_32x32x16_bf16 v[158:173], v[198:201], v[12:15], v[158:173]
	v_add_f32_e32 v27, v27, v91
	v_exp_f32_e32 v94, v94
	v_add_f32_e32 v27, v27, v92
	v_exp_f32_e32 v95, v95
	v_add_f32_e32 v27, v27, v93
	v_mfma_f32_32x32x16_bf16 v[142:157], v[194:197], v[130:133], v[142:157]
	v_exp_f32_e32 v96, v96
	v_add_f32_e32 v27, v27, v94
	v_exp_f32_e32 v97, v97
	v_add_f32_e32 v27, v27, v95
	v_add_f32_e32 v27, v27, v96
	v_mfma_f32_32x32x16_bf16 v[158:173], v[190:193], v[130:133], v[158:173]
	v_add_f32_e32 v27, v27, v97
	v_cvt_pk_bf16_f32 v90, v90, v91
	v_cvt_pk_bf16_f32 v91, v92, v93
	v_cvt_pk_bf16_f32 v92, v94, v95
	v_cvt_pk_bf16_f32 v93, v96, v97
	v_mfma_f32_32x32x16_bf16 v[142:157], v[186:189], v[134:137], v[142:157]
	v_exp_f32_e32 v98, v98
	v_exp_f32_e32 v99, v99
	v_exp_f32_e32 v100, v100
	v_add_f32_e32 v27, v27, v98
	v_exp_f32_e32 v101, v101
	v_mfma_f32_32x32x16_bf16 v[158:173], v[182:185], v[134:137], v[158:173]
	v_add_f32_e32 v27, v27, v99
	v_exp_f32_e32 v102, v102
	v_add_f32_e32 v27, v27, v100
	v_exp_f32_e32 v103, v103
	v_add_f32_e32 v27, v27, v101
	v_mfma_f32_32x32x16_bf16 v[142:157], v[178:181], v[138:141], v[142:157]
	v_exp_f32_e32 v104, v104
	v_add_f32_e32 v27, v27, v102
	v_exp_f32_e32 v105, v105
	v_add_f32_e32 v27, v27, v103
	v_add_f32_e32 v27, v27, v104
	v_mfma_f32_32x32x16_bf16 v[158:173], v[174:177], v[138:141], v[158:173]
	v_add_f32_e32 v27, v27, v105
	v_cvt_pk_bf16_f32 v98, v98, v99
	v_cvt_pk_bf16_f32 v99, v100, v101
	v_cvt_pk_bf16_f32 v100, v102, v103
	v_cvt_pk_bf16_f32 v101, v104, v105
	s_waitcnt vmcnt(5)
	s_barrier
	s_waitcnt lgkmcnt(0)
	v_mov_b32_e32 v2, v238
	v_mfma_f32_32x32x16_bf16 v[34:49], v[82:85], v[114:117], v[34:49]
	s_add_u32 m0, s57, 0x2000
	v_exp_f32_e32 v106, v106
	v_exp_f32_e32 v107, v107
	global_load_lds_dwordx4 v[28:29], off
	v_lshl_add_u64 v[28:29], v[28:29], 0, s[30:31]
	v_exp_f32_e32 v108, v108
	v_add_f32_e32 v27, v27, v106
	v_exp_f32_e32 v109, v109
	ds_read_b128 v[218:221], v2
	ds_read_b128 v[214:217], v2 offset:512
	ds_read_b128 v[210:213], v2 offset:2048
	v_mfma_f32_32x32x16_bf16 v[50:65], v[82:85], v[240:243], v[50:65]
	s_add_u32 m0, s40, 0x9000
	v_add_f32_e32 v27, v27, v107
	v_exp_f32_e32 v110, v110
	global_load_lds_dwordx4 v[24:25], off
	v_lshl_add_u64 v[24:25], v[24:25], 0, s[30:31]
	v_add_f32_e32 v27, v27, v108
	v_exp_f32_e32 v111, v111
	v_add_f32_e32 v27, v27, v109
	ds_read_b128 v[206:209], v2 offset:2560
	ds_read_b128 v[202:205], v2 offset:4096
	ds_read_b128 v[198:201], v2 offset:4608
	v_mfma_f32_32x32x16_bf16 v[34:49], v[90:93], v[118:121], v[34:49]
	s_add_u32 m0, s43, 0x9000
	v_exp_f32_e32 v112, v112
	v_add_f32_e32 v27, v27, v110
	global_load_lds_dwordx4 v[30:31], off
	v_lshl_add_u64 v[30:31], v[30:31], 0, s[12:13]
	v_exp_f32_e32 v113, v113
	v_add_f32_e32 v27, v27, v111
	v_add_f32_e32 v27, v27, v112
	ds_read_b128 v[194:197], v2 offset:6144
	ds_read_b128 v[190:193], v2 offset:6656
	ds_read_b128 v[186:189], v2 offset:8192
	v_mfma_f32_32x32x16_bf16 v[50:65], v[90:93], v[244:247], v[50:65]
	v_add_f32_e32 v27, v27, v113
	v_cvt_pk_bf16_f32 v106, v106, v107
	v_cvt_pk_bf16_f32 v107, v108, v109
	v_cvt_pk_bf16_f32 v108, v110, v111
	v_cvt_pk_bf16_f32 v109, v112, v113
	v_add_f32_e32 v236, v236, v27
	ds_read_b128 v[182:185], v2 offset:8704
	ds_read_b128 v[178:181], v2 offset:10240
	ds_read_b128 v[174:177], v2 offset:10752
	v_mfma_f32_32x32x16_bf16 v[34:49], v[98:101], v[122:125], v[34:49]
	v_max3_f32 v19, v142, v143, v144
	v_max3_f32 v26, v145, v146, v147
	v_max3_f32 v19, v19, v148, v149
	v_max3_f32 v26, v26, v150, v151
	v_mfma_f32_32x32x16_bf16 v[50:65], v[98:101], v[248:251], v[50:65]
	v_max3_f32 v19, v19, v152, v153
	v_max3_f32 v26, v26, v154, v155
	v_max3_f32 v19, v19, v156, v157
	v_max3_f32 v26, v26, v158, v159
	v_mfma_f32_32x32x16_bf16 v[34:49], v[106:109], v[126:129], v[34:49]
	v_max3_f32 v19, v19, v160, v161
	v_max3_f32 v26, v26, v162, v163
	v_max3_f32 v19, v19, v164, v165
	v_max3_f32 v26, v26, v166, v167
	v_mfma_f32_32x32x16_bf16 v[50:65], v[106:109], v[20:23], v[50:65]
	v_max3_f32 v19, v19, v168, v169
	v_max3_f32 v26, v26, v170, v171
	v_max3_f32 v19, v19, v172, v173
	v_max_f32_e32 v19, v19, v26
	v_cmp_lt_f32_e32 vcc, s41, v19
	s_cbranch_vccz .Lmy_nors_3
	s_nop 15
	s_nop 15
	v_mov_b32_e32 v26, v19
	s_nop 1
	v_permlane32_swap_b32_e32 v19, v26
	v_max_f32_e32 v19, v19, v26
	v_max_f32_e32 v19, v19, v19
	v_max_f32_e32 v90, 0, v19
	v_exp_f32_e64 v91, -v90
	v_add_f32_e32 v239, v239, v90
	v_xor_b32_e32 v66, 0x80000000, v239
	v_mov_b32_e32 v67, v66
	v_mov_b32_e32 v68, v66
	v_mov_b32_e32 v69, v66
	v_mov_b32_e32 v70, v66
	v_mov_b32_e32 v71, v66
	v_mov_b32_e32 v72, v66
	v_mov_b32_e32 v73, v66
	v_mov_b32_e32 v74, v66
	v_mov_b32_e32 v75, v66
	v_mov_b32_e32 v76, v66
	v_mov_b32_e32 v77, v66
	v_mov_b32_e32 v78, v66
	v_mov_b32_e32 v79, v66
	v_mov_b32_e32 v80, v66
	v_mov_b32_e32 v81, v66
	v_sub_f32_e32 v142, v142, v90
	v_sub_f32_e32 v143, v143, v90
	v_sub_f32_e32 v144, v144, v90
	v_sub_f32_e32 v145, v145, v90
	v_sub_f32_e32 v146, v146, v90
	v_sub_f32_e32 v147, v147, v90
	v_sub_f32_e32 v148, v148, v90
	v_sub_f32_e32 v149, v149, v90
	v_sub_f32_e32 v150, v150, v90
	v_sub_f32_e32 v151, v151, v90
	v_sub_f32_e32 v152, v152, v90
	v_sub_f32_e32 v153, v153, v90
	v_sub_f32_e32 v154, v154, v90
	v_sub_f32_e32 v155, v155, v90
	v_sub_f32_e32 v156, v156, v90
	v_sub_f32_e32 v157, v157, v90
	v_sub_f32_e32 v158, v158, v90
	v_sub_f32_e32 v159, v159, v90
	v_sub_f32_e32 v160, v160, v90
	v_sub_f32_e32 v161, v161, v90
	v_sub_f32_e32 v162, v162, v90
	v_sub_f32_e32 v163, v163, v90
	v_sub_f32_e32 v164, v164, v90
	v_sub_f32_e32 v165, v165, v90
	v_sub_f32_e32 v166, v166, v90
	v_sub_f32_e32 v167, v167, v90
	v_sub_f32_e32 v168, v168, v90
	v_sub_f32_e32 v169, v169, v90
	v_sub_f32_e32 v170, v170, v90
	v_sub_f32_e32 v171, v171, v90
	v_sub_f32_e32 v172, v172, v90
	v_sub_f32_e32 v173, v173, v90
	v_mul_f32_e32 v236, v236, v91
	s_mov_b64 s[96:97], exec
	s_and_b64 exec, exec, s[8:9]
	ds_write_b32 v235, v91
	s_mov_b64 exec, s[96:97]
	v_lshl_add_u32 v2, v228, 4, s47
	ds_read_b128 v[94:97], v2 offset:0
	s_waitcnt lgkmcnt(0)
	v_mul_f32_e32 v34, v34, v94
	v_mul_f32_e32 v50, v50, v94
	v_mul_f32_e32 v35, v35, v95
	v_mul_f32_e32 v51, v51, v95
	v_mul_f32_e32 v36, v36, v96
	v_mul_f32_e32 v52, v52, v96
	v_mul_f32_e32 v37, v37, v97
	v_mul_f32_e32 v53, v53, v97
	ds_read_b128 v[94:97], v2 offset:32
	s_waitcnt lgkmcnt(0)
	v_mul_f32_e32 v38, v38, v94
	v_mul_f32_e32 v54, v54, v94
	v_mul_f32_e32 v39, v39, v95
	v_mul_f32_e32 v55, v55, v95
	v_mul_f32_e32 v40, v40, v96
	v_mul_f32_e32 v56, v56, v96
	v_mul_f32_e32 v41, v41, v97
	v_mul_f32_e32 v57, v57, v97
	ds_read_b128 v[94:97], v2 offset:64
	s_waitcnt lgkmcnt(0)
	v_mul_f32_e32 v42, v42, v94
	v_mul_f32_e32 v58, v58, v94
	v_mul_f32_e32 v43, v43, v95
	v_mul_f32_e32 v59, v59, v95
	v_mul_f32_e32 v44, v44, v96
	v_mul_f32_e32 v60, v60, v96
	v_mul_f32_e32 v45, v45, v97
	v_mul_f32_e32 v61, v61, v97
	ds_read_b128 v[94:97], v2 offset:96
	s_waitcnt lgkmcnt(0)
	v_mul_f32_e32 v46, v46, v94
	v_mul_f32_e32 v62, v62, v94
	v_mul_f32_e32 v47, v47, v95
	v_mul_f32_e32 v63, v63, v95
	v_mul_f32_e32 v48, v48, v96
	v_mul_f32_e32 v64, v64, v96
	v_mul_f32_e32 v49, v49, v97
	v_mul_f32_e32 v65, v65, v97
.Lmy_nors_3:
	s_waitcnt lgkmcnt(0)
	v_add_u32_e32 v2, 0x6000, v237
	v_mfma_f32_32x32x16_bf16 v[82:97], v[218:221], v[4:7], v[66:81]
	v_exp_f32_e32 v142, v142
	v_exp_f32_e32 v143, v143
	v_exp_f32_e32 v144, v144
	v_add_f32_e32 v27, v142, v143
	v_exp_f32_e32 v145, v145
	ds_read_b64_tr_b16 v[114:115], v2 offset:49152
	ds_read_b64_tr_b16 v[116:117], v2 offset:49664
	ds_read_b64_tr_b16 v[118:119], v2 offset:50176
	ds_read_b64_tr_b16 v[120:121], v2 offset:50688
	v_mfma_f32_32x32x16_bf16 v[98:113], v[214:217], v[4:7], v[66:81]
	v_exp_f32_e32 v146, v146
	v_add_f32_e32 v27, v27, v144
	v_exp_f32_e32 v147, v147
	v_add_f32_e32 v27, v27, v145
	v_exp_f32_e32 v148, v148
	ds_read_b64_tr_b16 v[122:123], v2 offset:51200
	ds_read_b64_tr_b16 v[124:125], v2 offset:51712
	ds_read_b64_tr_b16 v[126:127], v2 offset:52224
	ds_read_b64_tr_b16 v[128:129], v2 offset:52736
	v_mfma_f32_32x32x16_bf16 v[82:97], v[210:213], v[8:11], v[82:97]
	v_add_f32_e32 v27, v27, v146
	v_exp_f32_e32 v149, v149
	v_add_f32_e32 v27, v27, v147
	v_add_f32_e32 v27, v27, v148
	v_add_f32_e32 v27, v27, v149
	ds_read_b64_tr_b16 v[240:241], v2 offset:53248
	ds_read_b64_tr_b16 v[242:243], v2 offset:53760
	ds_read_b64_tr_b16 v[244:245], v2 offset:54272
	ds_read_b64_tr_b16 v[246:247], v2 offset:54784
	v_mfma_f32_32x32x16_bf16 v[98:113], v[206:209], v[8:11], v[98:113]
	v_cvt_pk_bf16_f32 v142, v142, v143
	v_cvt_pk_bf16_f32 v143, v144, v145
	v_cvt_pk_bf16_f32 v144, v146, v147
	v_cvt_pk_bf16_f32 v145, v148, v149
	ds_read_b64_tr_b16 v[248:249], v2 offset:55296
	ds_read_b64_tr_b16 v[250:251], v2 offset:55808
	ds_read_b64_tr_b16 v[20:21], v2 offset:56320
	ds_read_b64_tr_b16 v[22:23], v2 offset:56832
	v_mfma_f32_32x32x16_bf16 v[82:97], v[202:205], v[12:15], v[82:97]
	v_exp_f32_e32 v150, v150
	v_exp_f32_e32 v151, v151
	v_exp_f32_e32 v152, v152
	v_add_f32_e32 v27, v27, v150
	v_exp_f32_e32 v153, v153
	v_mfma_f32_32x32x16_bf16 v[98:113], v[198:201], v[12:15], v[98:113]
	v_add_f32_e32 v27, v27, v151
	v_exp_f32_e32 v154, v154
	v_add_f32_e32 v27, v27, v152
	v_exp_f32_e32 v155, v155
	v_add_f32_e32 v27, v27, v153
	v_mfma_f32_32x32x16_bf16 v[82:97], v[194:197], v[130:133], v[82:97]
	v_exp_f32_e32 v156, v156
	v_add_f32_e32 v27, v27, v154
	v_exp_f32_e32 v157, v157
	v_add_f32_e32 v27, v27, v155
	v_add_f32_e32 v27, v27, v156
	v_mfma_f32_32x32x16_bf16 v[98:113], v[190:193], v[130:133], v[98:113]
	v_add_f32_e32 v27, v27, v157
	v_cvt_pk_bf16_f32 v150, v150, v151
	v_cvt_pk_bf16_f32 v151, v152, v153
	v_cvt_pk_bf16_f32 v152, v154, v155
	v_cvt_pk_bf16_f32 v153, v156, v157
	v_mfma_f32_32x32x16_bf16 v[82:97], v[186:189], v[134:137], v[82:97]
	v_exp_f32_e32 v158, v158
	v_exp_f32_e32 v159, v159
	v_exp_f32_e32 v160, v160
	v_add_f32_e32 v27, v27, v158
	v_exp_f32_e32 v161, v161
	v_mfma_f32_32x32x16_bf16 v[98:113], v[182:185], v[134:137], v[98:113]
	v_add_f32_e32 v27, v27, v159
	v_exp_f32_e32 v162, v162
	v_add_f32_e32 v27, v27, v160
	v_exp_f32_e32 v163, v163
	v_add_f32_e32 v27, v27, v161
	v_mfma_f32_32x32x16_bf16 v[82:97], v[178:181], v[138:141], v[82:97]
	v_exp_f32_e32 v164, v164
	v_add_f32_e32 v27, v27, v162
	v_exp_f32_e32 v165, v165
	v_add_f32_e32 v27, v27, v163
	v_add_f32_e32 v27, v27, v164
	v_mfma_f32_32x32x16_bf16 v[98:113], v[174:177], v[138:141], v[98:113]
	v_add_f32_e32 v27, v27, v165
	v_cvt_pk_bf16_f32 v158, v158, v159
	v_cvt_pk_bf16_f32 v159, v160, v161
	v_cvt_pk_bf16_f32 v160, v162, v163
	v_cvt_pk_bf16_f32 v161, v164, v165
	s_waitcnt vmcnt(6)
	s_barrier
	s_waitcnt lgkmcnt(0)
	v_add_u32_e32 v2, 0x3000, v238
	v_mfma_f32_32x32x16_bf16 v[34:49], v[142:145], v[114:117], v[34:49]
	s_add_u32 m0, s57, 0x4000
	v_exp_f32_e32 v166, v166
	v_exp_f32_e32 v167, v167
	global_load_lds_dwordx4 v[28:29], off
	v_lshl_add_u64 v[28:29], v[28:29], 0, s[30:31]
	v_exp_f32_e32 v168, v168
	v_add_f32_e32 v27, v27, v166
	v_exp_f32_e32 v169, v169
	ds_read_b128 v[218:221], v2
	ds_read_b128 v[214:217], v2 offset:512
	ds_read_b128 v[210:213], v2 offset:2048
	v_mfma_f32_32x32x16_bf16 v[50:65], v[142:145], v[240:243], v[50:65]
	s_cmp_eq_u32 s79, 1
	s_cbranch_scc1 .Lmy_gl_4
	s_add_u32 m0, s40, 0x0
	s_nop 0
	global_load_lds_dwordx4 v[24:25], off
	v_lshl_add_u64 v[24:25], v[24:25], 0, s[30:31]
.Lmy_gl_4:
	v_add_f32_e32 v27, v27, v167
	v_exp_f32_e32 v170, v170
	v_add_f32_e32 v27, v27, v168
	v_exp_f32_e32 v171, v171
	v_add_f32_e32 v27, v27, v169
	ds_read_b128 v[206:209], v2 offset:2560
	ds_read_b128 v[202:205], v2 offset:4096
	ds_read_b128 v[198:201], v2 offset:4608
	v_mfma_f32_32x32x16_bf16 v[34:49], v[150:153], v[118:121], v[34:49]
	s_cmp_eq_u32 s79, 1
	s_cbranch_scc1 .Lmy_gl_5
	s_add_u32 m0, s43, 0x0
	s_nop 0
	global_load_lds_dwordx4 v[30:31], off
	v_lshl_add_u64 v[30:31], v[30:31], 0, s[12:13]
.Lmy_gl_5:
	v_exp_f32_e32 v172, v172
	v_add_f32_e32 v27, v27, v170
	v_exp_f32_e32 v173, v173
	v_add_f32_e32 v27, v27, v171
	v_add_f32_e32 v27, v27, v172
	ds_read_b128 v[194:197], v2 offset:6144
	ds_read_b128 v[190:193], v2 offset:6656
	ds_read_b128 v[186:189], v2 offset:8192
	v_mfma_f32_32x32x16_bf16 v[50:65], v[150:153], v[244:247], v[50:65]
	v_add_f32_e32 v27, v27, v173
	v_cvt_pk_bf16_f32 v166, v166, v167
	v_cvt_pk_bf16_f32 v167, v168, v169
	v_cvt_pk_bf16_f32 v168, v170, v171
	v_cvt_pk_bf16_f32 v169, v172, v173
	v_add_f32_e32 v236, v236, v27
	ds_read_b128 v[182:185], v2 offset:8704
	ds_read_b128 v[178:181], v2 offset:10240
	ds_read_b128 v[174:177], v2 offset:10752
	v_mfma_f32_32x32x16_bf16 v[34:49], v[158:161], v[122:125], v[34:49]
	v_max3_f32 v19, v82, v83, v84
	v_max3_f32 v26, v85, v86, v87
	v_max3_f32 v19, v19, v88, v89
	v_max3_f32 v26, v26, v90, v91
	v_mfma_f32_32x32x16_bf16 v[50:65], v[158:161], v[248:251], v[50:65]
	v_max3_f32 v19, v19, v92, v93
	v_max3_f32 v26, v26, v94, v95
	v_max3_f32 v19, v19, v96, v97
	v_max3_f32 v26, v26, v98, v99
	v_mfma_f32_32x32x16_bf16 v[34:49], v[166:169], v[126:129], v[34:49]
	v_max3_f32 v19, v19, v100, v101
	v_max3_f32 v26, v26, v102, v103
	v_max3_f32 v19, v19, v104, v105
	v_max3_f32 v26, v26, v106, v107
	v_mfma_f32_32x32x16_bf16 v[50:65], v[166:169], v[20:23], v[50:65]
	v_max3_f32 v19, v19, v108, v109
	v_max3_f32 v26, v26, v110, v111
	v_max3_f32 v19, v19, v112, v113
	v_max_f32_e32 v19, v19, v26
	v_cmp_lt_f32_e32 vcc, s41, v19
	s_cbranch_vccz .Lmy_nors_6
	s_nop 15
	s_nop 15
	v_mov_b32_e32 v26, v19
	s_nop 1
	v_permlane32_swap_b32_e32 v19, v26
	v_max_f32_e32 v19, v19, v26
	v_max_f32_e32 v19, v19, v19
	v_max_f32_e32 v150, 0, v19
	v_exp_f32_e64 v151, -v150
	v_add_f32_e32 v239, v239, v150
	v_xor_b32_e32 v66, 0x80000000, v239
	v_mov_b32_e32 v67, v66
	v_mov_b32_e32 v68, v66
	v_mov_b32_e32 v69, v66
	v_mov_b32_e32 v70, v66
	v_mov_b32_e32 v71, v66
	v_mov_b32_e32 v72, v66
	v_mov_b32_e32 v73, v66
	v_mov_b32_e32 v74, v66
	v_mov_b32_e32 v75, v66
	v_mov_b32_e32 v76, v66
	v_mov_b32_e32 v77, v66
	v_mov_b32_e32 v78, v66
	v_mov_b32_e32 v79, v66
	v_mov_b32_e32 v80, v66
	v_mov_b32_e32 v81, v66
	v_sub_f32_e32 v82, v82, v150
	v_sub_f32_e32 v83, v83, v150
	v_sub_f32_e32 v84, v84, v150
	v_sub_f32_e32 v85, v85, v150
	v_sub_f32_e32 v86, v86, v150
	v_sub_f32_e32 v87, v87, v150
	v_sub_f32_e32 v88, v88, v150
	v_sub_f32_e32 v89, v89, v150
	v_sub_f32_e32 v90, v90, v150
	v_sub_f32_e32 v91, v91, v150
	v_sub_f32_e32 v92, v92, v150
	v_sub_f32_e32 v93, v93, v150
	v_sub_f32_e32 v94, v94, v150
	v_sub_f32_e32 v95, v95, v150
	v_sub_f32_e32 v96, v96, v150
	v_sub_f32_e32 v97, v97, v150
	v_sub_f32_e32 v98, v98, v150
	v_sub_f32_e32 v99, v99, v150
	v_sub_f32_e32 v100, v100, v150
	v_sub_f32_e32 v101, v101, v150
	v_sub_f32_e32 v102, v102, v150
	v_sub_f32_e32 v103, v103, v150
	v_sub_f32_e32 v104, v104, v150
	v_sub_f32_e32 v105, v105, v150
	v_sub_f32_e32 v106, v106, v150
	v_sub_f32_e32 v107, v107, v150
	v_sub_f32_e32 v108, v108, v150
	v_sub_f32_e32 v109, v109, v150
	v_sub_f32_e32 v110, v110, v150
	v_sub_f32_e32 v111, v111, v150
	v_sub_f32_e32 v112, v112, v150
	v_sub_f32_e32 v113, v113, v150
	v_mul_f32_e32 v236, v236, v151
	s_mov_b64 s[96:97], exec
	s_and_b64 exec, exec, s[8:9]
	ds_write_b32 v235, v151
	s_mov_b64 exec, s[96:97]
	v_lshl_add_u32 v2, v228, 4, s47
	ds_read_b128 v[154:157], v2 offset:0
	s_waitcnt lgkmcnt(0)
	v_mul_f32_e32 v34, v34, v154
	v_mul_f32_e32 v50, v50, v154
	v_mul_f32_e32 v35, v35, v155
	v_mul_f32_e32 v51, v51, v155
	v_mul_f32_e32 v36, v36, v156
	v_mul_f32_e32 v52, v52, v156
	v_mul_f32_e32 v37, v37, v157
	v_mul_f32_e32 v53, v53, v157
	ds_read_b128 v[154:157], v2 offset:32
	s_waitcnt lgkmcnt(0)
	v_mul_f32_e32 v38, v38, v154
	v_mul_f32_e32 v54, v54, v154
	v_mul_f32_e32 v39, v39, v155
	v_mul_f32_e32 v55, v55, v155
	v_mul_f32_e32 v40, v40, v156
	v_mul_f32_e32 v56, v56, v156
	v_mul_f32_e32 v41, v41, v157
	v_mul_f32_e32 v57, v57, v157
	ds_read_b128 v[154:157], v2 offset:64
	s_waitcnt lgkmcnt(0)
	v_mul_f32_e32 v42, v42, v154
	v_mul_f32_e32 v58, v58, v154
	v_mul_f32_e32 v43, v43, v155
	v_mul_f32_e32 v59, v59, v155
	v_mul_f32_e32 v44, v44, v156
	v_mul_f32_e32 v60, v60, v156
	v_mul_f32_e32 v45, v45, v157
	v_mul_f32_e32 v61, v61, v157
	ds_read_b128 v[154:157], v2 offset:96
	s_waitcnt lgkmcnt(0)
	v_mul_f32_e32 v46, v46, v154
	v_mul_f32_e32 v62, v62, v154
	v_mul_f32_e32 v47, v47, v155
	v_mul_f32_e32 v63, v63, v155
	v_mul_f32_e32 v48, v48, v156
	v_mul_f32_e32 v64, v64, v156
	v_mul_f32_e32 v49, v49, v157
	v_mul_f32_e32 v65, v65, v157

.Lmy_A_loop:
	s_waitcnt lgkmcnt(0)
	v_mov_b32_e32 v2, v237
	v_mfma_f32_32x32x16_bf16 v[142:157], v[218:221], v[4:7], v[66:81]
	v_exp_f32_e32 v82, v82
	v_exp_f32_e32 v83, v83
	v_exp_f32_e32 v84, v84
	v_add_f32_e32 v27, v82, v83
	v_exp_f32_e32 v85, v85
	ds_read_b64_tr_b16 v[114:115], v2 offset:49152
	ds_read_b64_tr_b16 v[116:117], v2 offset:49664
	ds_read_b64_tr_b16 v[118:119], v2 offset:50176
	ds_read_b64_tr_b16 v[120:121], v2 offset:50688
	v_mfma_f32_32x32x16_bf16 v[158:173], v[214:217], v[4:7], v[66:81]
	v_exp_f32_e32 v86, v86
	v_add_f32_e32 v27, v27, v84
	v_exp_f32_e32 v87, v87
	v_add_f32_e32 v27, v27, v85
	v_exp_f32_e32 v88, v88
	ds_read_b64_tr_b16 v[122:123], v2 offset:51200
	ds_read_b64_tr_b16 v[124:125], v2 offset:51712
	ds_read_b64_tr_b16 v[126:127], v2 offset:52224
	ds_read_b64_tr_b16 v[128:129], v2 offset:52736
	v_mfma_f32_32x32x16_bf16 v[142:157], v[210:213], v[8:11], v[142:157]
	v_add_f32_e32 v27, v27, v86
	v_exp_f32_e32 v89, v89
	v_add_f32_e32 v27, v27, v87
	v_add_f32_e32 v27, v27, v88
	v_add_f32_e32 v27, v27, v89
	ds_read_b64_tr_b16 v[240:241], v2 offset:53248
	ds_read_b64_tr_b16 v[242:243], v2 offset:53760
	ds_read_b64_tr_b16 v[244:245], v2 offset:54272
	ds_read_b64_tr_b16 v[246:247], v2 offset:54784
	v_mfma_f32_32x32x16_bf16 v[158:173], v[206:209], v[8:11], v[158:173]
	v_cvt_pk_bf16_f32 v82, v82, v83
	v_cvt_pk_bf16_f32 v83, v84, v85
	v_cvt_pk_bf16_f32 v84, v86, v87
	v_cvt_pk_bf16_f32 v85, v88, v89
	ds_read_b64_tr_b16 v[248:249], v2 offset:55296
	ds_read_b64_tr_b16 v[250:251], v2 offset:55808
	ds_read_b64_tr_b16 v[20:21], v2 offset:56320
	ds_read_b64_tr_b16 v[22:23], v2 offset:56832
	v_mfma_f32_32x32x16_bf16 v[142:157], v[202:205], v[12:15], v[142:157]
	v_exp_f32_e32 v90, v90
	v_exp_f32_e32 v91, v91
	v_exp_f32_e32 v92, v92
	v_add_f32_e32 v27, v27, v90
	v_exp_f32_e32 v93, v93
	v_mfma_f32_32x32x16_bf16 v[158:173], v[198:201], v[12:15], v[158:173]
	v_add_f32_e32 v27, v27, v91
	v_exp_f32_e32 v94, v94
	v_add_f32_e32 v27, v27, v92
	v_exp_f32_e32 v95, v95
	v_add_f32_e32 v27, v27, v93
	v_mfma_f32_32x32x16_bf16 v[142:157], v[194:197], v[130:133], v[142:157]
	v_exp_f32_e32 v96, v96
	v_add_f32_e32 v27, v27, v94
	v_exp_f32_e32 v97, v97
	v_add_f32_e32 v27, v27, v95
	v_add_f32_e32 v27, v27, v96
	v_mfma_f32_32x32x16_bf16 v[158:173], v[190:193], v[130:133], v[158:173]
	v_add_f32_e32 v27, v27, v97
	v_cvt_pk_bf16_f32 v90, v90, v91
	v_cvt_pk_bf16_f32 v91, v92, v93
	v_cvt_pk_bf16_f32 v92, v94, v95
	v_cvt_pk_bf16_f32 v93, v96, v97
	v_mfma_f32_32x32x16_bf16 v[142:157], v[186:189], v[134:137], v[142:157]
	v_exp_f32_e32 v98, v98
	v_exp_f32_e32 v99, v99
	v_exp_f32_e32 v100, v100
	v_add_f32_e32 v27, v27, v98
	v_exp_f32_e32 v101, v101
	v_mfma_f32_32x32x16_bf16 v[158:173], v[182:185], v[134:137], v[158:173]
	v_add_f32_e32 v27, v27, v99
	v_exp_f32_e32 v102, v102
	v_add_f32_e32 v27, v27, v100
	v_exp_f32_e32 v103, v103
	v_add_f32_e32 v27, v27, v101
	v_mfma_f32_32x32x16_bf16 v[142:157], v[178:181], v[138:141], v[142:157]
	v_exp_f32_e32 v104, v104
	v_add_f32_e32 v27, v27, v102
	v_exp_f32_e32 v105, v105
	v_add_f32_e32 v27, v27, v103
	v_add_f32_e32 v27, v27, v104
	v_mfma_f32_32x32x16_bf16 v[158:173], v[174:177], v[138:141], v[158:173]
	v_add_f32_e32 v27, v27, v105
	v_cvt_pk_bf16_f32 v98, v98, v99
	v_cvt_pk_bf16_f32 v99, v100, v101
	v_cvt_pk_bf16_f32 v100, v102, v103
	v_cvt_pk_bf16_f32 v101, v104, v105
	s_waitcnt vmcnt(6)
	s_barrier
	s_waitcnt lgkmcnt(0)
	v_add_u32_e32 v2, 0x6000, v238
	v_mfma_f32_32x32x16_bf16 v[34:49], v[82:85], v[114:117], v[34:49]
	s_add_u32 m0, s57, 0x6000
	v_exp_f32_e32 v106, v106
	v_exp_f32_e32 v107, v107
	global_load_lds_dwordx4 v[28:29], off
	v_lshl_add_u64 v[28:29], v[28:29], 0, s[30:31]
	v_exp_f32_e32 v108, v108
	v_add_f32_e32 v27, v27, v106
	v_exp_f32_e32 v109, v109
	ds_read_b128 v[218:221], v2
	ds_read_b128 v[214:217], v2 offset:512
	ds_read_b128 v[210:213], v2 offset:2048
	v_mfma_f32_32x32x16_bf16 v[50:65], v[82:85], v[240:243], v[50:65]
	s_add_u32 m0, s40, 0x3000
	v_add_f32_e32 v27, v27, v107
	v_exp_f32_e32 v110, v110
	global_load_lds_dwordx4 v[24:25], off
	v_lshl_add_u64 v[24:25], v[24:25], 0, s[30:31]
	v_add_f32_e32 v27, v27, v108
	v_exp_f32_e32 v111, v111
	v_add_f32_e32 v27, v27, v109
	ds_read_b128 v[206:209], v2 offset:2560
	ds_read_b128 v[202:205], v2 offset:4096
	ds_read_b128 v[198:201], v2 offset:4608
	v_mfma_f32_32x32x16_bf16 v[34:49], v[90:93], v[118:121], v[34:49]
	s_add_u32 m0, s43, 0x3000
	v_exp_f32_e32 v112, v112
	v_add_f32_e32 v27, v27, v110
	global_load_lds_dwordx4 v[30:31], off
	v_lshl_add_u64 v[30:31], v[30:31], 0, s[12:13]
	v_exp_f32_e32 v113, v113
	v_add_f32_e32 v27, v27, v111
	v_add_f32_e32 v27, v27, v112
	ds_read_b128 v[194:197], v2 offset:6144
	ds_read_b128 v[190:193], v2 offset:6656
	ds_read_b128 v[186:189], v2 offset:8192
	v_mfma_f32_32x32x16_bf16 v[50:65], v[90:93], v[244:247], v[50:65]
	v_add_f32_e32 v27, v27, v113
	v_cvt_pk_bf16_f32 v106, v106, v107
	v_cvt_pk_bf16_f32 v107, v108, v109
	v_cvt_pk_bf16_f32 v108, v110, v111
	v_cvt_pk_bf16_f32 v109, v112, v113
	v_add_f32_e32 v236, v236, v27
	ds_read_b128 v[182:185], v2 offset:8704
	ds_read_b128 v[178:181], v2 offset:10240
	ds_read_b128 v[174:177], v2 offset:10752
	v_mfma_f32_32x32x16_bf16 v[34:49], v[98:101], v[122:125], v[34:49]
	v_max3_f32 v19, v142, v143, v144
	v_max3_f32 v26, v145, v146, v147
	v_max3_f32 v19, v19, v148, v149
	v_max3_f32 v26, v26, v150, v151
	v_mfma_f32_32x32x16_bf16 v[50:65], v[98:101], v[248:251], v[50:65]
	v_max3_f32 v19, v19, v152, v153
	v_max3_f32 v26, v26, v154, v155
	v_max3_f32 v19, v19, v156, v157
	v_max3_f32 v26, v26, v158, v159
	v_mfma_f32_32x32x16_bf16 v[34:49], v[106:109], v[126:129], v[34:49]
	v_max3_f32 v19, v19, v160, v161
	v_max3_f32 v26, v26, v162, v163
	v_max3_f32 v19, v19, v164, v165
	v_max3_f32 v26, v26, v166, v167
	v_mfma_f32_32x32x16_bf16 v[50:65], v[106:109], v[20:23], v[50:65]
	v_max3_f32 v19, v19, v168, v169
	v_max3_f32 v26, v26, v170, v171
	v_max3_f32 v19, v19, v172, v173
	v_max_f32_e32 v19, v19, v26
	v_cmp_lt_f32_e32 vcc, s41, v19
	s_cbranch_vccz .Lmy_nors_7
	s_nop 15
	s_nop 15
	v_mov_b32_e32 v26, v19
	s_nop 1
	v_permlane32_swap_b32_e32 v19, v26
	v_max_f32_e32 v19, v19, v26
	v_max_f32_e32 v19, v19, v19
	v_max_f32_e32 v90, 0, v19
	v_exp_f32_e64 v91, -v90
	v_add_f32_e32 v239, v239, v90
	v_xor_b32_e32 v66, 0x80000000, v239
	v_mov_b32_e32 v67, v66
	v_mov_b32_e32 v68, v66
	v_mov_b32_e32 v69, v66
	v_mov_b32_e32 v70, v66
	v_mov_b32_e32 v71, v66
	v_mov_b32_e32 v72, v66
	v_mov_b32_e32 v73, v66
	v_mov_b32_e32 v74, v66
	v_mov_b32_e32 v75, v66
	v_mov_b32_e32 v76, v66
	v_mov_b32_e32 v77, v66
	v_mov_b32_e32 v78, v66
	v_mov_b32_e32 v79, v66
	v_mov_b32_e32 v80, v66
	v_mov_b32_e32 v81, v66
	v_sub_f32_e32 v142, v142, v90
	v_sub_f32_e32 v143, v143, v90
	v_sub_f32_e32 v144, v144, v90
	v_sub_f32_e32 v145, v145, v90
	v_sub_f32_e32 v146, v146, v90
	v_sub_f32_e32 v147, v147, v90
	v_sub_f32_e32 v148, v148, v90
	v_sub_f32_e32 v149, v149, v90
	v_sub_f32_e32 v150, v150, v90
	v_sub_f32_e32 v151, v151, v90
	v_sub_f32_e32 v152, v152, v90
	v_sub_f32_e32 v153, v153, v90
	v_sub_f32_e32 v154, v154, v90
	v_sub_f32_e32 v155, v155, v90
	v_sub_f32_e32 v156, v156, v90
	v_sub_f32_e32 v157, v157, v90
	v_sub_f32_e32 v158, v158, v90
	v_sub_f32_e32 v159, v159, v90
	v_sub_f32_e32 v160, v160, v90
	v_sub_f32_e32 v161, v161, v90
	v_sub_f32_e32 v162, v162, v90
	v_sub_f32_e32 v163, v163, v90
	v_sub_f32_e32 v164, v164, v90
	v_sub_f32_e32 v165, v165, v90
	v_sub_f32_e32 v166, v166, v90
	v_sub_f32_e32 v167, v167, v90
	v_sub_f32_e32 v168, v168, v90
	v_sub_f32_e32 v169, v169, v90
	v_sub_f32_e32 v170, v170, v90
	v_sub_f32_e32 v171, v171, v90
	v_sub_f32_e32 v172, v172, v90
	v_sub_f32_e32 v173, v173, v90
	v_mul_f32_e32 v236, v236, v91
	s_mov_b64 s[96:97], exec
	s_and_b64 exec, exec, s[8:9]
	ds_write_b32 v235, v91
	s_mov_b64 exec, s[96:97]
	v_lshl_add_u32 v2, v228, 4, s47
	ds_read_b128 v[94:97], v2 offset:0
	s_waitcnt lgkmcnt(0)
	v_mul_f32_e32 v34, v34, v94
	v_mul_f32_e32 v50, v50, v94
	v_mul_f32_e32 v35, v35, v95
	v_mul_f32_e32 v51, v51, v95
	v_mul_f32_e32 v36, v36, v96
	v_mul_f32_e32 v52, v52, v96
	v_mul_f32_e32 v37, v37, v97
	v_mul_f32_e32 v53, v53, v97
	ds_read_b128 v[94:97], v2 offset:32
	s_waitcnt lgkmcnt(0)
	v_mul_f32_e32 v38, v38, v94
	v_mul_f32_e32 v54, v54, v94
	v_mul_f32_e32 v39, v39, v95
	v_mul_f32_e32 v55, v55, v95
	v_mul_f32_e32 v40, v40, v96
	v_mul_f32_e32 v56, v56, v96
	v_mul_f32_e32 v41, v41, v97
	v_mul_f32_e32 v57, v57, v97
	ds_read_b128 v[94:97], v2 offset:64
	s_waitcnt lgkmcnt(0)
	v_mul_f32_e32 v42, v42, v94
	v_mul_f32_e32 v58, v58, v94
	v_mul_f32_e32 v43, v43, v95
	v_mul_f32_e32 v59, v59, v95
	v_mul_f32_e32 v44, v44, v96
	v_mul_f32_e32 v60, v60, v96
	v_mul_f32_e32 v45, v45, v97
	v_mul_f32_e32 v61, v61, v97
	ds_read_b128 v[94:97], v2 offset:96
	s_waitcnt lgkmcnt(0)
	v_mul_f32_e32 v46, v46, v94
	v_mul_f32_e32 v62, v62, v94
	v_mul_f32_e32 v47, v47, v95
	v_mul_f32_e32 v63, v63, v95
	v_mul_f32_e32 v48, v48, v96
	v_mul_f32_e32 v64, v64, v96
	v_mul_f32_e32 v49, v49, v97
	v_mul_f32_e32 v65, v65, v97
.Lmy_nors_7:
	s_waitcnt lgkmcnt(0)
	v_add_u32_e32 v2, 0x2000, v237
	v_mfma_f32_32x32x16_bf16 v[82:97], v[218:221], v[4:7], v[66:81]
	v_exp_f32_e32 v142, v142
	v_exp_f32_e32 v143, v143
	v_exp_f32_e32 v144, v144
	v_add_f32_e32 v27, v142, v143
	v_exp_f32_e32 v145, v145
	ds_read_b64_tr_b16 v[114:115], v2 offset:49152
	ds_read_b64_tr_b16 v[116:117], v2 offset:49664
	ds_read_b64_tr_b16 v[118:119], v2 offset:50176
	ds_read_b64_tr_b16 v[120:121], v2 offset:50688
	v_mfma_f32_32x32x16_bf16 v[98:113], v[214:217], v[4:7], v[66:81]
	v_exp_f32_e32 v146, v146
	v_add_f32_e32 v27, v27, v144
	v_exp_f32_e32 v147, v147
	v_add_f32_e32 v27, v27, v145
	v_exp_f32_e32 v148, v148
	ds_read_b64_tr_b16 v[122:123], v2 offset:51200
	ds_read_b64_tr_b16 v[124:125], v2 offset:51712
	ds_read_b64_tr_b16 v[126:127], v2 offset:52224
	ds_read_b64_tr_b16 v[128:129], v2 offset:52736
	v_mfma_f32_32x32x16_bf16 v[82:97], v[210:213], v[8:11], v[82:97]
	v_add_f32_e32 v27, v27, v146
	v_exp_f32_e32 v149, v149
	v_add_f32_e32 v27, v27, v147
	v_add_f32_e32 v27, v27, v148
	v_add_f32_e32 v27, v27, v149
	ds_read_b64_tr_b16 v[240:241], v2 offset:53248
	ds_read_b64_tr_b16 v[242:243], v2 offset:53760
	ds_read_b64_tr_b16 v[244:245], v2 offset:54272
	ds_read_b64_tr_b16 v[246:247], v2 offset:54784
	v_mfma_f32_32x32x16_bf16 v[98:113], v[206:209], v[8:11], v[98:113]
	v_cvt_pk_bf16_f32 v142, v142, v143
	v_cvt_pk_bf16_f32 v143, v144, v145
	v_cvt_pk_bf16_f32 v144, v146, v147
	v_cvt_pk_bf16_f32 v145, v148, v149
	ds_read_b64_tr_b16 v[248:249], v2 offset:55296
	ds_read_b64_tr_b16 v[250:251], v2 offset:55808
	ds_read_b64_tr_b16 v[20:21], v2 offset:56320
	ds_read_b64_tr_b16 v[22:23], v2 offset:56832
	v_mfma_f32_32x32x16_bf16 v[82:97], v[202:205], v[12:15], v[82:97]
	v_exp_f32_e32 v150, v150
	v_exp_f32_e32 v151, v151
	v_exp_f32_e32 v152, v152
	v_add_f32_e32 v27, v27, v150
	v_exp_f32_e32 v153, v153
	v_mfma_f32_32x32x16_bf16 v[98:113], v[198:201], v[12:15], v[98:113]
	v_add_f32_e32 v27, v27, v151
	v_exp_f32_e32 v154, v154
	v_add_f32_e32 v27, v27, v152
	v_exp_f32_e32 v155, v155
	v_add_f32_e32 v27, v27, v153
	v_mfma_f32_32x32x16_bf16 v[82:97], v[194:197], v[130:133], v[82:97]
	v_exp_f32_e32 v156, v156
	v_add_f32_e32 v27, v27, v154
	v_exp_f32_e32 v157, v157
	v_add_f32_e32 v27, v27, v155
	v_add_f32_e32 v27, v27, v156
	v_mfma_f32_32x32x16_bf16 v[98:113], v[190:193], v[130:133], v[98:113]
	v_add_f32_e32 v27, v27, v157
	v_cvt_pk_bf16_f32 v150, v150, v151
	v_cvt_pk_bf16_f32 v151, v152, v153
	v_cvt_pk_bf16_f32 v152, v154, v155
	v_cvt_pk_bf16_f32 v153, v156, v157
	v_mfma_f32_32x32x16_bf16 v[82:97], v[186:189], v[134:137], v[82:97]
	v_exp_f32_e32 v158, v158
	v_exp_f32_e32 v159, v159
	v_exp_f32_e32 v160, v160
	v_add_f32_e32 v27, v27, v158
	v_exp_f32_e32 v161, v161
	v_mfma_f32_32x32x16_bf16 v[98:113], v[182:185], v[134:137], v[98:113]
	v_add_f32_e32 v27, v27, v159
	v_exp_f32_e32 v162, v162
	v_add_f32_e32 v27, v27, v160
	v_exp_f32_e32 v163, v163
	v_add_f32_e32 v27, v27, v161
	v_mfma_f32_32x32x16_bf16 v[82:97], v[178:181], v[138:141], v[82:97]
	v_exp_f32_e32 v164, v164
	v_add_f32_e32 v27, v27, v162
	v_exp_f32_e32 v165, v165
	v_add_f32_e32 v27, v27, v163
	v_add_f32_e32 v27, v27, v164
	v_mfma_f32_32x32x16_bf16 v[98:113], v[174:177], v[138:141], v[98:113]
	v_add_f32_e32 v27, v27, v165
	v_cvt_pk_bf16_f32 v158, v158, v159
	v_cvt_pk_bf16_f32 v159, v160, v161
	v_cvt_pk_bf16_f32 v160, v162, v163
	v_cvt_pk_bf16_f32 v161, v164, v165
	s_waitcnt vmcnt(6)
	s_barrier
	s_waitcnt lgkmcnt(0)
	v_add_u32_e32 v2, 0x9000, v238
	v_mfma_f32_32x32x16_bf16 v[34:49], v[142:145], v[114:117], v[34:49]
	s_add_u32 m0, s57, 0x0
	v_exp_f32_e32 v166, v166
	v_exp_f32_e32 v167, v167
	global_load_lds_dwordx4 v[28:29], off
	v_lshl_add_u64 v[28:29], v[28:29], 0, s[30:31]
	v_exp_f32_e32 v168, v168
	v_add_f32_e32 v27, v27, v166
	v_exp_f32_e32 v169, v169
	ds_read_b128 v[218:221], v2
	ds_read_b128 v[214:217], v2 offset:512
	ds_read_b128 v[210:213], v2 offset:2048
	v_mfma_f32_32x32x16_bf16 v[50:65], v[142:145], v[240:243], v[50:65]
	s_add_u32 m0, s40, 0x6000
	v_add_f32_e32 v27, v27, v167
	v_exp_f32_e32 v170, v170
	global_load_lds_dwordx4 v[24:25], off
	v_lshl_add_u64 v[24:25], v[24:25], 0, s[30:31]
	v_add_f32_e32 v27, v27, v168
	v_exp_f32_e32 v171, v171
	v_add_f32_e32 v27, v27, v169
	ds_read_b128 v[206:209], v2 offset:2560
	ds_read_b128 v[202:205], v2 offset:4096
	ds_read_b128 v[198:201], v2 offset:4608
	v_mfma_f32_32x32x16_bf16 v[34:49], v[150:153], v[118:121], v[34:49]
	s_add_u32 m0, s43, 0x6000
	v_exp_f32_e32 v172, v172
	v_add_f32_e32 v27, v27, v170
	global_load_lds_dwordx4 v[30:31], off
	v_lshl_add_u64 v[30:31], v[30:31], 0, s[12:13]
	v_exp_f32_e32 v173, v173
	v_add_f32_e32 v27, v27, v171
	v_add_f32_e32 v27, v27, v172
	ds_read_b128 v[194:197], v2 offset:6144
	ds_read_b128 v[190:193], v2 offset:6656
	ds_read_b128 v[186:189], v2 offset:8192
	v_mfma_f32_32x32x16_bf16 v[50:65], v[150:153], v[244:247], v[50:65]
	v_add_f32_e32 v27, v27, v173
	v_cvt_pk_bf16_f32 v166, v166, v167
	v_cvt_pk_bf16_f32 v167, v168, v169
	v_cvt_pk_bf16_f32 v168, v170, v171
	v_cvt_pk_bf16_f32 v169, v172, v173
	v_add_f32_e32 v236, v236, v27
	ds_read_b128 v[182:185], v2 offset:8704
	ds_read_b128 v[178:181], v2 offset:10240
	ds_read_b128 v[174:177], v2 offset:10752
	v_mfma_f32_32x32x16_bf16 v[34:49], v[158:161], v[122:125], v[34:49]
	v_max3_f32 v19, v82, v83, v84
	v_max3_f32 v26, v85, v86, v87
	v_max3_f32 v19, v19, v88, v89
	v_max3_f32 v26, v26, v90, v91
	v_mfma_f32_32x32x16_bf16 v[50:65], v[158:161], v[248:251], v[50:65]
	v_max3_f32 v19, v19, v92, v93
	v_max3_f32 v26, v26, v94, v95
	v_max3_f32 v19, v19, v96, v97
	v_max3_f32 v26, v26, v98, v99
	v_mfma_f32_32x32x16_bf16 v[34:49], v[166:169], v[126:129], v[34:49]
	v_max3_f32 v19, v19, v100, v101
	v_max3_f32 v26, v26, v102, v103
	v_max3_f32 v19, v19, v104, v105
	v_max3_f32 v26, v26, v106, v107
	v_mfma_f32_32x32x16_bf16 v[50:65], v[166:169], v[20:23], v[50:65]
	v_max3_f32 v19, v19, v108, v109
	v_max3_f32 v26, v26, v110, v111
	v_max3_f32 v19, v19, v112, v113
	v_max_f32_e32 v19, v19, v26
	v_cmp_lt_f32_e32 vcc, s41, v19
	s_cbranch_vccz .Lmy_nors_8
	s_nop 15
	s_nop 15
	v_mov_b32_e32 v26, v19
	s_nop 1
	v_permlane32_swap_b32_e32 v19, v26
	v_max_f32_e32 v19, v19, v26
	v_max_f32_e32 v19, v19, v19
	v_max_f32_e32 v150, 0, v19
	v_exp_f32_e64 v151, -v150
	v_add_f32_e32 v239, v239, v150
	v_xor_b32_e32 v66, 0x80000000, v239
	v_mov_b32_e32 v67, v66
	v_mov_b32_e32 v68, v66
	v_mov_b32_e32 v69, v66
	v_mov_b32_e32 v70, v66
	v_mov_b32_e32 v71, v66
	v_mov_b32_e32 v72, v66
	v_mov_b32_e32 v73, v66
	v_mov_b32_e32 v74, v66
	v_mov_b32_e32 v75, v66
	v_mov_b32_e32 v76, v66
	v_mov_b32_e32 v77, v66
	v_mov_b32_e32 v78, v66
	v_mov_b32_e32 v79, v66
	v_mov_b32_e32 v80, v66
	v_mov_b32_e32 v81, v66
	v_sub_f32_e32 v82, v82, v150
	v_sub_f32_e32 v83, v83, v150
	v_sub_f32_e32 v84, v84, v150
	v_sub_f32_e32 v85, v85, v150
	v_sub_f32_e32 v86, v86, v150
	v_sub_f32_e32 v87, v87, v150
	v_sub_f32_e32 v88, v88, v150
	v_sub_f32_e32 v89, v89, v150
	v_sub_f32_e32 v90, v90, v150
	v_sub_f32_e32 v91, v91, v150
	v_sub_f32_e32 v92, v92, v150
	v_sub_f32_e32 v93, v93, v150
	v_sub_f32_e32 v94, v94, v150
	v_sub_f32_e32 v95, v95, v150
	v_sub_f32_e32 v96, v96, v150
	v_sub_f32_e32 v97, v97, v150
	v_sub_f32_e32 v98, v98, v150
	v_sub_f32_e32 v99, v99, v150
	v_sub_f32_e32 v100, v100, v150
	v_sub_f32_e32 v101, v101, v150
	v_sub_f32_e32 v102, v102, v150
	v_sub_f32_e32 v103, v103, v150
	v_sub_f32_e32 v104, v104, v150
	v_sub_f32_e32 v105, v105, v150
	v_sub_f32_e32 v106, v106, v150
	v_sub_f32_e32 v107, v107, v150
	v_sub_f32_e32 v108, v108, v150
	v_sub_f32_e32 v109, v109, v150
	v_sub_f32_e32 v110, v110, v150
	v_sub_f32_e32 v111, v111, v150
	v_sub_f32_e32 v112, v112, v150
	v_sub_f32_e32 v113, v113, v150
	v_mul_f32_e32 v236, v236, v151
	s_mov_b64 s[96:97], exec
	s_and_b64 exec, exec, s[8:9]
	ds_write_b32 v235, v151
	s_mov_b64 exec, s[96:97]
	v_lshl_add_u32 v2, v228, 4, s47
	ds_read_b128 v[154:157], v2 offset:0
	s_waitcnt lgkmcnt(0)
	v_mul_f32_e32 v34, v34, v154
	v_mul_f32_e32 v50, v50, v154
	v_mul_f32_e32 v35, v35, v155
	v_mul_f32_e32 v51, v51, v155
	v_mul_f32_e32 v36, v36, v156
	v_mul_f32_e32 v52, v52, v156
	v_mul_f32_e32 v37, v37, v157
	v_mul_f32_e32 v53, v53, v157
	ds_read_b128 v[154:157], v2 offset:32
	s_waitcnt lgkmcnt(0)
	v_mul_f32_e32 v38, v38, v154
	v_mul_f32_e32 v54, v54, v154
	v_mul_f32_e32 v39, v39, v155
	v_mul_f32_e32 v55, v55, v155
	v_mul_f32_e32 v40, v40, v156
	v_mul_f32_e32 v56, v56, v156
	v_mul_f32_e32 v41, v41, v157
	v_mul_f32_e32 v57, v57, v157
	ds_read_b128 v[154:157], v2 offset:64
	s_waitcnt lgkmcnt(0)
	v_mul_f32_e32 v42, v42, v154
	v_mul_f32_e32 v58, v58, v154
	v_mul_f32_e32 v43, v43, v155
	v_mul_f32_e32 v59, v59, v155
	v_mul_f32_e32 v44, v44, v156
	v_mul_f32_e32 v60, v60, v156
	v_mul_f32_e32 v45, v45, v157
	v_mul_f32_e32 v61, v61, v157
	ds_read_b128 v[154:157], v2 offset:96
	s_waitcnt lgkmcnt(0)
	v_mul_f32_e32 v46, v46, v154
	v_mul_f32_e32 v62, v62, v154
	v_mul_f32_e32 v47, v47, v155
	v_mul_f32_e32 v63, v63, v155
	v_mul_f32_e32 v48, v48, v156
	v_mul_f32_e32 v64, v64, v156
	v_mul_f32_e32 v49, v49, v157
	v_mul_f32_e32 v65, v65, v157
.Lmy_nors_8:
	s_waitcnt lgkmcnt(0)
	v_add_u32_e32 v2, 0x4000, v237
	v_mfma_f32_32x32x16_bf16 v[142:157], v[218:221], v[4:7], v[66:81]
	v_exp_f32_e32 v82, v82
	v_exp_f32_e32 v83, v83
	v_exp_f32_e32 v84, v84
	v_add_f32_e32 v27, v82, v83
	v_exp_f32_e32 v85, v85
	ds_read_b64_tr_b16 v[114:115], v2 offset:49152
	ds_read_b64_tr_b16 v[116:117], v2 offset:49664
	ds_read_b64_tr_b16 v[118:119], v2 offset:50176
	ds_read_b64_tr_b16 v[120:121], v2 offset:50688
	v_mfma_f32_32x32x16_bf16 v[158:173], v[214:217], v[4:7], v[66:81]
	v_exp_f32_e32 v86, v86
	v_add_f32_e32 v27, v27, v84
	v_exp_f32_e32 v87, v87
	v_add_f32_e32 v27, v27, v85
	v_exp_f32_e32 v88, v88
	ds_read_b64_tr_b16 v[122:123], v2 offset:51200
	ds_read_b64_tr_b16 v[124:125], v2 offset:51712
	ds_read_b64_tr_b16 v[126:127], v2 offset:52224
	ds_read_b64_tr_b16 v[128:129], v2 offset:52736
	v_mfma_f32_32x32x16_bf16 v[142:157], v[210:213], v[8:11], v[142:157]
	v_add_f32_e32 v27, v27, v86
	v_exp_f32_e32 v89, v89
	v_add_f32_e32 v27, v27, v87
	v_add_f32_e32 v27, v27, v88
	v_add_f32_e32 v27, v27, v89
	ds_read_b64_tr_b16 v[240:241], v2 offset:53248
	ds_read_b64_tr_b16 v[242:243], v2 offset:53760
	ds_read_b64_tr_b16 v[244:245], v2 offset:54272
	ds_read_b64_tr_b16 v[246:247], v2 offset:54784
	v_mfma_f32_32x32x16_bf16 v[158:173], v[206:209], v[8:11], v[158:173]
	v_cvt_pk_bf16_f32 v82, v82, v83
	v_cvt_pk_bf16_f32 v83, v84, v85
	v_cvt_pk_bf16_f32 v84, v86, v87
	v_cvt_pk_bf16_f32 v85, v88, v89
	ds_read_b64_tr_b16 v[248:249], v2 offset:55296
	ds_read_b64_tr_b16 v[250:251], v2 offset:55808
	ds_read_b64_tr_b16 v[20:21], v2 offset:56320
	ds_read_b64_tr_b16 v[22:23], v2 offset:56832
	v_mfma_f32_32x32x16_bf16 v[142:157], v[202:205], v[12:15], v[142:157]
	v_exp_f32_e32 v90, v90
	v_exp_f32_e32 v91, v91
	v_exp_f32_e32 v92, v92
	v_add_f32_e32 v27, v27, v90
	v_exp_f32_e32 v93, v93
	v_mfma_f32_32x32x16_bf16 v[158:173], v[198:201], v[12:15], v[158:173]
	v_add_f32_e32 v27, v27, v91
	v_exp_f32_e32 v94, v94
	v_add_f32_e32 v27, v27, v92
	v_exp_f32_e32 v95, v95
	v_add_f32_e32 v27, v27, v93
	v_mfma_f32_32x32x16_bf16 v[142:157], v[194:197], v[130:133], v[142:157]
	v_exp_f32_e32 v96, v96
	v_add_f32_e32 v27, v27, v94
	v_exp_f32_e32 v97, v97
	v_add_f32_e32 v27, v27, v95
	v_add_f32_e32 v27, v27, v96
	v_mfma_f32_32x32x16_bf16 v[158:173], v[190:193], v[130:133], v[158:173]
	v_add_f32_e32 v27, v27, v97
	v_cvt_pk_bf16_f32 v90, v90, v91
	v_cvt_pk_bf16_f32 v91, v92, v93
	v_cvt_pk_bf16_f32 v92, v94, v95
	v_cvt_pk_bf16_f32 v93, v96, v97
	v_mfma_f32_32x32x16_bf16 v[142:157], v[186:189], v[134:137], v[142:157]
	v_exp_f32_e32 v98, v98
	v_exp_f32_e32 v99, v99
	v_exp_f32_e32 v100, v100
	v_add_f32_e32 v27, v27, v98
	v_exp_f32_e32 v101, v101
	v_mfma_f32_32x32x16_bf16 v[158:173], v[182:185], v[134:137], v[158:173]
	v_add_f32_e32 v27, v27, v99
	v_exp_f32_e32 v102, v102
	v_add_f32_e32 v27, v27, v100
	v_exp_f32_e32 v103, v103
	v_add_f32_e32 v27, v27, v101
	v_mfma_f32_32x32x16_bf16 v[142:157], v[178:181], v[138:141], v[142:157]
	v_exp_f32_e32 v104, v104
	v_add_f32_e32 v27, v27, v102
	v_exp_f32_e32 v105, v105
	v_add_f32_e32 v27, v27, v103
	v_add_f32_e32 v27, v27, v104
	v_mfma_f32_32x32x16_bf16 v[158:173], v[174:177], v[138:141], v[158:173]
	v_add_f32_e32 v27, v27, v105
	v_cvt_pk_bf16_f32 v98, v98, v99
	v_cvt_pk_bf16_f32 v99, v100, v101
	v_cvt_pk_bf16_f32 v100, v102, v103
	v_cvt_pk_bf16_f32 v101, v104, v105
	s_waitcnt vmcnt(6)
	s_barrier
	s_waitcnt lgkmcnt(0)
	v_mov_b32_e32 v2, v238
	v_mfma_f32_32x32x16_bf16 v[34:49], v[82:85], v[114:117], v[34:49]
	s_add_u32 m0, s57, 0x2000
	v_exp_f32_e32 v106, v106
	v_exp_f32_e32 v107, v107
	global_load_lds_dwordx4 v[28:29], off
	v_lshl_add_u64 v[28:29], v[28:29], 0, s[30:31]
	v_exp_f32_e32 v108, v108
	v_add_f32_e32 v27, v27, v106
	v_exp_f32_e32 v109, v109
	ds_read_b128 v[218:221], v2
	ds_read_b128 v[214:217], v2 offset:512
	ds_read_b128 v[210:213], v2 offset:2048
	v_mfma_f32_32x32x16_bf16 v[50:65], v[82:85], v[240:243], v[50:65]
	s_add_u32 m0, s40, 0x9000
	v_add_f32_e32 v27, v27, v107
	v_exp_f32_e32 v110, v110
	global_load_lds_dwordx4 v[24:25], off
	v_lshl_add_u64 v[24:25], v[24:25], 0, s[30:31]
	v_add_f32_e32 v27, v27, v108
	v_exp_f32_e32 v111, v111
	v_add_f32_e32 v27, v27, v109
	ds_read_b128 v[206:209], v2 offset:2560
	ds_read_b128 v[202:205], v2 offset:4096
	ds_read_b128 v[198:201], v2 offset:4608
	v_mfma_f32_32x32x16_bf16 v[34:49], v[90:93], v[118:121], v[34:49]
	s_add_u32 m0, s43, 0x9000
	v_exp_f32_e32 v112, v112
	v_add_f32_e32 v27, v27, v110
	global_load_lds_dwordx4 v[30:31], off
	v_lshl_add_u64 v[30:31], v[30:31], 0, s[12:13]
	v_exp_f32_e32 v113, v113
	v_add_f32_e32 v27, v27, v111
	v_add_f32_e32 v27, v27, v112
	ds_read_b128 v[194:197], v2 offset:6144
	ds_read_b128 v[190:193], v2 offset:6656
	ds_read_b128 v[186:189], v2 offset:8192
	v_mfma_f32_32x32x16_bf16 v[50:65], v[90:93], v[244:247], v[50:65]
	v_add_f32_e32 v27, v27, v113
	v_cvt_pk_bf16_f32 v106, v106, v107
	v_cvt_pk_bf16_f32 v107, v108, v109
	v_cvt_pk_bf16_f32 v108, v110, v111
	v_cvt_pk_bf16_f32 v109, v112, v113
	v_add_f32_e32 v236, v236, v27
	ds_read_b128 v[182:185], v2 offset:8704
	ds_read_b128 v[178:181], v2 offset:10240
	ds_read_b128 v[174:177], v2 offset:10752
	v_mfma_f32_32x32x16_bf16 v[34:49], v[98:101], v[122:125], v[34:49]
	v_max3_f32 v19, v142, v143, v144
	v_max3_f32 v26, v145, v146, v147
	v_max3_f32 v19, v19, v148, v149
	v_max3_f32 v26, v26, v150, v151
	v_mfma_f32_32x32x16_bf16 v[50:65], v[98:101], v[248:251], v[50:65]
	v_max3_f32 v19, v19, v152, v153
	v_max3_f32 v26, v26, v154, v155
	v_max3_f32 v19, v19, v156, v157
	v_max3_f32 v26, v26, v158, v159
	v_mfma_f32_32x32x16_bf16 v[34:49], v[106:109], v[126:129], v[34:49]
	v_max3_f32 v19, v19, v160, v161
	v_max3_f32 v26, v26, v162, v163
	v_max3_f32 v19, v19, v164, v165
	v_max3_f32 v26, v26, v166, v167
	v_mfma_f32_32x32x16_bf16 v[50:65], v[106:109], v[20:23], v[50:65]
	v_max3_f32 v19, v19, v168, v169
	v_max3_f32 v26, v26, v170, v171
	v_max3_f32 v19, v19, v172, v173
	v_max_f32_e32 v19, v19, v26
	v_cmp_lt_f32_e32 vcc, s41, v19
	s_cbranch_vccz .Lmy_nors_9
	s_nop 15
	s_nop 15
	v_mov_b32_e32 v26, v19
	s_nop 1
	v_permlane32_swap_b32_e32 v19, v26
	v_max_f32_e32 v19, v19, v26
	v_max_f32_e32 v19, v19, v19
	v_max_f32_e32 v90, 0, v19
	v_exp_f32_e64 v91, -v90
	v_add_f32_e32 v239, v239, v90
	v_xor_b32_e32 v66, 0x80000000, v239
	v_mov_b32_e32 v67, v66
	v_mov_b32_e32 v68, v66
	v_mov_b32_e32 v69, v66
	v_mov_b32_e32 v70, v66
	v_mov_b32_e32 v71, v66
	v_mov_b32_e32 v72, v66
	v_mov_b32_e32 v73, v66
	v_mov_b32_e32 v74, v66
	v_mov_b32_e32 v75, v66
	v_mov_b32_e32 v76, v66
	v_mov_b32_e32 v77, v66
	v_mov_b32_e32 v78, v66
	v_mov_b32_e32 v79, v66
	v_mov_b32_e32 v80, v66
	v_mov_b32_e32 v81, v66
	v_sub_f32_e32 v142, v142, v90
	v_sub_f32_e32 v143, v143, v90
	v_sub_f32_e32 v144, v144, v90
	v_sub_f32_e32 v145, v145, v90
	v_sub_f32_e32 v146, v146, v90
	v_sub_f32_e32 v147, v147, v90
	v_sub_f32_e32 v148, v148, v90
	v_sub_f32_e32 v149, v149, v90
	v_sub_f32_e32 v150, v150, v90
	v_sub_f32_e32 v151, v151, v90
	v_sub_f32_e32 v152, v152, v90
	v_sub_f32_e32 v153, v153, v90
	v_sub_f32_e32 v154, v154, v90
	v_sub_f32_e32 v155, v155, v90
	v_sub_f32_e32 v156, v156, v90
	v_sub_f32_e32 v157, v157, v90
	v_sub_f32_e32 v158, v158, v90
	v_sub_f32_e32 v159, v159, v90
	v_sub_f32_e32 v160, v160, v90
	v_sub_f32_e32 v161, v161, v90
	v_sub_f32_e32 v162, v162, v90
	v_sub_f32_e32 v163, v163, v90
	v_sub_f32_e32 v164, v164, v90
	v_sub_f32_e32 v165, v165, v90
	v_sub_f32_e32 v166, v166, v90
	v_sub_f32_e32 v167, v167, v90
	v_sub_f32_e32 v168, v168, v90
	v_sub_f32_e32 v169, v169, v90
	v_sub_f32_e32 v170, v170, v90
	v_sub_f32_e32 v171, v171, v90
	v_sub_f32_e32 v172, v172, v90
	v_sub_f32_e32 v173, v173, v90
	v_mul_f32_e32 v236, v236, v91
	s_mov_b64 s[96:97], exec
	s_and_b64 exec, exec, s[8:9]
	ds_write_b32 v235, v91
	s_mov_b64 exec, s[96:97]
	v_lshl_add_u32 v2, v228, 4, s47
	ds_read_b128 v[94:97], v2 offset:0
	s_waitcnt lgkmcnt(0)
	v_mul_f32_e32 v34, v34, v94
	v_mul_f32_e32 v50, v50, v94
	v_mul_f32_e32 v35, v35, v95
	v_mul_f32_e32 v51, v51, v95
	v_mul_f32_e32 v36, v36, v96
	v_mul_f32_e32 v52, v52, v96
	v_mul_f32_e32 v37, v37, v97
	v_mul_f32_e32 v53, v53, v97
	ds_read_b128 v[94:97], v2 offset:32
	s_waitcnt lgkmcnt(0)
	v_mul_f32_e32 v38, v38, v94
	v_mul_f32_e32 v54, v54, v94
	v_mul_f32_e32 v39, v39, v95
	v_mul_f32_e32 v55, v55, v95
	v_mul_f32_e32 v40, v40, v96
	v_mul_f32_e32 v56, v56, v96
	v_mul_f32_e32 v41, v41, v97
	v_mul_f32_e32 v57, v57, v97
	ds_read_b128 v[94:97], v2 offset:64
	s_waitcnt lgkmcnt(0)
	v_mul_f32_e32 v42, v42, v94
	v_mul_f32_e32 v58, v58, v94
	v_mul_f32_e32 v43, v43, v95
	v_mul_f32_e32 v59, v59, v95
	v_mul_f32_e32 v44, v44, v96
	v_mul_f32_e32 v60, v60, v96
	v_mul_f32_e32 v45, v45, v97
	v_mul_f32_e32 v61, v61, v97
	ds_read_b128 v[94:97], v2 offset:96
	s_waitcnt lgkmcnt(0)
	v_mul_f32_e32 v46, v46, v94
	v_mul_f32_e32 v62, v62, v94
	v_mul_f32_e32 v47, v47, v95
	v_mul_f32_e32 v63, v63, v95
	v_mul_f32_e32 v48, v48, v96
	v_mul_f32_e32 v64, v64, v96
	v_mul_f32_e32 v49, v49, v97
	v_mul_f32_e32 v65, v65, v97

.Lmy_tf_13:
	s_waitcnt lgkmcnt(0)
	v_mov_b32_e32 v2, v237
	v_mfma_f32_32x32x16_bf16 v[142:157], v[218:221], v[4:7], v[66:81]
	v_exp_f32_e32 v82, v82
	v_exp_f32_e32 v83, v83
	v_exp_f32_e32 v84, v84
	v_add_f32_e32 v27, v82, v83
	v_exp_f32_e32 v85, v85
	ds_read_b64_tr_b16 v[114:115], v2 offset:49152
	ds_read_b64_tr_b16 v[116:117], v2 offset:49664
	ds_read_b64_tr_b16 v[118:119], v2 offset:50176
	ds_read_b64_tr_b16 v[120:121], v2 offset:50688
	v_mfma_f32_32x32x16_bf16 v[158:173], v[214:217], v[4:7], v[66:81]
	v_exp_f32_e32 v86, v86
	v_add_f32_e32 v27, v27, v84
	v_exp_f32_e32 v87, v87
	v_add_f32_e32 v27, v27, v85
	v_exp_f32_e32 v88, v88
	ds_read_b64_tr_b16 v[122:123], v2 offset:51200
	ds_read_b64_tr_b16 v[124:125], v2 offset:51712
	ds_read_b64_tr_b16 v[126:127], v2 offset:52224
	ds_read_b64_tr_b16 v[128:129], v2 offset:52736
	v_mfma_f32_32x32x16_bf16 v[142:157], v[210:213], v[8:11], v[142:157]
	v_add_f32_e32 v27, v27, v86
	v_exp_f32_e32 v89, v89
	v_add_f32_e32 v27, v27, v87
	v_add_f32_e32 v27, v27, v88
	v_add_f32_e32 v27, v27, v89
	ds_read_b64_tr_b16 v[240:241], v2 offset:53248
	ds_read_b64_tr_b16 v[242:243], v2 offset:53760
	ds_read_b64_tr_b16 v[244:245], v2 offset:54272
	ds_read_b64_tr_b16 v[246:247], v2 offset:54784
	v_mfma_f32_32x32x16_bf16 v[158:173], v[206:209], v[8:11], v[158:173]
	v_cvt_pk_bf16_f32 v82, v82, v83
	v_cvt_pk_bf16_f32 v83, v84, v85
	v_cvt_pk_bf16_f32 v84, v86, v87
	v_cvt_pk_bf16_f32 v85, v88, v89
	ds_read_b64_tr_b16 v[248:249], v2 offset:55296
	ds_read_b64_tr_b16 v[250:251], v2 offset:55808
	ds_read_b64_tr_b16 v[20:21], v2 offset:56320
	ds_read_b64_tr_b16 v[22:23], v2 offset:56832
	v_mfma_f32_32x32x16_bf16 v[142:157], v[202:205], v[12:15], v[142:157]
	v_exp_f32_e32 v90, v90
	v_exp_f32_e32 v91, v91
	v_exp_f32_e32 v92, v92
	v_add_f32_e32 v27, v27, v90
	v_exp_f32_e32 v93, v93
	v_mfma_f32_32x32x16_bf16 v[158:173], v[198:201], v[12:15], v[158:173]
	v_add_f32_e32 v27, v27, v91
	v_exp_f32_e32 v94, v94
	v_add_f32_e32 v27, v27, v92
	v_exp_f32_e32 v95, v95
	v_add_f32_e32 v27, v27, v93
	v_mfma_f32_32x32x16_bf16 v[142:157], v[194:197], v[130:133], v[142:157]
	v_exp_f32_e32 v96, v96
	v_add_f32_e32 v27, v27, v94
	v_exp_f32_e32 v97, v97
	v_add_f32_e32 v27, v27, v95
	v_add_f32_e32 v27, v27, v96
	v_mfma_f32_32x32x16_bf16 v[158:173], v[190:193], v[130:133], v[158:173]
	v_add_f32_e32 v27, v27, v97
	v_cvt_pk_bf16_f32 v90, v90, v91
	v_cvt_pk_bf16_f32 v91, v92, v93
	v_cvt_pk_bf16_f32 v92, v94, v95
	v_cvt_pk_bf16_f32 v93, v96, v97
	v_mfma_f32_32x32x16_bf16 v[142:157], v[186:189], v[134:137], v[142:157]
	v_exp_f32_e32 v98, v98
	v_exp_f32_e32 v99, v99
	v_exp_f32_e32 v100, v100
	v_add_f32_e32 v27, v27, v98
	v_exp_f32_e32 v101, v101
	v_mfma_f32_32x32x16_bf16 v[158:173], v[182:185], v[134:137], v[158:173]
	v_add_f32_e32 v27, v27, v99
	v_exp_f32_e32 v102, v102
	v_add_f32_e32 v27, v27, v100
	v_exp_f32_e32 v103, v103
	v_add_f32_e32 v27, v27, v101
	v_mfma_f32_32x32x16_bf16 v[142:157], v[178:181], v[138:141], v[142:157]
	v_exp_f32_e32 v104, v104
	v_add_f32_e32 v27, v27, v102
	v_exp_f32_e32 v105, v105
	v_add_f32_e32 v27, v27, v103
	v_add_f32_e32 v27, v27, v104
	v_mfma_f32_32x32x16_bf16 v[158:173], v[174:177], v[138:141], v[158:173]
	v_add_f32_e32 v27, v27, v105
	v_cvt_pk_bf16_f32 v98, v98, v99
	v_cvt_pk_bf16_f32 v99, v100, v101
	v_cvt_pk_bf16_f32 v100, v102, v103
	v_cvt_pk_bf16_f32 v101, v104, v105
	s_waitcnt vmcnt(3)
	s_barrier
	s_waitcnt lgkmcnt(0)
	v_add_u32_e32 v2, 0x6000, v238
	v_mfma_f32_32x32x16_bf16 v[34:49], v[82:85], v[114:117], v[34:49]
	s_add_u32 m0, s57, 0x6000
	v_exp_f32_e32 v106, v106
	v_exp_f32_e32 v107, v107
	global_load_lds_dwordx4 v[28:29], off
	v_lshl_add_u64 v[28:29], v[28:29], 0, s[30:31]
	v_exp_f32_e32 v108, v108
	v_add_f32_e32 v27, v27, v106
	v_exp_f32_e32 v109, v109
	s_cmp_gt_u32 s71, 1
	s_cbranch_scc0 .Lmy_nok_16
	ds_read_b128 v[218:221], v2
	ds_read_b128 v[214:217], v2 offset:512
	ds_read_b128 v[210:213], v2 offset:2048
	ds_read_b128 v[206:209], v2 offset:2560
	ds_read_b128 v[202:205], v2 offset:4096
	ds_read_b128 v[198:201], v2 offset:4608
	ds_read_b128 v[194:197], v2 offset:6144
	ds_read_b128 v[190:193], v2 offset:6656
	ds_read_b128 v[186:189], v2 offset:8192
	ds_read_b128 v[182:185], v2 offset:8704
	ds_read_b128 v[178:181], v2 offset:10240
	ds_read_b128 v[174:177], v2 offset:10752

.Lmy_tf_18:
	s_waitcnt lgkmcnt(0)
	v_add_u32_e32 v2, 0x2000, v237
	v_mfma_f32_32x32x16_bf16 v[82:97], v[218:221], v[4:7], v[66:81]
	v_exp_f32_e32 v142, v142
	v_exp_f32_e32 v143, v143
	v_exp_f32_e32 v144, v144
	v_add_f32_e32 v27, v142, v143
	v_exp_f32_e32 v145, v145
	ds_read_b64_tr_b16 v[114:115], v2 offset:49152
	ds_read_b64_tr_b16 v[116:117], v2 offset:49664
	ds_read_b64_tr_b16 v[118:119], v2 offset:50176
	ds_read_b64_tr_b16 v[120:121], v2 offset:50688
	v_mfma_f32_32x32x16_bf16 v[98:113], v[214:217], v[4:7], v[66:81]
	v_exp_f32_e32 v146, v146
	v_add_f32_e32 v27, v27, v144
	v_exp_f32_e32 v147, v147
	v_add_f32_e32 v27, v27, v145
	v_exp_f32_e32 v148, v148
	ds_read_b64_tr_b16 v[122:123], v2 offset:51200
	ds_read_b64_tr_b16 v[124:125], v2 offset:51712
	ds_read_b64_tr_b16 v[126:127], v2 offset:52224
	ds_read_b64_tr_b16 v[128:129], v2 offset:52736
	v_mfma_f32_32x32x16_bf16 v[82:97], v[210:213], v[8:11], v[82:97]
	v_add_f32_e32 v27, v27, v146
	v_exp_f32_e32 v149, v149
	v_add_f32_e32 v27, v27, v147
	v_add_f32_e32 v27, v27, v148
	v_add_f32_e32 v27, v27, v149
	ds_read_b64_tr_b16 v[240:241], v2 offset:53248
	ds_read_b64_tr_b16 v[242:243], v2 offset:53760
	ds_read_b64_tr_b16 v[244:245], v2 offset:54272
	ds_read_b64_tr_b16 v[246:247], v2 offset:54784
	v_mfma_f32_32x32x16_bf16 v[98:113], v[206:209], v[8:11], v[98:113]
	v_cvt_pk_bf16_f32 v142, v142, v143
	v_cvt_pk_bf16_f32 v143, v144, v145
	v_cvt_pk_bf16_f32 v144, v146, v147
	v_cvt_pk_bf16_f32 v145, v148, v149
	ds_read_b64_tr_b16 v[248:249], v2 offset:55296
	ds_read_b64_tr_b16 v[250:251], v2 offset:55808
	ds_read_b64_tr_b16 v[20:21], v2 offset:56320
	ds_read_b64_tr_b16 v[22:23], v2 offset:56832
	v_mfma_f32_32x32x16_bf16 v[82:97], v[202:205], v[12:15], v[82:97]
	v_exp_f32_e32 v150, v150
	v_exp_f32_e32 v151, v151
	v_exp_f32_e32 v152, v152
	v_add_f32_e32 v27, v27, v150
	v_exp_f32_e32 v153, v153
	v_mfma_f32_32x32x16_bf16 v[98:113], v[198:201], v[12:15], v[98:113]
	v_add_f32_e32 v27, v27, v151
	v_exp_f32_e32 v154, v154
	v_add_f32_e32 v27, v27, v152
	v_exp_f32_e32 v155, v155
	v_add_f32_e32 v27, v27, v153
	v_mfma_f32_32x32x16_bf16 v[82:97], v[194:197], v[130:133], v[82:97]
	v_exp_f32_e32 v156, v156
	v_add_f32_e32 v27, v27, v154
	v_exp_f32_e32 v157, v157
	v_add_f32_e32 v27, v27, v155
	v_add_f32_e32 v27, v27, v156
	v_mfma_f32_32x32x16_bf16 v[98:113], v[190:193], v[130:133], v[98:113]
	v_add_f32_e32 v27, v27, v157
	v_cvt_pk_bf16_f32 v150, v150, v151
	v_cvt_pk_bf16_f32 v151, v152, v153
	v_cvt_pk_bf16_f32 v152, v154, v155
	v_cvt_pk_bf16_f32 v153, v156, v157
	v_mfma_f32_32x32x16_bf16 v[82:97], v[186:189], v[134:137], v[82:97]
	v_exp_f32_e32 v158, v158
	v_exp_f32_e32 v159, v159
	v_exp_f32_e32 v160, v160
	v_add_f32_e32 v27, v27, v158
	v_exp_f32_e32 v161, v161
	v_mfma_f32_32x32x16_bf16 v[98:113], v[182:185], v[134:137], v[98:113]
	v_add_f32_e32 v27, v27, v159
	v_exp_f32_e32 v162, v162
	v_add_f32_e32 v27, v27, v160
	v_exp_f32_e32 v163, v163
	v_add_f32_e32 v27, v27, v161
	v_mfma_f32_32x32x16_bf16 v[82:97], v[178:181], v[138:141], v[82:97]
	v_exp_f32_e32 v164, v164
	v_add_f32_e32 v27, v27, v162
	v_exp_f32_e32 v165, v165
	v_add_f32_e32 v27, v27, v163
	v_add_f32_e32 v27, v27, v164
	v_mfma_f32_32x32x16_bf16 v[98:113], v[174:177], v[138:141], v[98:113]
	v_add_f32_e32 v27, v27, v165
	v_cvt_pk_bf16_f32 v158, v158, v159
	v_cvt_pk_bf16_f32 v159, v160, v161
	v_cvt_pk_bf16_f32 v160, v162, v163
	v_cvt_pk_bf16_f32 v161, v164, v165
	s_waitcnt vmcnt(1)
	s_barrier
	s_waitcnt lgkmcnt(0)
	v_add_u32_e32 v2, 0x9000, v238
	v_mfma_f32_32x32x16_bf16 v[34:49], v[142:145], v[114:117], v[34:49]
	v_exp_f32_e32 v166, v166
	v_exp_f32_e32 v167, v167
	v_exp_f32_e32 v168, v168
	v_add_f32_e32 v27, v27, v166
	v_exp_f32_e32 v169, v169
	s_cmp_gt_u32 s71, 2
	s_cbranch_scc0 .Lmy_nok_21
	ds_read_b128 v[218:221], v2
	ds_read_b128 v[214:217], v2 offset:512
	ds_read_b128 v[210:213], v2 offset:2048
	ds_read_b128 v[206:209], v2 offset:2560
	ds_read_b128 v[202:205], v2 offset:4096
	ds_read_b128 v[198:201], v2 offset:4608
	ds_read_b128 v[194:197], v2 offset:6144
	ds_read_b128 v[190:193], v2 offset:6656
	ds_read_b128 v[186:189], v2 offset:8192
	ds_read_b128 v[182:185], v2 offset:8704
	ds_read_b128 v[178:181], v2 offset:10240
	ds_read_b128 v[174:177], v2 offset:10752

.Lmy_tf_23:
	s_waitcnt lgkmcnt(0)
	v_add_u32_e32 v2, 0x4000, v237
	v_mfma_f32_32x32x16_bf16 v[142:157], v[218:221], v[4:7], v[66:81]
	v_exp_f32_e32 v82, v82
	v_exp_f32_e32 v83, v83
	v_exp_f32_e32 v84, v84
	v_add_f32_e32 v27, v82, v83
	v_exp_f32_e32 v85, v85
	ds_read_b64_tr_b16 v[114:115], v2 offset:49152
	ds_read_b64_tr_b16 v[116:117], v2 offset:49664
	ds_read_b64_tr_b16 v[118:119], v2 offset:50176
	ds_read_b64_tr_b16 v[120:121], v2 offset:50688
	v_mfma_f32_32x32x16_bf16 v[158:173], v[214:217], v[4:7], v[66:81]
	v_exp_f32_e32 v86, v86
	v_add_f32_e32 v27, v27, v84
	v_exp_f32_e32 v87, v87
	v_add_f32_e32 v27, v27, v85
	v_exp_f32_e32 v88, v88
	ds_read_b64_tr_b16 v[122:123], v2 offset:51200
	ds_read_b64_tr_b16 v[124:125], v2 offset:51712
	ds_read_b64_tr_b16 v[126:127], v2 offset:52224
	ds_read_b64_tr_b16 v[128:129], v2 offset:52736
	v_mfma_f32_32x32x16_bf16 v[142:157], v[210:213], v[8:11], v[142:157]
	v_add_f32_e32 v27, v27, v86
	v_exp_f32_e32 v89, v89
	v_add_f32_e32 v27, v27, v87
	v_add_f32_e32 v27, v27, v88
	v_add_f32_e32 v27, v27, v89
	ds_read_b64_tr_b16 v[240:241], v2 offset:53248
	ds_read_b64_tr_b16 v[242:243], v2 offset:53760
	ds_read_b64_tr_b16 v[244:245], v2 offset:54272
	ds_read_b64_tr_b16 v[246:247], v2 offset:54784
	v_mfma_f32_32x32x16_bf16 v[158:173], v[206:209], v[8:11], v[158:173]
	v_cvt_pk_bf16_f32 v82, v82, v83
	v_cvt_pk_bf16_f32 v83, v84, v85
	v_cvt_pk_bf16_f32 v84, v86, v87
	v_cvt_pk_bf16_f32 v85, v88, v89
	ds_read_b64_tr_b16 v[248:249], v2 offset:55296
	ds_read_b64_tr_b16 v[250:251], v2 offset:55808
	ds_read_b64_tr_b16 v[20:21], v2 offset:56320
	ds_read_b64_tr_b16 v[22:23], v2 offset:56832
	v_mfma_f32_32x32x16_bf16 v[142:157], v[202:205], v[12:15], v[142:157]
	v_exp_f32_e32 v90, v90
	v_exp_f32_e32 v91, v91
	v_exp_f32_e32 v92, v92
	v_add_f32_e32 v27, v27, v90
	v_exp_f32_e32 v93, v93
	v_mfma_f32_32x32x16_bf16 v[158:173], v[198:201], v[12:15], v[158:173]
	v_add_f32_e32 v27, v27, v91
	v_exp_f32_e32 v94, v94
	v_add_f32_e32 v27, v27, v92
	v_exp_f32_e32 v95, v95
	v_add_f32_e32 v27, v27, v93
	v_mfma_f32_32x32x16_bf16 v[142:157], v[194:197], v[130:133], v[142:157]
	v_exp_f32_e32 v96, v96
	v_add_f32_e32 v27, v27, v94
	v_exp_f32_e32 v97, v97
	v_add_f32_e32 v27, v27, v95
	v_add_f32_e32 v27, v27, v96
	v_mfma_f32_32x32x16_bf16 v[158:173], v[190:193], v[130:133], v[158:173]
	v_add_f32_e32 v27, v27, v97
	v_cvt_pk_bf16_f32 v90, v90, v91
	v_cvt_pk_bf16_f32 v91, v92, v93
	v_cvt_pk_bf16_f32 v92, v94, v95
	v_cvt_pk_bf16_f32 v93, v96, v97
	v_mfma_f32_32x32x16_bf16 v[142:157], v[186:189], v[134:137], v[142:157]
	v_exp_f32_e32 v98, v98
	v_exp_f32_e32 v99, v99
	v_exp_f32_e32 v100, v100
	v_add_f32_e32 v27, v27, v98
	v_exp_f32_e32 v101, v101
	v_mfma_f32_32x32x16_bf16 v[158:173], v[182:185], v[134:137], v[158:173]
	v_add_f32_e32 v27, v27, v99
	v_exp_f32_e32 v102, v102
	v_add_f32_e32 v27, v27, v100
	v_exp_f32_e32 v103, v103
	v_add_f32_e32 v27, v27, v101
	v_mfma_f32_32x32x16_bf16 v[142:157], v[178:181], v[138:141], v[142:157]
	v_exp_f32_e32 v104, v104
	v_add_f32_e32 v27, v27, v102
	v_exp_f32_e32 v105, v105
	v_add_f32_e32 v27, v27, v103
	v_add_f32_e32 v27, v27, v104
	v_mfma_f32_32x32x16_bf16 v[158:173], v[174:177], v[138:141], v[158:173]
	v_add_f32_e32 v27, v27, v105
	v_cvt_pk_bf16_f32 v98, v98, v99
	v_cvt_pk_bf16_f32 v99, v100, v101
	v_cvt_pk_bf16_f32 v100, v102, v103
	v_cvt_pk_bf16_f32 v101, v104, v105
	s_waitcnt vmcnt(0)
	s_barrier
	s_waitcnt lgkmcnt(0)
	v_mov_b32_e32 v2, v238
	v_mfma_f32_32x32x16_bf16 v[34:49], v[82:85], v[114:117], v[34:49]
	v_exp_f32_e32 v106, v106
	v_exp_f32_e32 v107, v107
	v_exp_f32_e32 v108, v108
	v_add_f32_e32 v27, v27, v106
	v_exp_f32_e32 v109, v109
	s_cmp_gt_u32 s71, 3
	s_cbranch_scc0 .Lmy_nok_26
	ds_read_b128 v[218:221], v2
	ds_read_b128 v[214:217], v2 offset:512
	ds_read_b128 v[210:213], v2 offset:2048
	ds_read_b128 v[206:209], v2 offset:2560
	ds_read_b128 v[202:205], v2 offset:4096
	ds_read_b128 v[198:201], v2 offset:4608
	ds_read_b128 v[194:197], v2 offset:6144
	ds_read_b128 v[190:193], v2 offset:6656
	ds_read_b128 v[186:189], v2 offset:8192
	ds_read_b128 v[182:185], v2 offset:8704
	ds_read_b128 v[178:181], v2 offset:10240
	ds_read_b128 v[174:177], v2 offset:10752

.Lmy_B_entry:
	s_mov_b32 s30, 0x20000
	s_mov_b32 s31, 0
	s_mov_b32 s12, 0x1000
	s_mov_b32 s13, 0
	s_lshr_b32 s71, s24, 1
	s_lshr_b32 s79, s25, 2
	s_add_i32 s79, s79, -1
	s_mov_b32 s0, 0x80000
	s_mov_b32 s1, 0
	v_lshl_add_u64 v[24:25], v[16:17], 0, s[0:1]
	s_mov_b32 s0, 0x60000
	v_lshl_add_u64 v[28:29], v[224:225], 0, s[0:1]
	s_mov_b32 s0, 0x4000
	v_lshl_add_u64 v[30:31], v[222:223], 0, s[0:1]
	s_waitcnt lgkmcnt(0)
	v_mfma_f32_32x32x16_bf16 v[82:97], v[218:221], v[4:7], v[66:81]
	v_mfma_f32_32x32x16_bf16 v[98:113], v[214:217], v[4:7], v[66:81]
	v_mfma_f32_32x32x16_bf16 v[82:97], v[210:213], v[8:11], v[82:97]
	v_mfma_f32_32x32x16_bf16 v[98:113], v[206:209], v[8:11], v[98:113]
	v_mfma_f32_32x32x16_bf16 v[82:97], v[202:205], v[12:15], v[82:97]
	v_mfma_f32_32x32x16_bf16 v[98:113], v[198:201], v[12:15], v[98:113]
	v_mfma_f32_32x32x16_bf16 v[82:97], v[194:197], v[130:133], v[82:97]
	v_mfma_f32_32x32x16_bf16 v[98:113], v[190:193], v[130:133], v[98:113]
	v_mfma_f32_32x32x16_bf16 v[82:97], v[186:189], v[134:137], v[82:97]
	v_mfma_f32_32x32x16_bf16 v[98:113], v[182:185], v[134:137], v[98:113]
	v_mfma_f32_32x32x16_bf16 v[82:97], v[178:181], v[138:141], v[82:97]
	v_mfma_f32_32x32x16_bf16 v[98:113], v[174:177], v[138:141], v[98:113]
	v_add_u32_e32 v2, 0x3000, v238
	ds_read_b128 v[218:221], v2
	ds_read_b128 v[214:217], v2 offset:512
	ds_read_b128 v[210:213], v2 offset:2048
	ds_read_b128 v[206:209], v2 offset:2560
	ds_read_b128 v[202:205], v2 offset:4096
	ds_read_b128 v[198:201], v2 offset:4608
	ds_read_b128 v[194:197], v2 offset:6144
	ds_read_b128 v[190:193], v2 offset:6656
	ds_read_b128 v[186:189], v2 offset:8192
	ds_read_b128 v[182:185], v2 offset:8704
	ds_read_b128 v[178:181], v2 offset:10240
	ds_read_b128 v[174:177], v2 offset:10752
	s_nop 7
	v_max3_f32 v19, v82, v83, v84
	v_max3_f32 v26, v85, v86, v87
	v_max3_f32 v19, v19, v88, v89
	v_max3_f32 v26, v26, v90, v91
	v_max3_f32 v19, v19, v92, v93
	v_max3_f32 v26, v26, v94, v95
	v_max3_f32 v19, v19, v96, v97
	v_max3_f32 v26, v26, v98, v99
	v_max3_f32 v19, v19, v100, v101
	v_max3_f32 v26, v26, v102, v103
	v_max3_f32 v19, v19, v104, v105
	v_max3_f32 v26, v26, v106, v107
	v_max3_f32 v19, v19, v108, v109
	v_max3_f32 v26, v26, v110, v111
	v_max3_f32 v19, v19, v112, v113
	v_max_f32_e32 v19, v19, v26
	v_mov_b32_e32 v26, v19
	s_nop 1
	v_permlane32_swap_b32_e32 v19, v26
	v_max_f32_e32 v19, v19, v26
	v_max_f32_e32 v19, v19, v19
	v_mov_b32_e32 v239, v19
	v_xor_b32_e32 v66, 0x80000000, v19
	v_mov_b32_e32 v67, v66
	v_mov_b32_e32 v68, v66
	v_mov_b32_e32 v69, v66
	v_mov_b32_e32 v70, v66
	v_mov_b32_e32 v71, v66
	v_mov_b32_e32 v72, v66
	v_mov_b32_e32 v73, v66
	v_mov_b32_e32 v74, v66
	v_mov_b32_e32 v75, v66
	v_mov_b32_e32 v76, v66
	v_mov_b32_e32 v77, v66
	v_mov_b32_e32 v78, v66
	v_mov_b32_e32 v79, v66
	v_mov_b32_e32 v80, v66
	v_mov_b32_e32 v81, v66
	v_sub_f32_e32 v82, v82, v19
	v_sub_f32_e32 v83, v83, v19
	v_sub_f32_e32 v84, v84, v19
	v_sub_f32_e32 v85, v85, v19
	v_sub_f32_e32 v86, v86, v19
	v_sub_f32_e32 v87, v87, v19
	v_sub_f32_e32 v88, v88, v19
	v_sub_f32_e32 v89, v89, v19
	v_sub_f32_e32 v90, v90, v19
	v_sub_f32_e32 v91, v91, v19
	v_sub_f32_e32 v92, v92, v19
	v_sub_f32_e32 v93, v93, v19
	v_sub_f32_e32 v94, v94, v19
	v_sub_f32_e32 v95, v95, v19
	v_sub_f32_e32 v96, v96, v19
	v_sub_f32_e32 v97, v97, v19
	v_sub_f32_e32 v98, v98, v19
	v_sub_f32_e32 v99, v99, v19
	v_sub_f32_e32 v100, v100, v19
	v_sub_f32_e32 v101, v101, v19
	v_sub_f32_e32 v102, v102, v19
	v_sub_f32_e32 v103, v103, v19
	v_sub_f32_e32 v104, v104, v19
	v_sub_f32_e32 v105, v105, v19
	v_sub_f32_e32 v106, v106, v19
	v_sub_f32_e32 v107, v107, v19
	v_sub_f32_e32 v108, v108, v19
	v_sub_f32_e32 v109, v109, v19
	v_sub_f32_e32 v110, v110, v19
	v_sub_f32_e32 v111, v111, v19
	v_sub_f32_e32 v112, v112, v19
	v_sub_f32_e32 v113, v113, v19
	s_cmp_lt_i32 s79, 1
	s_cbranch_scc1 .Lmy_B_tail
	s_waitcnt lgkmcnt(0)
	v_mov_b32_e32 v2, v237
	v_mfma_f32_32x32x16_bf16 v[142:157], v[218:221], v[4:7], v[66:81]
	v_exp_f32_e32 v82, v82
	v_exp_f32_e32 v83, v83
	v_exp_f32_e32 v84, v84
	v_add_f32_e32 v27, v82, v83
	v_exp_f32_e32 v85, v85
	ds_read_b64_tr_b16 v[114:115], v2 offset:49152
	ds_read_b64_tr_b16 v[116:117], v2 offset:49664
	ds_read_b64_tr_b16 v[118:119], v2 offset:50176
	ds_read_b64_tr_b16 v[120:121], v2 offset:50688
	v_mfma_f32_32x32x16_bf16 v[158:173], v[214:217], v[4:7], v[66:81]
	v_exp_f32_e32 v86, v86
	v_add_f32_e32 v27, v27, v84
	v_exp_f32_e32 v87, v87
	v_add_f32_e32 v27, v27, v85
	v_exp_f32_e32 v88, v88
	ds_read_b64_tr_b16 v[122:123], v2 offset:51200
	ds_read_b64_tr_b16 v[124:125], v2 offset:51712
	ds_read_b64_tr_b16 v[126:127], v2 offset:52224
	ds_read_b64_tr_b16 v[128:129], v2 offset:52736
	v_mfma_f32_32x32x16_bf16 v[142:157], v[210:213], v[8:11], v[142:157]
	v_add_f32_e32 v27, v27, v86
	v_exp_f32_e32 v89, v89
	v_add_f32_e32 v27, v27, v87
	v_add_f32_e32 v27, v27, v88
	v_add_f32_e32 v27, v27, v89
	ds_read_b64_tr_b16 v[240:241], v2 offset:53248
	ds_read_b64_tr_b16 v[242:243], v2 offset:53760
	ds_read_b64_tr_b16 v[244:245], v2 offset:54272
	ds_read_b64_tr_b16 v[246:247], v2 offset:54784
	v_mfma_f32_32x32x16_bf16 v[158:173], v[206:209], v[8:11], v[158:173]
	v_cvt_pk_bf16_f32 v82, v82, v83
	v_cvt_pk_bf16_f32 v83, v84, v85
	v_cvt_pk_bf16_f32 v84, v86, v87
	v_cvt_pk_bf16_f32 v85, v88, v89
	ds_read_b64_tr_b16 v[248:249], v2 offset:55296
	ds_read_b64_tr_b16 v[250:251], v2 offset:55808
	ds_read_b64_tr_b16 v[20:21], v2 offset:56320
	ds_read_b64_tr_b16 v[22:23], v2 offset:56832
	v_mfma_f32_32x32x16_bf16 v[142:157], v[202:205], v[12:15], v[142:157]
	v_exp_f32_e32 v90, v90
	v_exp_f32_e32 v91, v91
	v_exp_f32_e32 v92, v92
	v_add_f32_e32 v27, v27, v90
	v_exp_f32_e32 v93, v93
	v_mfma_f32_32x32x16_bf16 v[158:173], v[198:201], v[12:15], v[158:173]
	v_add_f32_e32 v27, v27, v91
	v_exp_f32_e32 v94, v94
	v_add_f32_e32 v27, v27, v92
	v_exp_f32_e32 v95, v95
	v_add_f32_e32 v27, v27, v93
	v_mfma_f32_32x32x16_bf16 v[142:157], v[194:197], v[130:133], v[142:157]
	v_exp_f32_e32 v96, v96
	v_add_f32_e32 v27, v27, v94
	v_exp_f32_e32 v97, v97
	v_add_f32_e32 v27, v27, v95
	v_add_f32_e32 v27, v27, v96
	v_mfma_f32_32x32x16_bf16 v[158:173], v[190:193], v[130:133], v[158:173]
	v_add_f32_e32 v27, v27, v97
	v_cvt_pk_bf16_f32 v90, v90, v91
	v_cvt_pk_bf16_f32 v91, v92, v93
	v_cvt_pk_bf16_f32 v92, v94, v95
	v_cvt_pk_bf16_f32 v93, v96, v97
	v_mfma_f32_32x32x16_bf16 v[142:157], v[186:189], v[134:137], v[142:157]
	v_exp_f32_e32 v98, v98
	v_exp_f32_e32 v99, v99
	v_exp_f32_e32 v100, v100
	v_add_f32_e32 v27, v27, v98
	v_exp_f32_e32 v101, v101
	v_mfma_f32_32x32x16_bf16 v[158:173], v[182:185], v[134:137], v[158:173]
	v_add_f32_e32 v27, v27, v99
	v_exp_f32_e32 v102, v102
	v_add_f32_e32 v27, v27, v100
	v_exp_f32_e32 v103, v103
	v_add_f32_e32 v27, v27, v101
	v_mfma_f32_32x32x16_bf16 v[142:157], v[178:181], v[138:141], v[142:157]
	v_exp_f32_e32 v104, v104
	v_add_f32_e32 v27, v27, v102
	v_exp_f32_e32 v105, v105
	v_add_f32_e32 v27, v27, v103
	v_add_f32_e32 v27, v27, v104
	v_mfma_f32_32x32x16_bf16 v[158:173], v[174:177], v[138:141], v[158:173]
	v_add_f32_e32 v27, v27, v105
	v_cvt_pk_bf16_f32 v98, v98, v99
	v_cvt_pk_bf16_f32 v99, v100, v101
	v_cvt_pk_bf16_f32 v100, v102, v103
	v_cvt_pk_bf16_f32 v101, v104, v105
	s_waitcnt vmcnt(2)
	s_barrier
	s_waitcnt lgkmcnt(0)
	v_add_u32_e32 v2, 0x6000, v238
	v_mfma_f32_32x32x16_bf16 v[34:49], v[82:85], v[114:117], v[34:49]
	s_add_u32 m0, s57, 0x6000
	v_exp_f32_e32 v106, v106
	v_exp_f32_e32 v107, v107
	global_load_lds_dwordx4 v[28:29], off
	v_lshl_add_u64 v[28:29], v[28:29], 0, s[30:31]
	v_exp_f32_e32 v108, v108
	v_add_f32_e32 v27, v27, v106
	v_exp_f32_e32 v109, v109
	ds_read_b128 v[218:221], v2
	ds_read_b128 v[214:217], v2 offset:512
	ds_read_b128 v[210:213], v2 offset:2048
	v_mfma_f32_32x32x16_bf16 v[50:65], v[82:85], v[240:243], v[50:65]
	s_add_u32 m0, s40, 0x0
	v_add_f32_e32 v27, v27, v107
	v_exp_f32_e32 v110, v110
	global_load_lds_dwordx4 v[24:25], off
	v_lshl_add_u64 v[24:25], v[24:25], 0, s[30:31]
	v_add_f32_e32 v27, v27, v108
	v_exp_f32_e32 v111, v111
	v_add_f32_e32 v27, v27, v109
	ds_read_b128 v[206:209], v2 offset:2560
	ds_read_b128 v[202:205], v2 offset:4096
	ds_read_b128 v[198:201], v2 offset:4608
	v_mfma_f32_32x32x16_bf16 v[34:49], v[90:93], v[118:121], v[34:49]
	s_add_u32 m0, s40, 0x3000
	v_exp_f32_e32 v112, v112
	v_add_f32_e32 v27, v27, v110
	global_load_lds_dwordx4 v[24:25], off
	v_lshl_add_u64 v[24:25], v[24:25], 0, s[30:31]
	v_exp_f32_e32 v113, v113
	v_add_f32_e32 v27, v27, v111
	v_add_f32_e32 v27, v27, v112
	ds_read_b128 v[194:197], v2 offset:6144
	ds_read_b128 v[190:193], v2 offset:6656
	ds_read_b128 v[186:189], v2 offset:8192
	v_mfma_f32_32x32x16_bf16 v[50:65], v[90:93], v[244:247], v[50:65]
	v_add_f32_e32 v27, v27, v113
	v_cvt_pk_bf16_f32 v106, v106, v107
	v_cvt_pk_bf16_f32 v107, v108, v109
	v_cvt_pk_bf16_f32 v108, v110, v111
	v_cvt_pk_bf16_f32 v109, v112, v113
	v_add_f32_e32 v236, v236, v27
	ds_read_b128 v[182:185], v2 offset:8704
	ds_read_b128 v[178:181], v2 offset:10240
	ds_read_b128 v[174:177], v2 offset:10752
	v_mfma_f32_32x32x16_bf16 v[34:49], v[98:101], v[122:125], v[34:49]
	v_max3_f32 v19, v142, v143, v144
	v_max3_f32 v26, v145, v146, v147
	v_max3_f32 v19, v19, v148, v149
	v_max3_f32 v26, v26, v150, v151
	v_mfma_f32_32x32x16_bf16 v[50:65], v[98:101], v[248:251], v[50:65]
	v_max3_f32 v19, v19, v152, v153
	v_max3_f32 v26, v26, v154, v155
	v_max3_f32 v19, v19, v156, v157
	v_max3_f32 v26, v26, v158, v159
	v_mfma_f32_32x32x16_bf16 v[34:49], v[106:109], v[126:129], v[34:49]
	v_max3_f32 v19, v19, v160, v161
	v_max3_f32 v26, v26, v162, v163
	v_max3_f32 v19, v19, v164, v165
	v_max3_f32 v26, v26, v166, v167
	v_mfma_f32_32x32x16_bf16 v[50:65], v[106:109], v[20:23], v[50:65]
	v_max3_f32 v19, v19, v168, v169
	v_max3_f32 v26, v26, v170, v171
	v_max3_f32 v19, v19, v172, v173
	v_max_f32_e32 v19, v19, v26
	v_cmp_lt_f32_e32 vcc, s41, v19
	s_cbranch_vccz .Lmy_nors_31
	s_nop 15
	s_nop 15
	v_mov_b32_e32 v26, v19
	s_nop 1
	v_permlane32_swap_b32_e32 v19, v26
	v_max_f32_e32 v19, v19, v26
	v_max_f32_e32 v19, v19, v19
	v_max_f32_e32 v90, 0, v19
	v_exp_f32_e64 v91, -v90
	v_add_f32_e32 v239, v239, v90
	v_xor_b32_e32 v66, 0x80000000, v239
	v_mov_b32_e32 v67, v66
	v_mov_b32_e32 v68, v66
	v_mov_b32_e32 v69, v66
	v_mov_b32_e32 v70, v66
	v_mov_b32_e32 v71, v66
	v_mov_b32_e32 v72, v66
	v_mov_b32_e32 v73, v66
	v_mov_b32_e32 v74, v66
	v_mov_b32_e32 v75, v66
	v_mov_b32_e32 v76, v66
	v_mov_b32_e32 v77, v66
	v_mov_b32_e32 v78, v66
	v_mov_b32_e32 v79, v66
	v_mov_b32_e32 v80, v66
	v_mov_b32_e32 v81, v66
	v_sub_f32_e32 v142, v142, v90
	v_sub_f32_e32 v143, v143, v90
	v_sub_f32_e32 v144, v144, v90
	v_sub_f32_e32 v145, v145, v90
	v_sub_f32_e32 v146, v146, v90
	v_sub_f32_e32 v147, v147, v90
	v_sub_f32_e32 v148, v148, v90
	v_sub_f32_e32 v149, v149, v90
	v_sub_f32_e32 v150, v150, v90
	v_sub_f32_e32 v151, v151, v90
	v_sub_f32_e32 v152, v152, v90
	v_sub_f32_e32 v153, v153, v90
	v_sub_f32_e32 v154, v154, v90
	v_sub_f32_e32 v155, v155, v90
	v_sub_f32_e32 v156, v156, v90
	v_sub_f32_e32 v157, v157, v90
	v_sub_f32_e32 v158, v158, v90
	v_sub_f32_e32 v159, v159, v90
	v_sub_f32_e32 v160, v160, v90
	v_sub_f32_e32 v161, v161, v90
	v_sub_f32_e32 v162, v162, v90
	v_sub_f32_e32 v163, v163, v90
	v_sub_f32_e32 v164, v164, v90
	v_sub_f32_e32 v165, v165, v90
	v_sub_f32_e32 v166, v166, v90
	v_sub_f32_e32 v167, v167, v90
	v_sub_f32_e32 v168, v168, v90
	v_sub_f32_e32 v169, v169, v90
	v_sub_f32_e32 v170, v170, v90
	v_sub_f32_e32 v171, v171, v90
	v_sub_f32_e32 v172, v172, v90
	v_sub_f32_e32 v173, v173, v90
	v_mul_f32_e32 v236, v236, v91
	s_mov_b64 s[96:97], exec
	s_and_b64 exec, exec, s[8:9]
	ds_write_b32 v235, v91
	s_mov_b64 exec, s[96:97]
	v_lshl_add_u32 v2, v228, 4, s47
	ds_read_b128 v[94:97], v2 offset:0
	s_waitcnt lgkmcnt(0)
	v_mul_f32_e32 v34, v34, v94
	v_mul_f32_e32 v50, v50, v94
	v_mul_f32_e32 v35, v35, v95
	v_mul_f32_e32 v51, v51, v95
	v_mul_f32_e32 v36, v36, v96
	v_mul_f32_e32 v52, v52, v96
	v_mul_f32_e32 v37, v37, v97
	v_mul_f32_e32 v53, v53, v97
	ds_read_b128 v[94:97], v2 offset:32
	s_waitcnt lgkmcnt(0)
	v_mul_f32_e32 v38, v38, v94
	v_mul_f32_e32 v54, v54, v94
	v_mul_f32_e32 v39, v39, v95
	v_mul_f32_e32 v55, v55, v95
	v_mul_f32_e32 v40, v40, v96
	v_mul_f32_e32 v56, v56, v96
	v_mul_f32_e32 v41, v41, v97
	v_mul_f32_e32 v57, v57, v97
	ds_read_b128 v[94:97], v2 offset:64
	s_waitcnt lgkmcnt(0)
	v_mul_f32_e32 v42, v42, v94
	v_mul_f32_e32 v58, v58, v94
	v_mul_f32_e32 v43, v43, v95
	v_mul_f32_e32 v59, v59, v95
	v_mul_f32_e32 v44, v44, v96
	v_mul_f32_e32 v60, v60, v96
	v_mul_f32_e32 v45, v45, v97
	v_mul_f32_e32 v61, v61, v97
	ds_read_b128 v[94:97], v2 offset:96
	s_waitcnt lgkmcnt(0)
	v_mul_f32_e32 v46, v46, v94
	v_mul_f32_e32 v62, v62, v94
	v_mul_f32_e32 v47, v47, v95
	v_mul_f32_e32 v63, v63, v95
	v_mul_f32_e32 v48, v48, v96
	v_mul_f32_e32 v64, v64, v96
	v_mul_f32_e32 v49, v49, v97
	v_mul_f32_e32 v65, v65, v97
.Lmy_nors_31:
	s_waitcnt lgkmcnt(0)
	v_add_u32_e32 v2, 0x2000, v237
	v_mfma_f32_32x32x16_bf16 v[82:97], v[218:221], v[4:7], v[66:81]
	v_exp_f32_e32 v142, v142
	v_exp_f32_e32 v143, v143
	v_exp_f32_e32 v144, v144
	v_add_f32_e32 v27, v142, v143
	v_exp_f32_e32 v145, v145
	ds_read_b64_tr_b16 v[114:115], v2 offset:49152
	ds_read_b64_tr_b16 v[116:117], v2 offset:49664
	ds_read_b64_tr_b16 v[118:119], v2 offset:50176
	ds_read_b64_tr_b16 v[120:121], v2 offset:50688
	v_mfma_f32_32x32x16_bf16 v[98:113], v[214:217], v[4:7], v[66:81]
	v_exp_f32_e32 v146, v146
	v_add_f32_e32 v27, v27, v144
	v_exp_f32_e32 v147, v147
	v_add_f32_e32 v27, v27, v145
	v_exp_f32_e32 v148, v148
	ds_read_b64_tr_b16 v[122:123], v2 offset:51200
	ds_read_b64_tr_b16 v[124:125], v2 offset:51712
	ds_read_b64_tr_b16 v[126:127], v2 offset:52224
	ds_read_b64_tr_b16 v[128:129], v2 offset:52736
	v_mfma_f32_32x32x16_bf16 v[82:97], v[210:213], v[8:11], v[82:97]
	v_add_f32_e32 v27, v27, v146
	v_exp_f32_e32 v149, v149
	v_add_f32_e32 v27, v27, v147
	v_add_f32_e32 v27, v27, v148
	v_add_f32_e32 v27, v27, v149
	ds_read_b64_tr_b16 v[240:241], v2 offset:53248
	ds_read_b64_tr_b16 v[242:243], v2 offset:53760
	ds_read_b64_tr_b16 v[244:245], v2 offset:54272
	ds_read_b64_tr_b16 v[246:247], v2 offset:54784
	v_mfma_f32_32x32x16_bf16 v[98:113], v[206:209], v[8:11], v[98:113]
	v_cvt_pk_bf16_f32 v142, v142, v143
	v_cvt_pk_bf16_f32 v143, v144, v145
	v_cvt_pk_bf16_f32 v144, v146, v147
	v_cvt_pk_bf16_f32 v145, v148, v149
	ds_read_b64_tr_b16 v[248:249], v2 offset:55296
	ds_read_b64_tr_b16 v[250:251], v2 offset:55808
	ds_read_b64_tr_b16 v[20:21], v2 offset:56320
	ds_read_b64_tr_b16 v[22:23], v2 offset:56832
	v_mfma_f32_32x32x16_bf16 v[82:97], v[202:205], v[12:15], v[82:97]
	v_exp_f32_e32 v150, v150
	v_exp_f32_e32 v151, v151
	v_exp_f32_e32 v152, v152
	v_add_f32_e32 v27, v27, v150
	v_exp_f32_e32 v153, v153
	v_mfma_f32_32x32x16_bf16 v[98:113], v[198:201], v[12:15], v[98:113]
	v_add_f32_e32 v27, v27, v151
	v_exp_f32_e32 v154, v154
	v_add_f32_e32 v27, v27, v152
	v_exp_f32_e32 v155, v155
	v_add_f32_e32 v27, v27, v153
	v_mfma_f32_32x32x16_bf16 v[82:97], v[194:197], v[130:133], v[82:97]
	v_exp_f32_e32 v156, v156
	v_add_f32_e32 v27, v27, v154
	v_exp_f32_e32 v157, v157
	v_add_f32_e32 v27, v27, v155
	v_add_f32_e32 v27, v27, v156
	v_mfma_f32_32x32x16_bf16 v[98:113], v[190:193], v[130:133], v[98:113]
	v_add_f32_e32 v27, v27, v157
	v_cvt_pk_bf16_f32 v150, v150, v151
	v_cvt_pk_bf16_f32 v151, v152, v153
	v_cvt_pk_bf16_f32 v152, v154, v155
	v_cvt_pk_bf16_f32 v153, v156, v157
	v_mfma_f32_32x32x16_bf16 v[82:97], v[186:189], v[134:137], v[82:97]
	v_exp_f32_e32 v158, v158
	v_exp_f32_e32 v159, v159
	v_exp_f32_e32 v160, v160
	v_add_f32_e32 v27, v27, v158
	v_exp_f32_e32 v161, v161
	v_mfma_f32_32x32x16_bf16 v[98:113], v[182:185], v[134:137], v[98:113]
	v_add_f32_e32 v27, v27, v159
	v_exp_f32_e32 v162, v162
	v_add_f32_e32 v27, v27, v160
	v_exp_f32_e32 v163, v163
	v_add_f32_e32 v27, v27, v161
	v_mfma_f32_32x32x16_bf16 v[82:97], v[178:181], v[138:141], v[82:97]
	v_exp_f32_e32 v164, v164
	v_add_f32_e32 v27, v27, v162
	v_exp_f32_e32 v165, v165
	v_add_f32_e32 v27, v27, v163
	v_add_f32_e32 v27, v27, v164
	v_mfma_f32_32x32x16_bf16 v[98:113], v[174:177], v[138:141], v[98:113]
	v_add_f32_e32 v27, v27, v165
	v_cvt_pk_bf16_f32 v158, v158, v159
	v_cvt_pk_bf16_f32 v159, v160, v161
	v_cvt_pk_bf16_f32 v160, v162, v163
	v_cvt_pk_bf16_f32 v161, v164, v165
	s_waitcnt vmcnt(4)
	s_barrier
	s_waitcnt lgkmcnt(0)
	v_add_u32_e32 v2, 0x9000, v238
	v_mfma_f32_32x32x16_bf16 v[34:49], v[142:145], v[114:117], v[34:49]
	s_add_u32 m0, s57, 0x0
	v_exp_f32_e32 v166, v166
	v_exp_f32_e32 v167, v167
	global_load_lds_dwordx4 v[28:29], off
	v_lshl_add_u64 v[28:29], v[28:29], 0, s[30:31]
	v_exp_f32_e32 v168, v168
	v_add_f32_e32 v27, v27, v166
	v_exp_f32_e32 v169, v169
	ds_read_b128 v[218:221], v2
	ds_read_b128 v[214:217], v2 offset:512
	ds_read_b128 v[210:213], v2 offset:2048
	v_mfma_f32_32x32x16_bf16 v[50:65], v[142:145], v[240:243], v[50:65]
	s_add_u32 m0, s40, 0x6000
	v_add_f32_e32 v27, v27, v167
	v_exp_f32_e32 v170, v170
	global_load_lds_dwordx4 v[24:25], off
	v_lshl_add_u64 v[24:25], v[24:25], 0, s[30:31]
	v_add_f32_e32 v27, v27, v168
	v_exp_f32_e32 v171, v171
	v_add_f32_e32 v27, v27, v169
	ds_read_b128 v[206:209], v2 offset:2560
	ds_read_b128 v[202:205], v2 offset:4096
	ds_read_b128 v[198:201], v2 offset:4608
	v_mfma_f32_32x32x16_bf16 v[34:49], v[150:153], v[118:121], v[34:49]
	v_exp_f32_e32 v172, v172
	v_add_f32_e32 v27, v27, v170
	v_exp_f32_e32 v173, v173
	v_add_f32_e32 v27, v27, v171
	v_add_f32_e32 v27, v27, v172
	ds_read_b128 v[194:197], v2 offset:6144
	ds_read_b128 v[190:193], v2 offset:6656
	ds_read_b128 v[186:189], v2 offset:8192
	v_mfma_f32_32x32x16_bf16 v[50:65], v[150:153], v[244:247], v[50:65]
	v_add_f32_e32 v27, v27, v173
	v_cvt_pk_bf16_f32 v166, v166, v167
	v_cvt_pk_bf16_f32 v167, v168, v169
	v_cvt_pk_bf16_f32 v168, v170, v171
	v_cvt_pk_bf16_f32 v169, v172, v173
	v_add_f32_e32 v236, v236, v27
	ds_read_b128 v[182:185], v2 offset:8704
	ds_read_b128 v[178:181], v2 offset:10240
	ds_read_b128 v[174:177], v2 offset:10752
	v_mfma_f32_32x32x16_bf16 v[34:49], v[158:161], v[122:125], v[34:49]
	v_max3_f32 v19, v82, v83, v84
	v_max3_f32 v26, v85, v86, v87
	v_max3_f32 v19, v19, v88, v89
	v_max3_f32 v26, v26, v90, v91
	v_mfma_f32_32x32x16_bf16 v[50:65], v[158:161], v[248:251], v[50:65]
	v_max3_f32 v19, v19, v92, v93
	v_max3_f32 v26, v26, v94, v95
	v_max3_f32 v19, v19, v96, v97
	v_max3_f32 v26, v26, v98, v99
	v_mfma_f32_32x32x16_bf16 v[34:49], v[166:169], v[126:129], v[34:49]
	v_max3_f32 v19, v19, v100, v101
	v_max3_f32 v26, v26, v102, v103
	v_max3_f32 v19, v19, v104, v105
	v_max3_f32 v26, v26, v106, v107
	v_mfma_f32_32x32x16_bf16 v[50:65], v[166:169], v[20:23], v[50:65]
	v_max3_f32 v19, v19, v108, v109
	v_max3_f32 v26, v26, v110, v111
	v_max3_f32 v19, v19, v112, v113
	v_max_f32_e32 v19, v19, v26
	v_cmp_lt_f32_e32 vcc, s41, v19
	s_cbranch_vccz .Lmy_nors_32
	s_nop 15
	s_nop 15
	v_mov_b32_e32 v26, v19
	s_nop 1
	v_permlane32_swap_b32_e32 v19, v26
	v_max_f32_e32 v19, v19, v26
	v_max_f32_e32 v19, v19, v19
	v_max_f32_e32 v150, 0, v19
	v_exp_f32_e64 v151, -v150
	v_add_f32_e32 v239, v239, v150
	v_xor_b32_e32 v66, 0x80000000, v239
	v_mov_b32_e32 v67, v66
	v_mov_b32_e32 v68, v66
	v_mov_b32_e32 v69, v66
	v_mov_b32_e32 v70, v66
	v_mov_b32_e32 v71, v66
	v_mov_b32_e32 v72, v66
	v_mov_b32_e32 v73, v66
	v_mov_b32_e32 v74, v66
	v_mov_b32_e32 v75, v66
	v_mov_b32_e32 v76, v66
	v_mov_b32_e32 v77, v66
	v_mov_b32_e32 v78, v66
	v_mov_b32_e32 v79, v66
	v_mov_b32_e32 v80, v66
	v_mov_b32_e32 v81, v66
	v_sub_f32_e32 v82, v82, v150
	v_sub_f32_e32 v83, v83, v150
	v_sub_f32_e32 v84, v84, v150
	v_sub_f32_e32 v85, v85, v150
	v_sub_f32_e32 v86, v86, v150
	v_sub_f32_e32 v87, v87, v150
	v_sub_f32_e32 v88, v88, v150
	v_sub_f32_e32 v89, v89, v150
	v_sub_f32_e32 v90, v90, v150
	v_sub_f32_e32 v91, v91, v150
	v_sub_f32_e32 v92, v92, v150
	v_sub_f32_e32 v93, v93, v150
	v_sub_f32_e32 v94, v94, v150
	v_sub_f32_e32 v95, v95, v150
	v_sub_f32_e32 v96, v96, v150
	v_sub_f32_e32 v97, v97, v150
	v_sub_f32_e32 v98, v98, v150
	v_sub_f32_e32 v99, v99, v150
	v_sub_f32_e32 v100, v100, v150
	v_sub_f32_e32 v101, v101, v150
	v_sub_f32_e32 v102, v102, v150
	v_sub_f32_e32 v103, v103, v150
	v_sub_f32_e32 v104, v104, v150
	v_sub_f32_e32 v105, v105, v150
	v_sub_f32_e32 v106, v106, v150
	v_sub_f32_e32 v107, v107, v150
	v_sub_f32_e32 v108, v108, v150
	v_sub_f32_e32 v109, v109, v150
	v_sub_f32_e32 v110, v110, v150
	v_sub_f32_e32 v111, v111, v150
	v_sub_f32_e32 v112, v112, v150
	v_sub_f32_e32 v113, v113, v150
	v_mul_f32_e32 v236, v236, v151
	s_mov_b64 s[96:97], exec
	s_and_b64 exec, exec, s[8:9]
	ds_write_b32 v235, v151
	s_mov_b64 exec, s[96:97]
	v_lshl_add_u32 v2, v228, 4, s47
	ds_read_b128 v[154:157], v2 offset:0
	s_waitcnt lgkmcnt(0)
	v_mul_f32_e32 v34, v34, v154
	v_mul_f32_e32 v50, v50, v154
	v_mul_f32_e32 v35, v35, v155
	v_mul_f32_e32 v51, v51, v155
	v_mul_f32_e32 v36, v36, v156
	v_mul_f32_e32 v52, v52, v156
	v_mul_f32_e32 v37, v37, v157
	v_mul_f32_e32 v53, v53, v157
	ds_read_b128 v[154:157], v2 offset:32
	s_waitcnt lgkmcnt(0)
	v_mul_f32_e32 v38, v38, v154
	v_mul_f32_e32 v54, v54, v154
	v_mul_f32_e32 v39, v39, v155
	v_mul_f32_e32 v55, v55, v155
	v_mul_f32_e32 v40, v40, v156
	v_mul_f32_e32 v56, v56, v156
	v_mul_f32_e32 v41, v41, v157
	v_mul_f32_e32 v57, v57, v157
	ds_read_b128 v[154:157], v2 offset:64
	s_waitcnt lgkmcnt(0)
	v_mul_f32_e32 v42, v42, v154
	v_mul_f32_e32 v58, v58, v154
	v_mul_f32_e32 v43, v43, v155
	v_mul_f32_e32 v59, v59, v155
	v_mul_f32_e32 v44, v44, v156
	v_mul_f32_e32 v60, v60, v156
	v_mul_f32_e32 v45, v45, v157
	v_mul_f32_e32 v61, v61, v157
	ds_read_b128 v[154:157], v2 offset:96
	s_waitcnt lgkmcnt(0)
	v_mul_f32_e32 v46, v46, v154
	v_mul_f32_e32 v62, v62, v154
	v_mul_f32_e32 v47, v47, v155
	v_mul_f32_e32 v63, v63, v155
	v_mul_f32_e32 v48, v48, v156
	v_mul_f32_e32 v64, v64, v156
	v_mul_f32_e32 v49, v49, v157
	v_mul_f32_e32 v65, v65, v157
.Lmy_nors_32:
	s_waitcnt lgkmcnt(0)
	v_add_u32_e32 v2, 0x4000, v237
	v_mfma_f32_32x32x16_bf16 v[142:157], v[218:221], v[4:7], v[66:81]
	v_exp_f32_e32 v82, v82
	v_exp_f32_e32 v83, v83
	v_exp_f32_e32 v84, v84
	v_add_f32_e32 v27, v82, v83
	v_exp_f32_e32 v85, v85
	ds_read_b64_tr_b16 v[114:115], v2 offset:49152
	ds_read_b64_tr_b16 v[116:117], v2 offset:49664
	ds_read_b64_tr_b16 v[118:119], v2 offset:50176
	ds_read_b64_tr_b16 v[120:121], v2 offset:50688
	v_mfma_f32_32x32x16_bf16 v[158:173], v[214:217], v[4:7], v[66:81]
	v_exp_f32_e32 v86, v86
	v_add_f32_e32 v27, v27, v84
	v_exp_f32_e32 v87, v87
	v_add_f32_e32 v27, v27, v85
	v_exp_f32_e32 v88, v88
	ds_read_b64_tr_b16 v[122:123], v2 offset:51200
	ds_read_b64_tr_b16 v[124:125], v2 offset:51712
	ds_read_b64_tr_b16 v[126:127], v2 offset:52224
	ds_read_b64_tr_b16 v[128:129], v2 offset:52736
	v_mfma_f32_32x32x16_bf16 v[142:157], v[210:213], v[8:11], v[142:157]
	v_add_f32_e32 v27, v27, v86
	v_exp_f32_e32 v89, v89
	v_add_f32_e32 v27, v27, v87
	v_add_f32_e32 v27, v27, v88
	v_add_f32_e32 v27, v27, v89
	ds_read_b64_tr_b16 v[240:241], v2 offset:53248
	ds_read_b64_tr_b16 v[242:243], v2 offset:53760
	ds_read_b64_tr_b16 v[244:245], v2 offset:54272
	ds_read_b64_tr_b16 v[246:247], v2 offset:54784
	v_mfma_f32_32x32x16_bf16 v[158:173], v[206:209], v[8:11], v[158:173]
	v_cvt_pk_bf16_f32 v82, v82, v83
	v_cvt_pk_bf16_f32 v83, v84, v85
	v_cvt_pk_bf16_f32 v84, v86, v87
	v_cvt_pk_bf16_f32 v85, v88, v89
	ds_read_b64_tr_b16 v[248:249], v2 offset:55296
	ds_read_b64_tr_b16 v[250:251], v2 offset:55808
	ds_read_b64_tr_b16 v[20:21], v2 offset:56320
	ds_read_b64_tr_b16 v[22:23], v2 offset:56832
	v_mfma_f32_32x32x16_bf16 v[142:157], v[202:205], v[12:15], v[142:157]
	v_exp_f32_e32 v90, v90
	v_exp_f32_e32 v91, v91
	v_exp_f32_e32 v92, v92
	v_add_f32_e32 v27, v27, v90
	v_exp_f32_e32 v93, v93
	v_mfma_f32_32x32x16_bf16 v[158:173], v[198:201], v[12:15], v[158:173]
	v_add_f32_e32 v27, v27, v91
	v_exp_f32_e32 v94, v94
	v_add_f32_e32 v27, v27, v92
	v_exp_f32_e32 v95, v95
	v_add_f32_e32 v27, v27, v93
	v_mfma_f32_32x32x16_bf16 v[142:157], v[194:197], v[130:133], v[142:157]
	v_exp_f32_e32 v96, v96
	v_add_f32_e32 v27, v27, v94
	v_exp_f32_e32 v97, v97
	v_add_f32_e32 v27, v27, v95
	v_add_f32_e32 v27, v27, v96
	v_mfma_f32_32x32x16_bf16 v[158:173], v[190:193], v[130:133], v[158:173]
	v_add_f32_e32 v27, v27, v97
	v_cvt_pk_bf16_f32 v90, v90, v91
	v_cvt_pk_bf16_f32 v91, v92, v93
	v_cvt_pk_bf16_f32 v92, v94, v95
	v_cvt_pk_bf16_f32 v93, v96, v97
	v_mfma_f32_32x32x16_bf16 v[142:157], v[186:189], v[134:137], v[142:157]
	v_exp_f32_e32 v98, v98
	v_exp_f32_e32 v99, v99
	v_exp_f32_e32 v100, v100
	v_add_f32_e32 v27, v27, v98
	v_exp_f32_e32 v101, v101
	v_mfma_f32_32x32x16_bf16 v[158:173], v[182:185], v[134:137], v[158:173]
	v_add_f32_e32 v27, v27, v99
	v_exp_f32_e32 v102, v102
	v_add_f32_e32 v27, v27, v100
	v_exp_f32_e32 v103, v103
	v_add_f32_e32 v27, v27, v101
	v_mfma_f32_32x32x16_bf16 v[142:157], v[178:181], v[138:141], v[142:157]
	v_exp_f32_e32 v104, v104
	v_add_f32_e32 v27, v27, v102
	v_exp_f32_e32 v105, v105
	v_add_f32_e32 v27, v27, v103
	v_add_f32_e32 v27, v27, v104
	v_mfma_f32_32x32x16_bf16 v[158:173], v[174:177], v[138:141], v[158:173]
	v_add_f32_e32 v27, v27, v105
	v_cvt_pk_bf16_f32 v98, v98, v99
	v_cvt_pk_bf16_f32 v99, v100, v101
	v_cvt_pk_bf16_f32 v100, v102, v103
	v_cvt_pk_bf16_f32 v101, v104, v105
	s_waitcnt vmcnt(3)
	s_barrier
	s_waitcnt lgkmcnt(0)
	v_mov_b32_e32 v2, v238
	v_mfma_f32_32x32x16_bf16 v[34:49], v[82:85], v[114:117], v[34:49]
	s_add_u32 m0, s57, 0x2000
	v_exp_f32_e32 v106, v106
	v_exp_f32_e32 v107, v107
	global_load_lds_dwordx4 v[28:29], off
	v_lshl_add_u64 v[28:29], v[28:29], 0, s[30:31]
	v_exp_f32_e32 v108, v108
	v_add_f32_e32 v27, v27, v106
	v_exp_f32_e32 v109, v109
	ds_read_b128 v[218:221], v2
	ds_read_b128 v[214:217], v2 offset:512
	ds_read_b128 v[210:213], v2 offset:2048
	v_mfma_f32_32x32x16_bf16 v[50:65], v[82:85], v[240:243], v[50:65]
	s_add_u32 m0, s40, 0x9000
	v_add_f32_e32 v27, v27, v107
	v_exp_f32_e32 v110, v110
	global_load_lds_dwordx4 v[24:25], off
	v_lshl_add_u64 v[24:25], v[24:25], 0, s[30:31]
	v_add_f32_e32 v27, v27, v108
	v_exp_f32_e32 v111, v111
	v_add_f32_e32 v27, v27, v109
	ds_read_b128 v[206:209], v2 offset:2560
	ds_read_b128 v[202:205], v2 offset:4096
	ds_read_b128 v[198:201], v2 offset:4608
	v_mfma_f32_32x32x16_bf16 v[34:49], v[90:93], v[118:121], v[34:49]
	v_exp_f32_e32 v112, v112
	v_add_f32_e32 v27, v27, v110
	v_exp_f32_e32 v113, v113
	v_add_f32_e32 v27, v27, v111
	v_add_f32_e32 v27, v27, v112
	ds_read_b128 v[194:197], v2 offset:6144
	ds_read_b128 v[190:193], v2 offset:6656
	ds_read_b128 v[186:189], v2 offset:8192
	v_mfma_f32_32x32x16_bf16 v[50:65], v[90:93], v[244:247], v[50:65]
	v_add_f32_e32 v27, v27, v113
	v_cvt_pk_bf16_f32 v106, v106, v107
	v_cvt_pk_bf16_f32 v107, v108, v109
	v_cvt_pk_bf16_f32 v108, v110, v111
	v_cvt_pk_bf16_f32 v109, v112, v113
	v_add_f32_e32 v236, v236, v27
	ds_read_b128 v[182:185], v2 offset:8704
	ds_read_b128 v[178:181], v2 offset:10240
	ds_read_b128 v[174:177], v2 offset:10752
	v_mfma_f32_32x32x16_bf16 v[34:49], v[98:101], v[122:125], v[34:49]
	v_max3_f32 v19, v142, v143, v144
	v_max3_f32 v26, v145, v146, v147
	v_max3_f32 v19, v19, v148, v149
	v_max3_f32 v26, v26, v150, v151
	v_mfma_f32_32x32x16_bf16 v[50:65], v[98:101], v[248:251], v[50:65]
	v_max3_f32 v19, v19, v152, v153
	v_max3_f32 v26, v26, v154, v155
	v_max3_f32 v19, v19, v156, v157
	v_max3_f32 v26, v26, v158, v159
	v_mfma_f32_32x32x16_bf16 v[34:49], v[106:109], v[126:129], v[34:49]
	v_max3_f32 v19, v19, v160, v161
	v_max3_f32 v26, v26, v162, v163
	v_max3_f32 v19, v19, v164, v165
	v_max3_f32 v26, v26, v166, v167
	v_mfma_f32_32x32x16_bf16 v[50:65], v[106:109], v[20:23], v[50:65]
	v_max3_f32 v19, v19, v168, v169
	v_max3_f32 v26, v26, v170, v171
	v_max3_f32 v19, v19, v172, v173
	v_max_f32_e32 v19, v19, v26
	v_cmp_lt_f32_e32 vcc, s41, v19
	s_cbranch_vccz .Lmy_nors_33
	s_nop 15
	s_nop 15
	v_mov_b32_e32 v26, v19
	s_nop 1
	v_permlane32_swap_b32_e32 v19, v26
	v_max_f32_e32 v19, v19, v26
	v_max_f32_e32 v19, v19, v19
	v_max_f32_e32 v90, 0, v19
	v_exp_f32_e64 v91, -v90
	v_add_f32_e32 v239, v239, v90
	v_xor_b32_e32 v66, 0x80000000, v239
	v_mov_b32_e32 v67, v66
	v_mov_b32_e32 v68, v66
	v_mov_b32_e32 v69, v66
	v_mov_b32_e32 v70, v66
	v_mov_b32_e32 v71, v66
	v_mov_b32_e32 v72, v66
	v_mov_b32_e32 v73, v66
	v_mov_b32_e32 v74, v66
	v_mov_b32_e32 v75, v66
	v_mov_b32_e32 v76, v66
	v_mov_b32_e32 v77, v66
	v_mov_b32_e32 v78, v66
	v_mov_b32_e32 v79, v66
	v_mov_b32_e32 v80, v66
	v_mov_b32_e32 v81, v66
	v_sub_f32_e32 v142, v142, v90
	v_sub_f32_e32 v143, v143, v90
	v_sub_f32_e32 v144, v144, v90
	v_sub_f32_e32 v145, v145, v90
	v_sub_f32_e32 v146, v146, v90
	v_sub_f32_e32 v147, v147, v90
	v_sub_f32_e32 v148, v148, v90
	v_sub_f32_e32 v149, v149, v90
	v_sub_f32_e32 v150, v150, v90
	v_sub_f32_e32 v151, v151, v90
	v_sub_f32_e32 v152, v152, v90
	v_sub_f32_e32 v153, v153, v90
	v_sub_f32_e32 v154, v154, v90
	v_sub_f32_e32 v155, v155, v90
	v_sub_f32_e32 v156, v156, v90
	v_sub_f32_e32 v157, v157, v90
	v_sub_f32_e32 v158, v158, v90
	v_sub_f32_e32 v159, v159, v90
	v_sub_f32_e32 v160, v160, v90
	v_sub_f32_e32 v161, v161, v90
	v_sub_f32_e32 v162, v162, v90
	v_sub_f32_e32 v163, v163, v90
	v_sub_f32_e32 v164, v164, v90
	v_sub_f32_e32 v165, v165, v90
	v_sub_f32_e32 v166, v166, v90
	v_sub_f32_e32 v167, v167, v90
	v_sub_f32_e32 v168, v168, v90
	v_sub_f32_e32 v169, v169, v90
	v_sub_f32_e32 v170, v170, v90
	v_sub_f32_e32 v171, v171, v90
	v_sub_f32_e32 v172, v172, v90
	v_sub_f32_e32 v173, v173, v90
	v_mul_f32_e32 v236, v236, v91
	s_mov_b64 s[96:97], exec
	s_and_b64 exec, exec, s[8:9]
	ds_write_b32 v235, v91
	s_mov_b64 exec, s[96:97]
	v_lshl_add_u32 v2, v228, 4, s47
	ds_read_b128 v[94:97], v2 offset:0
	s_waitcnt lgkmcnt(0)
	v_mul_f32_e32 v34, v34, v94
	v_mul_f32_e32 v50, v50, v94
	v_mul_f32_e32 v35, v35, v95
	v_mul_f32_e32 v51, v51, v95
	v_mul_f32_e32 v36, v36, v96
	v_mul_f32_e32 v52, v52, v96
	v_mul_f32_e32 v37, v37, v97
	v_mul_f32_e32 v53, v53, v97
	ds_read_b128 v[94:97], v2 offset:32
	s_waitcnt lgkmcnt(0)
	v_mul_f32_e32 v38, v38, v94
	v_mul_f32_e32 v54, v54, v94
	v_mul_f32_e32 v39, v39, v95
	v_mul_f32_e32 v55, v55, v95
	v_mul_f32_e32 v40, v40, v96
	v_mul_f32_e32 v56, v56, v96
	v_mul_f32_e32 v41, v41, v97
	v_mul_f32_e32 v57, v57, v97
	ds_read_b128 v[94:97], v2 offset:64
	s_waitcnt lgkmcnt(0)
	v_mul_f32_e32 v42, v42, v94
	v_mul_f32_e32 v58, v58, v94
	v_mul_f32_e32 v43, v43, v95
	v_mul_f32_e32 v59, v59, v95
	v_mul_f32_e32 v44, v44, v96
	v_mul_f32_e32 v60, v60, v96
	v_mul_f32_e32 v45, v45, v97
	v_mul_f32_e32 v61, v61, v97
	ds_read_b128 v[94:97], v2 offset:96
	s_waitcnt lgkmcnt(0)
	v_mul_f32_e32 v46, v46, v94
	v_mul_f32_e32 v62, v62, v94
	v_mul_f32_e32 v47, v47, v95
	v_mul_f32_e32 v63, v63, v95
	v_mul_f32_e32 v48, v48, v96
	v_mul_f32_e32 v64, v64, v96
	v_mul_f32_e32 v49, v49, v97
	v_mul_f32_e32 v65, v65, v97
.Lmy_nors_33:
	s_waitcnt lgkmcnt(0)
	v_add_u32_e32 v2, 0x6000, v237
	v_mfma_f32_32x32x16_bf16 v[82:97], v[218:221], v[4:7], v[66:81]
	v_exp_f32_e32 v142, v142
	v_exp_f32_e32 v143, v143
	v_exp_f32_e32 v144, v144
	v_add_f32_e32 v27, v142, v143
	v_exp_f32_e32 v145, v145
	ds_read_b64_tr_b16 v[114:115], v2 offset:49152
	ds_read_b64_tr_b16 v[116:117], v2 offset:49664
	ds_read_b64_tr_b16 v[118:119], v2 offset:50176
	ds_read_b64_tr_b16 v[120:121], v2 offset:50688
	v_mfma_f32_32x32x16_bf16 v[98:113], v[214:217], v[4:7], v[66:81]
	v_exp_f32_e32 v146, v146
	v_add_f32_e32 v27, v27, v144
	v_exp_f32_e32 v147, v147
	v_add_f32_e32 v27, v27, v145
	v_exp_f32_e32 v148, v148
	ds_read_b64_tr_b16 v[122:123], v2 offset:51200
	ds_read_b64_tr_b16 v[124:125], v2 offset:51712
	ds_read_b64_tr_b16 v[126:127], v2 offset:52224
	ds_read_b64_tr_b16 v[128:129], v2 offset:52736
	v_mfma_f32_32x32x16_bf16 v[82:97], v[210:213], v[8:11], v[82:97]
	v_add_f32_e32 v27, v27, v146
	v_exp_f32_e32 v149, v149
	v_add_f32_e32 v27, v27, v147
	v_add_f32_e32 v27, v27, v148
	v_add_f32_e32 v27, v27, v149
	ds_read_b64_tr_b16 v[240:241], v2 offset:53248
	ds_read_b64_tr_b16 v[242:243], v2 offset:53760
	ds_read_b64_tr_b16 v[244:245], v2 offset:54272
	ds_read_b64_tr_b16 v[246:247], v2 offset:54784
	v_mfma_f32_32x32x16_bf16 v[98:113], v[206:209], v[8:11], v[98:113]
	v_cvt_pk_bf16_f32 v142, v142, v143
	v_cvt_pk_bf16_f32 v143, v144, v145
	v_cvt_pk_bf16_f32 v144, v146, v147
	v_cvt_pk_bf16_f32 v145, v148, v149
	ds_read_b64_tr_b16 v[248:249], v2 offset:55296
	ds_read_b64_tr_b16 v[250:251], v2 offset:55808
	ds_read_b64_tr_b16 v[20:21], v2 offset:56320
	ds_read_b64_tr_b16 v[22:23], v2 offset:56832
	v_mfma_f32_32x32x16_bf16 v[82:97], v[202:205], v[12:15], v[82:97]
	v_exp_f32_e32 v150, v150
	v_exp_f32_e32 v151, v151
	v_exp_f32_e32 v152, v152
	v_add_f32_e32 v27, v27, v150
	v_exp_f32_e32 v153, v153
	v_mfma_f32_32x32x16_bf16 v[98:113], v[198:201], v[12:15], v[98:113]
	v_add_f32_e32 v27, v27, v151
	v_exp_f32_e32 v154, v154
	v_add_f32_e32 v27, v27, v152
	v_exp_f32_e32 v155, v155
	v_add_f32_e32 v27, v27, v153
	v_mfma_f32_32x32x16_bf16 v[82:97], v[194:197], v[130:133], v[82:97]
	v_exp_f32_e32 v156, v156
	v_add_f32_e32 v27, v27, v154
	v_exp_f32_e32 v157, v157
	v_add_f32_e32 v27, v27, v155
	v_add_f32_e32 v27, v27, v156
	v_mfma_f32_32x32x16_bf16 v[98:113], v[190:193], v[130:133], v[98:113]
	v_add_f32_e32 v27, v27, v157
	v_cvt_pk_bf16_f32 v150, v150, v151
	v_cvt_pk_bf16_f32 v151, v152, v153
	v_cvt_pk_bf16_f32 v152, v154, v155
	v_cvt_pk_bf16_f32 v153, v156, v157
	v_mfma_f32_32x32x16_bf16 v[82:97], v[186:189], v[134:137], v[82:97]
	v_exp_f32_e32 v158, v158
	v_exp_f32_e32 v159, v159
	v_exp_f32_e32 v160, v160
	v_add_f32_e32 v27, v27, v158
	v_exp_f32_e32 v161, v161
	v_mfma_f32_32x32x16_bf16 v[98:113], v[182:185], v[134:137], v[98:113]
	v_add_f32_e32 v27, v27, v159
	v_exp_f32_e32 v162, v162
	v_add_f32_e32 v27, v27, v160
	v_exp_f32_e32 v163, v163
	v_add_f32_e32 v27, v27, v161
	v_mfma_f32_32x32x16_bf16 v[82:97], v[178:181], v[138:141], v[82:97]
	v_exp_f32_e32 v164, v164
	v_add_f32_e32 v27, v27, v162
	v_exp_f32_e32 v165, v165
	v_add_f32_e32 v27, v27, v163
	v_add_f32_e32 v27, v27, v164
	v_mfma_f32_32x32x16_bf16 v[98:113], v[174:177], v[138:141], v[98:113]
	v_add_f32_e32 v27, v27, v165
	v_cvt_pk_bf16_f32 v158, v158, v159
	v_cvt_pk_bf16_f32 v159, v160, v161
	v_cvt_pk_bf16_f32 v160, v162, v163
	v_cvt_pk_bf16_f32 v161, v164, v165
	s_waitcnt vmcnt(4)
	s_barrier
	s_waitcnt lgkmcnt(0)
	v_add_u32_e32 v2, 0x3000, v238
	v_mfma_f32_32x32x16_bf16 v[34:49], v[142:145], v[114:117], v[34:49]
	s_add_u32 m0, s57, 0x4000
	v_exp_f32_e32 v166, v166
	v_exp_f32_e32 v167, v167
	global_load_lds_dwordx4 v[28:29], off
	v_lshl_add_u64 v[28:29], v[28:29], 0, s[30:31]
	v_exp_f32_e32 v168, v168
	v_add_f32_e32 v27, v27, v166
	v_exp_f32_e32 v169, v169
	ds_read_b128 v[218:221], v2
	ds_read_b128 v[214:217], v2 offset:512
	ds_read_b128 v[210:213], v2 offset:2048
	v_mfma_f32_32x32x16_bf16 v[50:65], v[142:145], v[240:243], v[50:65]
	s_cmp_eq_u32 s79, 1
	s_cbranch_scc1 .Lmy_gl_34
	s_add_u32 m0, s40, 0x0
	s_nop 0
	global_load_lds_dwordx4 v[24:25], off
	v_lshl_add_u64 v[24:25], v[24:25], 0, s[30:31]
.Lmy_gl_34:
	v_add_f32_e32 v27, v27, v167
	v_exp_f32_e32 v170, v170
	v_add_f32_e32 v27, v27, v168
	v_exp_f32_e32 v171, v171
	v_add_f32_e32 v27, v27, v169
	ds_read_b128 v[206:209], v2 offset:2560
	ds_read_b128 v[202:205], v2 offset:4096
	ds_read_b128 v[198:201], v2 offset:4608
	v_mfma_f32_32x32x16_bf16 v[34:49], v[150:153], v[118:121], v[34:49]
	v_exp_f32_e32 v172, v172
	v_add_f32_e32 v27, v27, v170
	v_exp_f32_e32 v173, v173
	v_add_f32_e32 v27, v27, v171
	v_add_f32_e32 v27, v27, v172
	ds_read_b128 v[194:197], v2 offset:6144
	ds_read_b128 v[190:193], v2 offset:6656
	ds_read_b128 v[186:189], v2 offset:8192
	v_mfma_f32_32x32x16_bf16 v[50:65], v[150:153], v[244:247], v[50:65]
	v_add_f32_e32 v27, v27, v173
	v_cvt_pk_bf16_f32 v166, v166, v167
	v_cvt_pk_bf16_f32 v167, v168, v169
	v_cvt_pk_bf16_f32 v168, v170, v171
	v_cvt_pk_bf16_f32 v169, v172, v173
	v_add_f32_e32 v236, v236, v27
	ds_read_b128 v[182:185], v2 offset:8704
	ds_read_b128 v[178:181], v2 offset:10240
	ds_read_b128 v[174:177], v2 offset:10752
	v_mfma_f32_32x32x16_bf16 v[34:49], v[158:161], v[122:125], v[34:49]
	v_max3_f32 v19, v82, v83, v84
	v_max3_f32 v26, v85, v86, v87
	v_max3_f32 v19, v19, v88, v89
	v_max3_f32 v26, v26, v90, v91
	v_mfma_f32_32x32x16_bf16 v[50:65], v[158:161], v[248:251], v[50:65]
	v_max3_f32 v19, v19, v92, v93
	v_max3_f32 v26, v26, v94, v95
	v_max3_f32 v19, v19, v96, v97
	v_max3_f32 v26, v26, v98, v99
	v_mfma_f32_32x32x16_bf16 v[34:49], v[166:169], v[126:129], v[34:49]
	v_max3_f32 v19, v19, v100, v101
	v_max3_f32 v26, v26, v102, v103
	v_max3_f32 v19, v19, v104, v105
	v_max3_f32 v26, v26, v106, v107
	v_mfma_f32_32x32x16_bf16 v[50:65], v[166:169], v[20:23], v[50:65]
	v_max3_f32 v19, v19, v108, v109
	v_max3_f32 v26, v26, v110, v111
	v_max3_f32 v19, v19, v112, v113
	v_max_f32_e32 v19, v19, v26
	v_cmp_lt_f32_e32 vcc, s41, v19
	s_cbranch_vccz .Lmy_nors_35
	s_nop 15
	s_nop 15
	v_mov_b32_e32 v26, v19
	s_nop 1
	v_permlane32_swap_b32_e32 v19, v26
	v_max_f32_e32 v19, v19, v26
	v_max_f32_e32 v19, v19, v19
	v_max_f32_e32 v150, 0, v19
	v_exp_f32_e64 v151, -v150
	v_add_f32_e32 v239, v239, v150
	v_xor_b32_e32 v66, 0x80000000, v239
	v_mov_b32_e32 v67, v66
	v_mov_b32_e32 v68, v66
	v_mov_b32_e32 v69, v66
	v_mov_b32_e32 v70, v66
	v_mov_b32_e32 v71, v66
	v_mov_b32_e32 v72, v66
	v_mov_b32_e32 v73, v66
	v_mov_b32_e32 v74, v66
	v_mov_b32_e32 v75, v66
	v_mov_b32_e32 v76, v66
	v_mov_b32_e32 v77, v66
	v_mov_b32_e32 v78, v66
	v_mov_b32_e32 v79, v66
	v_mov_b32_e32 v80, v66
	v_mov_b32_e32 v81, v66
	v_sub_f32_e32 v82, v82, v150
	v_sub_f32_e32 v83, v83, v150
	v_sub_f32_e32 v84, v84, v150
	v_sub_f32_e32 v85, v85, v150
	v_sub_f32_e32 v86, v86, v150
	v_sub_f32_e32 v87, v87, v150
	v_sub_f32_e32 v88, v88, v150
	v_sub_f32_e32 v89, v89, v150
	v_sub_f32_e32 v90, v90, v150
	v_sub_f32_e32 v91, v91, v150
	v_sub_f32_e32 v92, v92, v150
	v_sub_f32_e32 v93, v93, v150
	v_sub_f32_e32 v94, v94, v150
	v_sub_f32_e32 v95, v95, v150
	v_sub_f32_e32 v96, v96, v150
	v_sub_f32_e32 v97, v97, v150
	v_sub_f32_e32 v98, v98, v150
	v_sub_f32_e32 v99, v99, v150
	v_sub_f32_e32 v100, v100, v150
	v_sub_f32_e32 v101, v101, v150
	v_sub_f32_e32 v102, v102, v150
	v_sub_f32_e32 v103, v103, v150
	v_sub_f32_e32 v104, v104, v150
	v_sub_f32_e32 v105, v105, v150
	v_sub_f32_e32 v106, v106, v150
	v_sub_f32_e32 v107, v107, v150
	v_sub_f32_e32 v108, v108, v150
	v_sub_f32_e32 v109, v109, v150
	v_sub_f32_e32 v110, v110, v150
	v_sub_f32_e32 v111, v111, v150
	v_sub_f32_e32 v112, v112, v150
	v_sub_f32_e32 v113, v113, v150
	v_mul_f32_e32 v236, v236, v151
	s_mov_b64 s[96:97], exec
	s_and_b64 exec, exec, s[8:9]
	ds_write_b32 v235, v151
	s_mov_b64 exec, s[96:97]
	v_lshl_add_u32 v2, v228, 4, s47
	ds_read_b128 v[154:157], v2 offset:0
	s_waitcnt lgkmcnt(0)
	v_mul_f32_e32 v34, v34, v154
	v_mul_f32_e32 v50, v50, v154
	v_mul_f32_e32 v35, v35, v155
	v_mul_f32_e32 v51, v51, v155
	v_mul_f32_e32 v36, v36, v156
	v_mul_f32_e32 v52, v52, v156
	v_mul_f32_e32 v37, v37, v157
	v_mul_f32_e32 v53, v53, v157
	ds_read_b128 v[154:157], v2 offset:32
	s_waitcnt lgkmcnt(0)
	v_mul_f32_e32 v38, v38, v154
	v_mul_f32_e32 v54, v54, v154
	v_mul_f32_e32 v39, v39, v155
	v_mul_f32_e32 v55, v55, v155
	v_mul_f32_e32 v40, v40, v156
	v_mul_f32_e32 v56, v56, v156
	v_mul_f32_e32 v41, v41, v157
	v_mul_f32_e32 v57, v57, v157
	ds_read_b128 v[154:157], v2 offset:64
	s_waitcnt lgkmcnt(0)
	v_mul_f32_e32 v42, v42, v154
	v_mul_f32_e32 v58, v58, v154
	v_mul_f32_e32 v43, v43, v155
	v_mul_f32_e32 v59, v59, v155
	v_mul_f32_e32 v44, v44, v156
	v_mul_f32_e32 v60, v60, v156
	v_mul_f32_e32 v45, v45, v157
	v_mul_f32_e32 v61, v61, v157
	ds_read_b128 v[154:157], v2 offset:96
	s_waitcnt lgkmcnt(0)
	v_mul_f32_e32 v46, v46, v154
	v_mul_f32_e32 v62, v62, v154
	v_mul_f32_e32 v47, v47, v155
	v_mul_f32_e32 v63, v63, v155
	v_mul_f32_e32 v48, v48, v156
	v_mul_f32_e32 v64, v64, v156
	v_mul_f32_e32 v49, v49, v157
	v_mul_f32_e32 v65, v65, v157

.Lmy_B_loop:
	s_waitcnt lgkmcnt(0)
	v_mov_b32_e32 v2, v237
	v_mfma_f32_32x32x16_bf16 v[142:157], v[218:221], v[4:7], v[66:81]
	v_exp_f32_e32 v82, v82
	v_exp_f32_e32 v83, v83
	v_exp_f32_e32 v84, v84
	v_add_f32_e32 v27, v82, v83
	v_exp_f32_e32 v85, v85
	ds_read_b64_tr_b16 v[114:115], v2 offset:49152
	ds_read_b64_tr_b16 v[116:117], v2 offset:49664
	ds_read_b64_tr_b16 v[118:119], v2 offset:50176
	ds_read_b64_tr_b16 v[120:121], v2 offset:50688
	v_mfma_f32_32x32x16_bf16 v[158:173], v[214:217], v[4:7], v[66:81]
	v_exp_f32_e32 v86, v86
	v_add_f32_e32 v27, v27, v84
	v_exp_f32_e32 v87, v87
	v_add_f32_e32 v27, v27, v85
	v_exp_f32_e32 v88, v88
	ds_read_b64_tr_b16 v[122:123], v2 offset:51200
	ds_read_b64_tr_b16 v[124:125], v2 offset:51712
	ds_read_b64_tr_b16 v[126:127], v2 offset:52224
	ds_read_b64_tr_b16 v[128:129], v2 offset:52736
	v_mfma_f32_32x32x16_bf16 v[142:157], v[210:213], v[8:11], v[142:157]
	v_add_f32_e32 v27, v27, v86
	v_exp_f32_e32 v89, v89
	v_add_f32_e32 v27, v27, v87
	v_add_f32_e32 v27, v27, v88
	v_add_f32_e32 v27, v27, v89
	ds_read_b64_tr_b16 v[240:241], v2 offset:53248
	ds_read_b64_tr_b16 v[242:243], v2 offset:53760
	ds_read_b64_tr_b16 v[244:245], v2 offset:54272
	ds_read_b64_tr_b16 v[246:247], v2 offset:54784
	v_mfma_f32_32x32x16_bf16 v[158:173], v[206:209], v[8:11], v[158:173]
	v_cvt_pk_bf16_f32 v82, v82, v83
	v_cvt_pk_bf16_f32 v83, v84, v85
	v_cvt_pk_bf16_f32 v84, v86, v87
	v_cvt_pk_bf16_f32 v85, v88, v89
	ds_read_b64_tr_b16 v[248:249], v2 offset:55296
	ds_read_b64_tr_b16 v[250:251], v2 offset:55808
	ds_read_b64_tr_b16 v[20:21], v2 offset:56320
	ds_read_b64_tr_b16 v[22:23], v2 offset:56832
	v_mfma_f32_32x32x16_bf16 v[142:157], v[202:205], v[12:15], v[142:157]
	v_exp_f32_e32 v90, v90
	v_exp_f32_e32 v91, v91
	v_exp_f32_e32 v92, v92
	v_add_f32_e32 v27, v27, v90
	v_exp_f32_e32 v93, v93
	v_mfma_f32_32x32x16_bf16 v[158:173], v[198:201], v[12:15], v[158:173]
	v_add_f32_e32 v27, v27, v91
	v_exp_f32_e32 v94, v94
	v_add_f32_e32 v27, v27, v92
	v_exp_f32_e32 v95, v95
	v_add_f32_e32 v27, v27, v93
	v_mfma_f32_32x32x16_bf16 v[142:157], v[194:197], v[130:133], v[142:157]
	v_exp_f32_e32 v96, v96
	v_add_f32_e32 v27, v27, v94
	v_exp_f32_e32 v97, v97
	v_add_f32_e32 v27, v27, v95
	v_add_f32_e32 v27, v27, v96
	v_mfma_f32_32x32x16_bf16 v[158:173], v[190:193], v[130:133], v[158:173]
	v_add_f32_e32 v27, v27, v97
	v_cvt_pk_bf16_f32 v90, v90, v91
	v_cvt_pk_bf16_f32 v91, v92, v93
	v_cvt_pk_bf16_f32 v92, v94, v95
	v_cvt_pk_bf16_f32 v93, v96, v97
	v_mfma_f32_32x32x16_bf16 v[142:157], v[186:189], v[134:137], v[142:157]
	v_exp_f32_e32 v98, v98
	v_exp_f32_e32 v99, v99
	v_exp_f32_e32 v100, v100
	v_add_f32_e32 v27, v27, v98
	v_exp_f32_e32 v101, v101
	v_mfma_f32_32x32x16_bf16 v[158:173], v[182:185], v[134:137], v[158:173]
	v_add_f32_e32 v27, v27, v99
	v_exp_f32_e32 v102, v102
	v_add_f32_e32 v27, v27, v100
	v_exp_f32_e32 v103, v103
	v_add_f32_e32 v27, v27, v101
	v_mfma_f32_32x32x16_bf16 v[142:157], v[178:181], v[138:141], v[142:157]
	v_exp_f32_e32 v104, v104
	v_add_f32_e32 v27, v27, v102
	v_exp_f32_e32 v105, v105
	v_add_f32_e32 v27, v27, v103
	v_add_f32_e32 v27, v27, v104
	v_mfma_f32_32x32x16_bf16 v[158:173], v[174:177], v[138:141], v[158:173]
	v_add_f32_e32 v27, v27, v105
	v_cvt_pk_bf16_f32 v98, v98, v99
	v_cvt_pk_bf16_f32 v99, v100, v101
	v_cvt_pk_bf16_f32 v100, v102, v103
	v_cvt_pk_bf16_f32 v101, v104, v105
	s_waitcnt vmcnt(4)
	s_barrier
	s_waitcnt lgkmcnt(0)
	v_add_u32_e32 v2, 0x6000, v238
	v_mfma_f32_32x32x16_bf16 v[34:49], v[82:85], v[114:117], v[34:49]
	s_add_u32 m0, s57, 0x6000
	v_exp_f32_e32 v106, v106
	v_exp_f32_e32 v107, v107
	global_load_lds_dwordx4 v[28:29], off
	v_lshl_add_u64 v[28:29], v[28:29], 0, s[30:31]
	v_exp_f32_e32 v108, v108
	v_add_f32_e32 v27, v27, v106
	v_exp_f32_e32 v109, v109
	ds_read_b128 v[218:221], v2
	ds_read_b128 v[214:217], v2 offset:512
	ds_read_b128 v[210:213], v2 offset:2048
	v_mfma_f32_32x32x16_bf16 v[50:65], v[82:85], v[240:243], v[50:65]
	s_add_u32 m0, s40, 0x3000
	v_add_f32_e32 v27, v27, v107
	v_exp_f32_e32 v110, v110
	global_load_lds_dwordx4 v[24:25], off
	v_lshl_add_u64 v[24:25], v[24:25], 0, s[30:31]
	v_add_f32_e32 v27, v27, v108
	v_exp_f32_e32 v111, v111
	v_add_f32_e32 v27, v27, v109
	ds_read_b128 v[206:209], v2 offset:2560
	ds_read_b128 v[202:205], v2 offset:4096
	ds_read_b128 v[198:201], v2 offset:4608
	v_mfma_f32_32x32x16_bf16 v[34:49], v[90:93], v[118:121], v[34:49]
	v_exp_f32_e32 v112, v112
	v_add_f32_e32 v27, v27, v110
	v_exp_f32_e32 v113, v113
	v_add_f32_e32 v27, v27, v111
	v_add_f32_e32 v27, v27, v112
	ds_read_b128 v[194:197], v2 offset:6144
	ds_read_b128 v[190:193], v2 offset:6656
	ds_read_b128 v[186:189], v2 offset:8192
	v_mfma_f32_32x32x16_bf16 v[50:65], v[90:93], v[244:247], v[50:65]
	v_add_f32_e32 v27, v27, v113
	v_cvt_pk_bf16_f32 v106, v106, v107
	v_cvt_pk_bf16_f32 v107, v108, v109
	v_cvt_pk_bf16_f32 v108, v110, v111
	v_cvt_pk_bf16_f32 v109, v112, v113
	v_add_f32_e32 v236, v236, v27
	ds_read_b128 v[182:185], v2 offset:8704
	ds_read_b128 v[178:181], v2 offset:10240
	ds_read_b128 v[174:177], v2 offset:10752
	v_mfma_f32_32x32x16_bf16 v[34:49], v[98:101], v[122:125], v[34:49]
	v_max3_f32 v19, v142, v143, v144
	v_max3_f32 v26, v145, v146, v147
	v_max3_f32 v19, v19, v148, v149
	v_max3_f32 v26, v26, v150, v151
	v_mfma_f32_32x32x16_bf16 v[50:65], v[98:101], v[248:251], v[50:65]
	v_max3_f32 v19, v19, v152, v153
	v_max3_f32 v26, v26, v154, v155
	v_max3_f32 v19, v19, v156, v157
	v_max3_f32 v26, v26, v158, v159
	v_mfma_f32_32x32x16_bf16 v[34:49], v[106:109], v[126:129], v[34:49]
	v_max3_f32 v19, v19, v160, v161
	v_max3_f32 v26, v26, v162, v163
	v_max3_f32 v19, v19, v164, v165
	v_max3_f32 v26, v26, v166, v167
	v_mfma_f32_32x32x16_bf16 v[50:65], v[106:109], v[20:23], v[50:65]
	v_max3_f32 v19, v19, v168, v169
	v_max3_f32 v26, v26, v170, v171
	v_max3_f32 v19, v19, v172, v173
	v_max_f32_e32 v19, v19, v26
	v_cmp_lt_f32_e32 vcc, s41, v19
	s_cbranch_vccz .Lmy_nors_36
	s_nop 15
	s_nop 15
	v_mov_b32_e32 v26, v19
	s_nop 1
	v_permlane32_swap_b32_e32 v19, v26
	v_max_f32_e32 v19, v19, v26
	v_max_f32_e32 v19, v19, v19
	v_max_f32_e32 v90, 0, v19
	v_exp_f32_e64 v91, -v90
	v_add_f32_e32 v239, v239, v90
	v_xor_b32_e32 v66, 0x80000000, v239
	v_mov_b32_e32 v67, v66
	v_mov_b32_e32 v68, v66
	v_mov_b32_e32 v69, v66
	v_mov_b32_e32 v70, v66
	v_mov_b32_e32 v71, v66
	v_mov_b32_e32 v72, v66
	v_mov_b32_e32 v73, v66
	v_mov_b32_e32 v74, v66
	v_mov_b32_e32 v75, v66
	v_mov_b32_e32 v76, v66
	v_mov_b32_e32 v77, v66
	v_mov_b32_e32 v78, v66
	v_mov_b32_e32 v79, v66
	v_mov_b32_e32 v80, v66
	v_mov_b32_e32 v81, v66
	v_sub_f32_e32 v142, v142, v90
	v_sub_f32_e32 v143, v143, v90
	v_sub_f32_e32 v144, v144, v90
	v_sub_f32_e32 v145, v145, v90
	v_sub_f32_e32 v146, v146, v90
	v_sub_f32_e32 v147, v147, v90
	v_sub_f32_e32 v148, v148, v90
	v_sub_f32_e32 v149, v149, v90
	v_sub_f32_e32 v150, v150, v90
	v_sub_f32_e32 v151, v151, v90
	v_sub_f32_e32 v152, v152, v90
	v_sub_f32_e32 v153, v153, v90
	v_sub_f32_e32 v154, v154, v90
	v_sub_f32_e32 v155, v155, v90
	v_sub_f32_e32 v156, v156, v90
	v_sub_f32_e32 v157, v157, v90
	v_sub_f32_e32 v158, v158, v90
	v_sub_f32_e32 v159, v159, v90
	v_sub_f32_e32 v160, v160, v90
	v_sub_f32_e32 v161, v161, v90
	v_sub_f32_e32 v162, v162, v90
	v_sub_f32_e32 v163, v163, v90
	v_sub_f32_e32 v164, v164, v90
	v_sub_f32_e32 v165, v165, v90
	v_sub_f32_e32 v166, v166, v90
	v_sub_f32_e32 v167, v167, v90
	v_sub_f32_e32 v168, v168, v90
	v_sub_f32_e32 v169, v169, v90
	v_sub_f32_e32 v170, v170, v90
	v_sub_f32_e32 v171, v171, v90
	v_sub_f32_e32 v172, v172, v90
	v_sub_f32_e32 v173, v173, v90
	v_mul_f32_e32 v236, v236, v91
	s_mov_b64 s[96:97], exec
	s_and_b64 exec, exec, s[8:9]
	ds_write_b32 v235, v91
	s_mov_b64 exec, s[96:97]
	v_lshl_add_u32 v2, v228, 4, s47
	ds_read_b128 v[94:97], v2 offset:0
	s_waitcnt lgkmcnt(0)
	v_mul_f32_e32 v34, v34, v94
	v_mul_f32_e32 v50, v50, v94
	v_mul_f32_e32 v35, v35, v95
	v_mul_f32_e32 v51, v51, v95
	v_mul_f32_e32 v36, v36, v96
	v_mul_f32_e32 v52, v52, v96
	v_mul_f32_e32 v37, v37, v97
	v_mul_f32_e32 v53, v53, v97
	ds_read_b128 v[94:97], v2 offset:32
	s_waitcnt lgkmcnt(0)
	v_mul_f32_e32 v38, v38, v94
	v_mul_f32_e32 v54, v54, v94
	v_mul_f32_e32 v39, v39, v95
	v_mul_f32_e32 v55, v55, v95
	v_mul_f32_e32 v40, v40, v96
	v_mul_f32_e32 v56, v56, v96
	v_mul_f32_e32 v41, v41, v97
	v_mul_f32_e32 v57, v57, v97
	ds_read_b128 v[94:97], v2 offset:64
	s_waitcnt lgkmcnt(0)
	v_mul_f32_e32 v42, v42, v94
	v_mul_f32_e32 v58, v58, v94
	v_mul_f32_e32 v43, v43, v95
	v_mul_f32_e32 v59, v59, v95
	v_mul_f32_e32 v44, v44, v96
	v_mul_f32_e32 v60, v60, v96
	v_mul_f32_e32 v45, v45, v97
	v_mul_f32_e32 v61, v61, v97
	ds_read_b128 v[94:97], v2 offset:96
	s_waitcnt lgkmcnt(0)
	v_mul_f32_e32 v46, v46, v94
	v_mul_f32_e32 v62, v62, v94
	v_mul_f32_e32 v47, v47, v95
	v_mul_f32_e32 v63, v63, v95
	v_mul_f32_e32 v48, v48, v96
	v_mul_f32_e32 v64, v64, v96
	v_mul_f32_e32 v49, v49, v97
	v_mul_f32_e32 v65, v65, v97

.Lmy_nors_37:
	s_waitcnt lgkmcnt(0)
	v_add_u32_e32 v2, 0x4000, v237
	v_mfma_f32_32x32x16_bf16 v[142:157], v[218:221], v[4:7], v[66:81]
	v_exp_f32_e32 v82, v82
	v_exp_f32_e32 v83, v83
	v_exp_f32_e32 v84, v84
	v_add_f32_e32 v27, v82, v83
	v_exp_f32_e32 v85, v85
	ds_read_b64_tr_b16 v[114:115], v2 offset:49152
	ds_read_b64_tr_b16 v[116:117], v2 offset:49664
	ds_read_b64_tr_b16 v[118:119], v2 offset:50176
	ds_read_b64_tr_b16 v[120:121], v2 offset:50688
	v_mfma_f32_32x32x16_bf16 v[158:173], v[214:217], v[4:7], v[66:81]
	v_exp_f32_e32 v86, v86
	v_add_f32_e32 v27, v27, v84
	v_exp_f32_e32 v87, v87
	v_add_f32_e32 v27, v27, v85
	v_exp_f32_e32 v88, v88
	ds_read_b64_tr_b16 v[122:123], v2 offset:51200
	ds_read_b64_tr_b16 v[124:125], v2 offset:51712
	ds_read_b64_tr_b16 v[126:127], v2 offset:52224
	ds_read_b64_tr_b16 v[128:129], v2 offset:52736
	v_mfma_f32_32x32x16_bf16 v[142:157], v[210:213], v[8:11], v[142:157]
	v_add_f32_e32 v27, v27, v86
	v_exp_f32_e32 v89, v89
	v_add_f32_e32 v27, v27, v87
	v_add_f32_e32 v27, v27, v88
	v_add_f32_e32 v27, v27, v89
	ds_read_b64_tr_b16 v[240:241], v2 offset:53248
	ds_read_b64_tr_b16 v[242:243], v2 offset:53760
	ds_read_b64_tr_b16 v[244:245], v2 offset:54272
	ds_read_b64_tr_b16 v[246:247], v2 offset:54784
	v_mfma_f32_32x32x16_bf16 v[158:173], v[206:209], v[8:11], v[158:173]
	v_cvt_pk_bf16_f32 v82, v82, v83
	v_cvt_pk_bf16_f32 v83, v84, v85
	v_cvt_pk_bf16_f32 v84, v86, v87
	v_cvt_pk_bf16_f32 v85, v88, v89
	ds_read_b64_tr_b16 v[248:249], v2 offset:55296
	ds_read_b64_tr_b16 v[250:251], v2 offset:55808
	ds_read_b64_tr_b16 v[20:21], v2 offset:56320
	ds_read_b64_tr_b16 v[22:23], v2 offset:56832
	v_mfma_f32_32x32x16_bf16 v[142:157], v[202:205], v[12:15], v[142:157]
	v_exp_f32_e32 v90, v90
	v_exp_f32_e32 v91, v91
	v_exp_f32_e32 v92, v92
	v_add_f32_e32 v27, v27, v90
	v_exp_f32_e32 v93, v93
	v_mfma_f32_32x32x16_bf16 v[158:173], v[198:201], v[12:15], v[158:173]
	v_add_f32_e32 v27, v27, v91
	v_exp_f32_e32 v94, v94
	v_add_f32_e32 v27, v27, v92
	v_exp_f32_e32 v95, v95
	v_add_f32_e32 v27, v27, v93
	v_mfma_f32_32x32x16_bf16 v[142:157], v[194:197], v[130:133], v[142:157]
	v_exp_f32_e32 v96, v96
	v_add_f32_e32 v27, v27, v94
	v_exp_f32_e32 v97, v97
	v_add_f32_e32 v27, v27, v95
	v_add_f32_e32 v27, v27, v96
	v_mfma_f32_32x32x16_bf16 v[158:173], v[190:193], v[130:133], v[158:173]
	v_add_f32_e32 v27, v27, v97
	v_cvt_pk_bf16_f32 v90, v90, v91
	v_cvt_pk_bf16_f32 v91, v92, v93
	v_cvt_pk_bf16_f32 v92, v94, v95
	v_cvt_pk_bf16_f32 v93, v96, v97
	v_mfma_f32_32x32x16_bf16 v[142:157], v[186:189], v[134:137], v[142:157]
	v_exp_f32_e32 v98, v98
	v_exp_f32_e32 v99, v99
	v_exp_f32_e32 v100, v100
	v_add_f32_e32 v27, v27, v98
	v_exp_f32_e32 v101, v101
	v_mfma_f32_32x32x16_bf16 v[158:173], v[182:185], v[134:137], v[158:173]
	v_add_f32_e32 v27, v27, v99
	v_exp_f32_e32 v102, v102
	v_add_f32_e32 v27, v27, v100
	v_exp_f32_e32 v103, v103
	v_add_f32_e32 v27, v27, v101
	v_mfma_f32_32x32x16_bf16 v[142:157], v[178:181], v[138:141], v[142:157]
	v_exp_f32_e32 v104, v104
	v_add_f32_e32 v27, v27, v102
	v_exp_f32_e32 v105, v105
	v_add_f32_e32 v27, v27, v103
	v_add_f32_e32 v27, v27, v104
	v_mfma_f32_32x32x16_bf16 v[158:173], v[174:177], v[138:141], v[158:173]
	v_add_f32_e32 v27, v27, v105
	v_cvt_pk_bf16_f32 v98, v98, v99
	v_cvt_pk_bf16_f32 v99, v100, v101
	v_cvt_pk_bf16_f32 v100, v102, v103
	v_cvt_pk_bf16_f32 v101, v104, v105
	s_waitcnt vmcnt(4)
	s_barrier
	s_waitcnt lgkmcnt(0)
	v_mov_b32_e32 v2, v238
	v_mfma_f32_32x32x16_bf16 v[34:49], v[82:85], v[114:117], v[34:49]
	s_add_u32 m0, s57, 0x2000
	v_exp_f32_e32 v106, v106
	v_exp_f32_e32 v107, v107
	global_load_lds_dwordx4 v[28:29], off
	v_lshl_add_u64 v[28:29], v[28:29], 0, s[30:31]
	v_exp_f32_e32 v108, v108
	v_add_f32_e32 v27, v27, v106
	v_exp_f32_e32 v109, v109
	ds_read_b128 v[218:221], v2
	ds_read_b128 v[214:217], v2 offset:512
	ds_read_b128 v[210:213], v2 offset:2048
	v_mfma_f32_32x32x16_bf16 v[50:65], v[82:85], v[240:243], v[50:65]
	s_add_u32 m0, s40, 0x9000
	v_add_f32_e32 v27, v27, v107
	v_exp_f32_e32 v110, v110
	global_load_lds_dwordx4 v[24:25], off
	v_lshl_add_u64 v[24:25], v[24:25], 0, s[30:31]
	v_add_f32_e32 v27, v27, v108
	v_exp_f32_e32 v111, v111
	v_add_f32_e32 v27, v27, v109
	ds_read_b128 v[206:209], v2 offset:2560
	ds_read_b128 v[202:205], v2 offset:4096
	ds_read_b128 v[198:201], v2 offset:4608
	v_mfma_f32_32x32x16_bf16 v[34:49], v[90:93], v[118:121], v[34:49]
	v_exp_f32_e32 v112, v112
	v_add_f32_e32 v27, v27, v110
	v_exp_f32_e32 v113, v113
	v_add_f32_e32 v27, v27, v111
	v_add_f32_e32 v27, v27, v112
	ds_read_b128 v[194:197], v2 offset:6144
	ds_read_b128 v[190:193], v2 offset:6656
	ds_read_b128 v[186:189], v2 offset:8192
	v_mfma_f32_32x32x16_bf16 v[50:65], v[90:93], v[244:247], v[50:65]
	v_add_f32_e32 v27, v27, v113
	v_cvt_pk_bf16_f32 v106, v106, v107
	v_cvt_pk_bf16_f32 v107, v108, v109
	v_cvt_pk_bf16_f32 v108, v110, v111
	v_cvt_pk_bf16_f32 v109, v112, v113
	v_add_f32_e32 v236, v236, v27
	ds_read_b128 v[182:185], v2 offset:8704
	ds_read_b128 v[178:181], v2 offset:10240
	ds_read_b128 v[174:177], v2 offset:10752
	v_mfma_f32_32x32x16_bf16 v[34:49], v[98:101], v[122:125], v[34:49]
	v_max3_f32 v19, v142, v143, v144
	v_max3_f32 v26, v145, v146, v147
	v_max3_f32 v19, v19, v148, v149
	v_max3_f32 v26, v26, v150, v151
	v_mfma_f32_32x32x16_bf16 v[50:65], v[98:101], v[248:251], v[50:65]
	v_max3_f32 v19, v19, v152, v153
	v_max3_f32 v26, v26, v154, v155
	v_max3_f32 v19, v19, v156, v157
	v_max3_f32 v26, v26, v158, v159
	v_mfma_f32_32x32x16_bf16 v[34:49], v[106:109], v[126:129], v[34:49]
	v_max3_f32 v19, v19, v160, v161
	v_max3_f32 v26, v26, v162, v163
	v_max3_f32 v19, v19, v164, v165
	v_max3_f32 v26, v26, v166, v167
	v_mfma_f32_32x32x16_bf16 v[50:65], v[106:109], v[20:23], v[50:65]
	v_max3_f32 v19, v19, v168, v169
	v_max3_f32 v26, v26, v170, v171
	v_max3_f32 v19, v19, v172, v173
	v_max_f32_e32 v19, v19, v26
	v_cmp_lt_f32_e32 vcc, s41, v19
	s_cbranch_vccz .Lmy_nors_38
	s_nop 15
	s_nop 15
	v_mov_b32_e32 v26, v19
	s_nop 1
	v_permlane32_swap_b32_e32 v19, v26
	v_max_f32_e32 v19, v19, v26
	v_max_f32_e32 v19, v19, v19
	v_max_f32_e32 v90, 0, v19
	v_exp_f32_e64 v91, -v90
	v_add_f32_e32 v239, v239, v90
	v_xor_b32_e32 v66, 0x80000000, v239
	v_mov_b32_e32 v67, v66
	v_mov_b32_e32 v68, v66
	v_mov_b32_e32 v69, v66
	v_mov_b32_e32 v70, v66
	v_mov_b32_e32 v71, v66
	v_mov_b32_e32 v72, v66
	v_mov_b32_e32 v73, v66
	v_mov_b32_e32 v74, v66
	v_mov_b32_e32 v75, v66
	v_mov_b32_e32 v76, v66
	v_mov_b32_e32 v77, v66
	v_mov_b32_e32 v78, v66
	v_mov_b32_e32 v79, v66
	v_mov_b32_e32 v80, v66
	v_mov_b32_e32 v81, v66
	v_sub_f32_e32 v142, v142, v90
	v_sub_f32_e32 v143, v143, v90
	v_sub_f32_e32 v144, v144, v90
	v_sub_f32_e32 v145, v145, v90
	v_sub_f32_e32 v146, v146, v90
	v_sub_f32_e32 v147, v147, v90
	v_sub_f32_e32 v148, v148, v90
	v_sub_f32_e32 v149, v149, v90
	v_sub_f32_e32 v150, v150, v90
	v_sub_f32_e32 v151, v151, v90
	v_sub_f32_e32 v152, v152, v90
	v_sub_f32_e32 v153, v153, v90
	v_sub_f32_e32 v154, v154, v90
	v_sub_f32_e32 v155, v155, v90
	v_sub_f32_e32 v156, v156, v90
	v_sub_f32_e32 v157, v157, v90
	v_sub_f32_e32 v158, v158, v90
	v_sub_f32_e32 v159, v159, v90
	v_sub_f32_e32 v160, v160, v90
	v_sub_f32_e32 v161, v161, v90
	v_sub_f32_e32 v162, v162, v90
	v_sub_f32_e32 v163, v163, v90
	v_sub_f32_e32 v164, v164, v90
	v_sub_f32_e32 v165, v165, v90
	v_sub_f32_e32 v166, v166, v90
	v_sub_f32_e32 v167, v167, v90
	v_sub_f32_e32 v168, v168, v90
	v_sub_f32_e32 v169, v169, v90
	v_sub_f32_e32 v170, v170, v90
	v_sub_f32_e32 v171, v171, v90
	v_sub_f32_e32 v172, v172, v90
	v_sub_f32_e32 v173, v173, v90
	v_mul_f32_e32 v236, v236, v91
	s_mov_b64 s[96:97], exec
	s_and_b64 exec, exec, s[8:9]
	ds_write_b32 v235, v91
	s_mov_b64 exec, s[96:97]
	v_lshl_add_u32 v2, v228, 4, s47
	ds_read_b128 v[94:97], v2 offset:0
	s_waitcnt lgkmcnt(0)
	v_mul_f32_e32 v34, v34, v94
	v_mul_f32_e32 v50, v50, v94
	v_mul_f32_e32 v35, v35, v95
	v_mul_f32_e32 v51, v51, v95
	v_mul_f32_e32 v36, v36, v96
	v_mul_f32_e32 v52, v52, v96
	v_mul_f32_e32 v37, v37, v97
	v_mul_f32_e32 v53, v53, v97
	ds_read_b128 v[94:97], v2 offset:32
	s_waitcnt lgkmcnt(0)
	v_mul_f32_e32 v38, v38, v94
	v_mul_f32_e32 v54, v54, v94
	v_mul_f32_e32 v39, v39, v95
	v_mul_f32_e32 v55, v55, v95
	v_mul_f32_e32 v40, v40, v96
	v_mul_f32_e32 v56, v56, v96
	v_mul_f32_e32 v41, v41, v97
	v_mul_f32_e32 v57, v57, v97
	ds_read_b128 v[94:97], v2 offset:64
	s_waitcnt lgkmcnt(0)
	v_mul_f32_e32 v42, v42, v94
	v_mul_f32_e32 v58, v58, v94
	v_mul_f32_e32 v43, v43, v95
	v_mul_f32_e32 v59, v59, v95
	v_mul_f32_e32 v44, v44, v96
	v_mul_f32_e32 v60, v60, v96
	v_mul_f32_e32 v45, v45, v97
	v_mul_f32_e32 v61, v61, v97
	ds_read_b128 v[94:97], v2 offset:96
	s_waitcnt lgkmcnt(0)
	v_mul_f32_e32 v46, v46, v94
	v_mul_f32_e32 v62, v62, v94
	v_mul_f32_e32 v47, v47, v95
	v_mul_f32_e32 v63, v63, v95
	v_mul_f32_e32 v48, v48, v96
	v_mul_f32_e32 v64, v64, v96
	v_mul_f32_e32 v49, v49, v97
	v_mul_f32_e32 v65, v65, v97

.Lmy_tf_41:
	s_waitcnt lgkmcnt(0)
	v_mov_b32_e32 v2, v237
	v_mfma_f32_32x32x16_bf16 v[142:157], v[218:221], v[4:7], v[66:81]
	v_exp_f32_e32 v82, v82
	v_exp_f32_e32 v83, v83
	v_exp_f32_e32 v84, v84
	v_add_f32_e32 v27, v82, v83
	v_exp_f32_e32 v85, v85
	ds_read_b64_tr_b16 v[114:115], v2 offset:49152
	ds_read_b64_tr_b16 v[116:117], v2 offset:49664
	ds_read_b64_tr_b16 v[118:119], v2 offset:50176
	ds_read_b64_tr_b16 v[120:121], v2 offset:50688
	v_mfma_f32_32x32x16_bf16 v[158:173], v[214:217], v[4:7], v[66:81]
	v_exp_f32_e32 v86, v86
	v_add_f32_e32 v27, v27, v84
	v_exp_f32_e32 v87, v87
	v_add_f32_e32 v27, v27, v85
	v_exp_f32_e32 v88, v88
	ds_read_b64_tr_b16 v[122:123], v2 offset:51200
	ds_read_b64_tr_b16 v[124:125], v2 offset:51712
	ds_read_b64_tr_b16 v[126:127], v2 offset:52224
	ds_read_b64_tr_b16 v[128:129], v2 offset:52736
	v_mfma_f32_32x32x16_bf16 v[142:157], v[210:213], v[8:11], v[142:157]
	v_add_f32_e32 v27, v27, v86
	v_exp_f32_e32 v89, v89
	v_add_f32_e32 v27, v27, v87
	v_add_f32_e32 v27, v27, v88
	v_add_f32_e32 v27, v27, v89
	ds_read_b64_tr_b16 v[240:241], v2 offset:53248
	ds_read_b64_tr_b16 v[242:243], v2 offset:53760
	ds_read_b64_tr_b16 v[244:245], v2 offset:54272
	ds_read_b64_tr_b16 v[246:247], v2 offset:54784
	v_mfma_f32_32x32x16_bf16 v[158:173], v[206:209], v[8:11], v[158:173]
	v_cvt_pk_bf16_f32 v82, v82, v83
	v_cvt_pk_bf16_f32 v83, v84, v85
	v_cvt_pk_bf16_f32 v84, v86, v87
	v_cvt_pk_bf16_f32 v85, v88, v89
	ds_read_b64_tr_b16 v[248:249], v2 offset:55296
	ds_read_b64_tr_b16 v[250:251], v2 offset:55808
	ds_read_b64_tr_b16 v[20:21], v2 offset:56320
	ds_read_b64_tr_b16 v[22:23], v2 offset:56832
	v_mfma_f32_32x32x16_bf16 v[142:157], v[202:205], v[12:15], v[142:157]
	v_exp_f32_e32 v90, v90
	v_exp_f32_e32 v91, v91
	v_exp_f32_e32 v92, v92
	v_add_f32_e32 v27, v27, v90
	v_exp_f32_e32 v93, v93
	v_mfma_f32_32x32x16_bf16 v[158:173], v[198:201], v[12:15], v[158:173]
	v_add_f32_e32 v27, v27, v91
	v_exp_f32_e32 v94, v94
	v_add_f32_e32 v27, v27, v92
	v_exp_f32_e32 v95, v95
	v_add_f32_e32 v27, v27, v93
	v_mfma_f32_32x32x16_bf16 v[142:157], v[194:197], v[130:133], v[142:157]
	v_exp_f32_e32 v96, v96
	v_add_f32_e32 v27, v27, v94
	v_exp_f32_e32 v97, v97
	v_add_f32_e32 v27, v27, v95
	v_add_f32_e32 v27, v27, v96
	v_mfma_f32_32x32x16_bf16 v[158:173], v[190:193], v[130:133], v[158:173]
	v_add_f32_e32 v27, v27, v97
	v_cvt_pk_bf16_f32 v90, v90, v91
	v_cvt_pk_bf16_f32 v91, v92, v93
	v_cvt_pk_bf16_f32 v92, v94, v95
	v_cvt_pk_bf16_f32 v93, v96, v97
	v_mfma_f32_32x32x16_bf16 v[142:157], v[186:189], v[134:137], v[142:157]
	v_exp_f32_e32 v98, v98
	v_exp_f32_e32 v99, v99
	v_exp_f32_e32 v100, v100
	v_add_f32_e32 v27, v27, v98
	v_exp_f32_e32 v101, v101
	v_mfma_f32_32x32x16_bf16 v[158:173], v[182:185], v[134:137], v[158:173]
	v_add_f32_e32 v27, v27, v99
	v_exp_f32_e32 v102, v102
	v_add_f32_e32 v27, v27, v100
	v_exp_f32_e32 v103, v103
	v_add_f32_e32 v27, v27, v101
	v_mfma_f32_32x32x16_bf16 v[142:157], v[178:181], v[138:141], v[142:157]
	v_exp_f32_e32 v104, v104
	v_add_f32_e32 v27, v27, v102
	v_exp_f32_e32 v105, v105
	v_add_f32_e32 v27, v27, v103
	v_add_f32_e32 v27, v27, v104
	v_mfma_f32_32x32x16_bf16 v[158:173], v[174:177], v[138:141], v[158:173]
	v_add_f32_e32 v27, v27, v105
	v_cvt_pk_bf16_f32 v98, v98, v99
	v_cvt_pk_bf16_f32 v99, v100, v101
	v_cvt_pk_bf16_f32 v100, v102, v103
	v_cvt_pk_bf16_f32 v101, v104, v105
	s_waitcnt vmcnt(2)
	s_barrier
	s_waitcnt lgkmcnt(0)
	v_add_u32_e32 v2, 0x6000, v238
	v_mfma_f32_32x32x16_bf16 v[34:49], v[82:85], v[114:117], v[34:49]
	s_add_u32 m0, s57, 0x6000
	v_exp_f32_e32 v106, v106
	v_exp_f32_e32 v107, v107
	global_load_lds_dwordx4 v[28:29], off
	v_lshl_add_u64 v[28:29], v[28:29], 0, s[30:31]
	v_exp_f32_e32 v108, v108
	v_add_f32_e32 v27, v27, v106
	v_exp_f32_e32 v109, v109
	s_cmp_gt_u32 s71, 1
	s_cbranch_scc0 .Lmy_nok_44
	ds_read_b128 v[218:221], v2
	ds_read_b128 v[214:217], v2 offset:512
	ds_read_b128 v[210:213], v2 offset:2048
	ds_read_b128 v[206:209], v2 offset:2560
	ds_read_b128 v[202:205], v2 offset:4096
	ds_read_b128 v[198:201], v2 offset:4608
	ds_read_b128 v[194:197], v2 offset:6144
	ds_read_b128 v[190:193], v2 offset:6656
	ds_read_b128 v[186:189], v2 offset:8192
	ds_read_b128 v[182:185], v2 offset:8704
	ds_read_b128 v[178:181], v2 offset:10240
	ds_read_b128 v[174:177], v2 offset:10752
